# v14 with MFMA order variant snake instead of acc-paired (ordering study)
# baseline (speedup 1.0000x reference)
; #define PG8_STAGE(bufoff, gbase, voff) do { _Pragma("unroll") for (int _i = 0; _i < 2; ++_i) \
;         __builtin_amdgcn_global_load_lds((const unsigned*)((const char*)(gbase) + (voff)[_i]), (LAS unsigned*)(lds + (bufoff) + ldsw + _i * 8192), 16, 0, 0); } while (0)
; #define PG8_LDA(dst, b, h) do { _Pragma("unroll") for (int m = 0; m < 4; ++m) _Pragma("unroll") for (int k = 0; k < 2; ++k) dst[m][k] = *(const LAS bf16x8*)(lds + PG8_SA(b, h) + aoff + m * 2048 + k * 1024); } while (0)
; #define PG8_LDB(dst, b, h) do { _Pragma("unroll") for (int n = 0; n < 2; ++n) _Pragma("unroll") for (int k = 0; k < 2; ++k) dst[n][k] = *(const LAS bf16x8*)(lds + PG8_SB(b, h) + boff + n * 2048 + k * 1024); } while (0)
; #define PG8_MMA(ai, bj, At, Bt) do { __builtin_amdgcn_s_setprio(1); _Pragma("unroll") for (int m = 0; m < 4; ++m) _Pragma("unroll") for (int n = 0; n < 2; ++n) _Pragma("unroll") for (int k = 0; k < 2; ++k) \
;         acc[ai][bj][m][n] = __builtin_amdgcn_mfma_f32_16x16x32_bf16(Bt[n][k], At[m][k], acc[ai][bj][m][n], 0, 0, 0); __builtin_amdgcn_s_setprio(0); } while (0)
; #define PG8_WAIT_V(n) asm volatile("s_waitcnt vmcnt(" #n ")" ::: "memory")
; #define PG8_WAIT_L(n) asm volatile("s_waitcnt lgkmcnt(" #n ")" ::: "memory")
; #define PG8_BAR __builtin_amdgcn_s_barrier()
; #define PG8_SCHED __builtin_amdgcn_sched_barrier(0)
; template <class Epi, class Ptrs>
; __device__ __forceinline__ void gemm_phase(LAS unsigned char* lds, const int K, const StaticOrder& S, const Ptrs& P, const Epi& E) {
;     ...
;             PG8_LDB(B0, 0, 0); PG8_SCHED; PG8_LDA(At, 0, 0); PG8_STAGE(PG8_SA(1, 1), a1 + hstep, voffA);
;             PG8_WAIT_L(8); PG8_BAR; PG8_WAIT_L(0); PG8_MMA(0, 0, At, B0); PG8_BAR; PG8_SCHED;
;             PG8_LDB(B1, 0, 1); PG8_STAGE(PG8_SB(0, 0), b2, voffB);
;             PG8_BAR; PG8_WAIT_L(0); PG8_MMA(0, 1, At, B1); PG8_BAR;
;             PG8_LDA(At, 0, 1); PG8_STAGE(PG8_SA(0, 0), a2, voffA);
;             PG8_BAR; PG8_WAIT_L(0); PG8_MMA(1, 0, At, B0); PG8_BAR; PG8_SCHED;
;             PG8_STAGE(PG8_SB(0, 1), b2 + hstep, voffB);
;             PG8_WAIT_V(6); PG8_BAR; PG8_MMA(1, 1, At, B1); PG8_BAR;
.LBB0_126:
	s_add_u32 s6, s6, 0x40080
	s_addc_u32 s7, s7, 0
	s_add_u32 s20, s78, 0x100
	s_addc_u32 s25, s79, 0
	s_mov_b32 s63, -2
	v_add_u32_e32 v252, 0x18000, v131
	v_add_u32_e32 v253, 0x1c000, v131
	ds_read_b128 v[150:153], v205
	ds_read_b128 v[154:157], v205 offset:1024
	ds_read_b128 v[158:161], v205 offset:2048
	ds_read_b128 v[162:165], v205 offset:3072
	s_add_u32 s69, s6, 0xfffc0080
	s_addc_u32 s71, s7, -1
	s_cmp_eq_u32 s63, 12
	s_cselect_b32 s81, s1, s71
	s_cselect_b32 s80, s0, s69
	s_cselect_b32 s79, s73, s25
	s_cselect_b32 s78, s72, s20
	s_add_i32 m0, s67, 0xc000
	ds_read_b128 v[166:169], v206
	ds_read_b128 v[170:173], v206 offset:1024
	ds_read_b128 v[174:177], v206 offset:2048
	ds_read_b128 v[178:181], v206 offset:3072
	ds_read_b128 v[182:185], v206 offset:4096
	ds_read_b128 v[186:189], v206 offset:5120
	ds_read_b128 v[190:193], v206 offset:6144
	ds_read_b128 v[194:197], v206 offset:7168
	global_load_lds_dwordx4 v142, s[6:7]
	s_add_i32 m0, s67, 0xe000
	s_nop 0
	global_load_lds_dwordx4 v144, s[6:7]
	s_waitcnt lgkmcnt(8)
	s_barrier
	s_waitcnt lgkmcnt(0)
	v_mfma_f32_16x16x32_bf16 v[120:123], v[150:153], v[166:169], 0
	v_mfma_f32_16x16x32_bf16 v[116:119], v[158:161], v[166:169], 0
	v_mfma_f32_16x16x32_bf16 v[100:103], v[158:161], v[174:177], 0
	v_mfma_f32_16x16x32_bf16 v[104:107], v[150:153], v[174:177], 0
	v_mfma_f32_16x16x32_bf16 v[88:91], v[150:153], v[182:185], 0
	v_mfma_f32_16x16x32_bf16 v[84:87], v[158:161], v[182:185], 0
	v_mfma_f32_16x16x32_bf16 v[68:71], v[158:161], v[190:193], 0
	v_mfma_f32_16x16x32_bf16 v[72:75], v[150:153], v[190:193], 0
	v_mfma_f32_16x16x32_bf16 v[120:123], v[154:157], v[170:173], v[120:123]
	v_mfma_f32_16x16x32_bf16 v[116:119], v[162:165], v[170:173], v[116:119]
	v_mfma_f32_16x16x32_bf16 v[100:103], v[162:165], v[178:181], v[100:103]
	v_mfma_f32_16x16x32_bf16 v[104:107], v[154:157], v[178:181], v[104:107]
	v_mfma_f32_16x16x32_bf16 v[88:91], v[154:157], v[186:189], v[88:91]
	v_mfma_f32_16x16x32_bf16 v[84:87], v[162:165], v[186:189], v[84:87]
	v_mfma_f32_16x16x32_bf16 v[68:71], v[162:165], v[194:197], v[68:71]
	v_mfma_f32_16x16x32_bf16 v[72:75], v[154:157], v[194:197], v[72:75]
	s_barrier
	s_add_i32 s69, s91, s65
	s_add_u32 s100, s78, 0x80
	s_addc_u32 s101, s79, 0
	s_mov_b32 m0, s69
	ds_read_b128 v[198:201], v207
	ds_read_b128 v[210:213], v207 offset:1024
	ds_read_b128 v[214:217], v207 offset:2048
	ds_read_b128 v[218:221], v207 offset:3072
	global_load_lds_dwordx4 v134, s[78:79]
	s_add_i32 m0, s69, 0x2000
	s_nop 0
	global_load_lds_dwordx4 v138, s[78:79]
	s_barrier
	s_waitcnt lgkmcnt(0)
	v_mfma_f32_16x16x32_bf16 v[124:127], v[198:201], v[166:169], 0
	v_mfma_f32_16x16x32_bf16 v[112:115], v[214:217], v[166:169], 0
	v_mfma_f32_16x16x32_bf16 v[96:99], v[214:217], v[174:177], 0
	v_mfma_f32_16x16x32_bf16 v[108:111], v[198:201], v[174:177], 0
	v_mfma_f32_16x16x32_bf16 v[92:95], v[198:201], v[182:185], 0
	v_mfma_f32_16x16x32_bf16 v[80:83], v[214:217], v[182:185], 0
	v_mfma_f32_16x16x32_bf16 v[64:67], v[214:217], v[190:193], 0
	v_mfma_f32_16x16x32_bf16 v[76:79], v[198:201], v[190:193], 0
	v_mfma_f32_16x16x32_bf16 v[124:127], v[210:213], v[170:173], v[124:127]
	v_mfma_f32_16x16x32_bf16 v[112:115], v[218:221], v[170:173], v[112:115]
	v_mfma_f32_16x16x32_bf16 v[96:99], v[218:221], v[178:181], v[96:99]
	v_mfma_f32_16x16x32_bf16 v[108:111], v[210:213], v[178:181], v[108:111]
	v_mfma_f32_16x16x32_bf16 v[92:95], v[210:213], v[186:189], v[92:95]
	v_mfma_f32_16x16x32_bf16 v[80:83], v[218:221], v[186:189], v[80:83]
	v_mfma_f32_16x16x32_bf16 v[64:67], v[218:221], v[194:197], v[64:67]
	v_mfma_f32_16x16x32_bf16 v[76:79], v[210:213], v[194:197], v[76:79]
	s_barrier
	s_mov_b32 m0, s67
	ds_read_b128 v[166:169], v206 offset:16384
	ds_read_b128 v[170:173], v206 offset:17408
	ds_read_b128 v[174:177], v206 offset:18432
	ds_read_b128 v[178:181], v206 offset:19456
	ds_read_b128 v[182:185], v206 offset:20480
	ds_read_b128 v[186:189], v206 offset:21504
	ds_read_b128 v[190:193], v206 offset:22528
	ds_read_b128 v[194:197], v206 offset:23552
	global_load_lds_dwordx4 v132, s[80:81]
	s_mov_b32 m0, s75
	s_nop 0
	global_load_lds_dwordx4 v136, s[80:81]
	s_barrier
	s_waitcnt lgkmcnt(0)
	v_mfma_f32_16x16x32_bf16 v[56:59], v[150:153], v[166:169], 0
	v_mfma_f32_16x16x32_bf16 v[52:55], v[158:161], v[166:169], 0
	v_mfma_f32_16x16x32_bf16 v[36:39], v[158:161], v[174:177], 0
	v_mfma_f32_16x16x32_bf16 v[40:43], v[150:153], v[174:177], 0
	v_mfma_f32_16x16x32_bf16 v[24:27], v[150:153], v[182:185], 0
	v_mfma_f32_16x16x32_bf16 v[20:23], v[158:161], v[182:185], 0
	v_mfma_f32_16x16x32_bf16 v[4:7], v[158:161], v[190:193], 0
	v_mfma_f32_16x16x32_bf16 v[8:11], v[150:153], v[190:193], 0
	v_mfma_f32_16x16x32_bf16 v[56:59], v[154:157], v[170:173], v[56:59]
	v_mfma_f32_16x16x32_bf16 v[52:55], v[162:165], v[170:173], v[52:55]
	v_mfma_f32_16x16x32_bf16 v[36:39], v[162:165], v[178:181], v[36:39]
	v_mfma_f32_16x16x32_bf16 v[40:43], v[154:157], v[178:181], v[40:43]
	v_mfma_f32_16x16x32_bf16 v[24:27], v[154:157], v[186:189], v[24:27]
	v_mfma_f32_16x16x32_bf16 v[20:23], v[162:165], v[186:189], v[20:23]
	v_mfma_f32_16x16x32_bf16 v[4:7], v[162:165], v[194:197], v[4:7]
	v_mfma_f32_16x16x32_bf16 v[8:11], v[154:157], v[194:197], v[8:11]
	s_barrier
	s_add_u32 s82, s78, 0x40000
	s_addc_u32 s83, s79, 0
	s_add_i32 s69, s92, s65
	s_mov_b32 m0, s69
	s_nop 0
	global_load_lds_dwordx4 v134, s[82:83]
	s_add_i32 m0, s69, 0x2000
	s_nop 0
	global_load_lds_dwordx4 v138, s[82:83]
	s_waitcnt vmcnt(6)
	s_barrier
; #define PG8_STAGE(bufoff, gbase, voff) do { _Pragma("unroll") for (int _i = 0; _i < 2; ++_i) \
;         __builtin_amdgcn_global_load_lds((const unsigned*)((const char*)(gbase) + (voff)[_i]), (LAS unsigned*)(lds + (bufoff) + ldsw + _i * 8192), 16, 0, 0); } while (0)
; #define PG8_LDA(dst, b, h) do { _Pragma("unroll") for (int m = 0; m < 4; ++m) _Pragma("unroll") for (int k = 0; k < 2; ++k) dst[m][k] = *(const LAS bf16x8*)(lds + PG8_SA(b, h) + aoff + m * 2048 + k * 1024); } while (0)
; #define PG8_LDB(dst, b, h) do { _Pragma("unroll") for (int n = 0; n < 2; ++n) _Pragma("unroll") for (int k = 0; k < 2; ++k) dst[n][k] = *(const LAS bf16x8*)(lds + PG8_SB(b, h) + boff + n * 2048 + k * 1024); } while (0)
; #define PG8_WAIT_V(n) asm volatile("s_waitcnt vmcnt(" #n ")" ::: "memory")
; #define PG8_WAIT_L(n) asm volatile("s_waitcnt lgkmcnt(" #n ")" ::: "memory")
; #define PG8_BAR __builtin_amdgcn_s_barrier()
; #define PG8_SCHED __builtin_amdgcn_sched_barrier(0)
; template <class Epi, class Ptrs>
; __device__ __forceinline__ void gemm_phase(LAS unsigned char* lds, const int K, const StaticOrder& S, const Ptrs& P, const Epi& E) {
;     ...
;             PG8_LDB(B0, 0, 0); PG8_SCHED; PG8_LDA(At, 0, 0); PG8_STAGE(PG8_SA(1, 1), a1 + hstep, voffA);
;             PG8_WAIT_L(8); PG8_BAR; PG8_WAIT_L(0); PG8_MMA(0, 0, At, B0); PG8_BAR; PG8_SCHED;
;             PG8_LDB(B1, 0, 1); PG8_STAGE(PG8_SB(0, 0), b2, voffB);
;             PG8_BAR; PG8_WAIT_L(0); PG8_MMA(0, 1, At, B1); PG8_BAR;
;             PG8_LDA(At, 0, 1); PG8_STAGE(PG8_SA(0, 0), a2, voffA);
;             PG8_BAR; PG8_WAIT_L(0); PG8_MMA(1, 0, At, B0); PG8_BAR; PG8_SCHED;
;             PG8_STAGE(PG8_SB(0, 1), b2 + hstep, voffB);
;             PG8_WAIT_V(6); PG8_BAR; PG8_MMA(1, 1, At, B1); PG8_BAR;
;             PG8_LDB(B0, 1, 0); PG8_SCHED; PG8_LDA(At, 1, 0); PG8_STAGE(PG8_SA(0, 1), a2 + hstep, voffA);
;             PG8_WAIT_L(8); PG8_BAR; PG8_WAIT_L(0); PG8_MMA(0, 0, At, B0); PG8_BAR; PG8_SCHED;
;             PG8_LDB(B1, 1, 1); PG8_STAGE(PG8_SB(1, 0), b3, voffB);
;             PG8_BAR; PG8_WAIT_L(0); PG8_MMA(0, 1, At, B1); PG8_BAR;
;             PG8_LDA(At, 1, 1); PG8_STAGE(PG8_SA(1, 0), a3, voffA);
;             PG8_BAR; PG8_WAIT_L(0); PG8_MMA(1, 0, At, B0); PG8_BAR; PG8_SCHED;
;             PG8_STAGE(PG8_SB(1, 1), b3 + hstep, voffB);
;             PG8_WAIT_V(6); PG8_BAR; PG8_MMA(1, 1, At, B1); PG8_BAR;
	v_mfma_f32_16x16x32_bf16 v[60:63], v[198:201], v[166:169], 0
	v_mfma_f32_16x16x32_bf16 v[48:51], v[214:217], v[166:169], 0
	v_mfma_f32_16x16x32_bf16 v[32:35], v[214:217], v[174:177], 0
	v_mfma_f32_16x16x32_bf16 v[44:47], v[198:201], v[174:177], 0
	v_mfma_f32_16x16x32_bf16 v[28:31], v[198:201], v[182:185], 0
	v_mfma_f32_16x16x32_bf16 v[16:19], v[214:217], v[182:185], 0
	v_mfma_f32_16x16x32_bf16 v[0:3], v[214:217], v[190:193], 0
	v_mfma_f32_16x16x32_bf16 v[12:15], v[198:201], v[190:193], 0
	v_mfma_f32_16x16x32_bf16 v[60:63], v[210:213], v[170:173], v[60:63]
	v_mfma_f32_16x16x32_bf16 v[48:51], v[218:221], v[170:173], v[48:51]
	v_mfma_f32_16x16x32_bf16 v[32:35], v[218:221], v[178:181], v[32:35]
	v_mfma_f32_16x16x32_bf16 v[44:47], v[210:213], v[178:181], v[44:47]
	v_mfma_f32_16x16x32_bf16 v[28:31], v[210:213], v[186:189], v[28:31]
	v_mfma_f32_16x16x32_bf16 v[16:19], v[218:221], v[186:189], v[16:19]
	v_mfma_f32_16x16x32_bf16 v[0:3], v[218:221], v[194:197], v[0:3]
	v_mfma_f32_16x16x32_bf16 v[12:15], v[210:213], v[194:197], v[12:15]
	s_barrier
	s_add_i32 s69, 0, 0x18000
	ds_read_b128 v[150:153], v252
	ds_read_b128 v[154:157], v252 offset:1024
	ds_read_b128 v[158:161], v252 offset:2048
	ds_read_b128 v[162:165], v252 offset:3072
	s_add_u32 s80, s80, 0x40000
	s_addc_u32 s81, s81, 0
	s_mov_b32 m0, s77
	ds_read_b128 v[166:169], v206 offset:32768
	ds_read_b128 v[170:173], v206 offset:33792
	ds_read_b128 v[174:177], v206 offset:34816
	ds_read_b128 v[178:181], v206 offset:35840
	ds_read_b128 v[182:185], v206 offset:36864
	ds_read_b128 v[186:189], v206 offset:37888
	ds_read_b128 v[190:193], v206 offset:38912
	ds_read_b128 v[194:197], v206 offset:39936
	global_load_lds_dwordx4 v132, s[80:81]
	s_mov_b32 m0, s85
	s_nop 0
	global_load_lds_dwordx4 v136, s[80:81]
	s_waitcnt lgkmcnt(8)
	s_barrier
	s_waitcnt lgkmcnt(0)
	v_mfma_f32_16x16x32_bf16 v[120:123], v[150:153], v[166:169], v[120:123]
	v_mfma_f32_16x16x32_bf16 v[116:119], v[158:161], v[166:169], v[116:119]
	v_mfma_f32_16x16x32_bf16 v[100:103], v[158:161], v[174:177], v[100:103]
	v_mfma_f32_16x16x32_bf16 v[104:107], v[150:153], v[174:177], v[104:107]
	v_mfma_f32_16x16x32_bf16 v[88:91], v[150:153], v[182:185], v[88:91]
	v_mfma_f32_16x16x32_bf16 v[84:87], v[158:161], v[182:185], v[84:87]
	v_mfma_f32_16x16x32_bf16 v[68:71], v[158:161], v[190:193], v[68:71]
	v_mfma_f32_16x16x32_bf16 v[72:75], v[150:153], v[190:193], v[72:75]
	v_mfma_f32_16x16x32_bf16 v[120:123], v[154:157], v[170:173], v[120:123]
	v_mfma_f32_16x16x32_bf16 v[116:119], v[162:165], v[170:173], v[116:119]
	v_mfma_f32_16x16x32_bf16 v[100:103], v[162:165], v[178:181], v[100:103]
	v_mfma_f32_16x16x32_bf16 v[104:107], v[154:157], v[178:181], v[104:107]
	v_mfma_f32_16x16x32_bf16 v[88:91], v[154:157], v[186:189], v[88:91]
	v_mfma_f32_16x16x32_bf16 v[84:87], v[162:165], v[186:189], v[84:87]
	v_mfma_f32_16x16x32_bf16 v[68:71], v[162:165], v[194:197], v[68:71]
	v_mfma_f32_16x16x32_bf16 v[72:75], v[154:157], v[194:197], v[72:75]
	s_barrier
	s_add_i32 s71, 0, 0x1c000
	s_add_i32 s69, s69, s65
	s_mov_b32 m0, s69
	ds_read_b128 v[198:201], v253
	ds_read_b128 v[210:213], v253 offset:1024
	ds_read_b128 v[214:217], v253 offset:2048
	ds_read_b128 v[218:221], v253 offset:3072
	global_load_lds_dwordx4 v134, s[100:101]
	s_add_i32 m0, s69, 0x2000
	s_nop 0
	global_load_lds_dwordx4 v138, s[100:101]
	s_barrier
	s_waitcnt lgkmcnt(0)
	v_mfma_f32_16x16x32_bf16 v[124:127], v[198:201], v[166:169], v[124:127]
	v_mfma_f32_16x16x32_bf16 v[112:115], v[214:217], v[166:169], v[112:115]
	v_mfma_f32_16x16x32_bf16 v[96:99], v[214:217], v[174:177], v[96:99]
	v_mfma_f32_16x16x32_bf16 v[108:111], v[198:201], v[174:177], v[108:111]
	v_mfma_f32_16x16x32_bf16 v[92:95], v[198:201], v[182:185], v[92:95]
	v_mfma_f32_16x16x32_bf16 v[80:83], v[214:217], v[182:185], v[80:83]
	v_mfma_f32_16x16x32_bf16 v[64:67], v[214:217], v[190:193], v[64:67]
	v_mfma_f32_16x16x32_bf16 v[76:79], v[198:201], v[190:193], v[76:79]
	v_mfma_f32_16x16x32_bf16 v[124:127], v[210:213], v[170:173], v[124:127]
	v_mfma_f32_16x16x32_bf16 v[112:115], v[218:221], v[170:173], v[112:115]
	v_mfma_f32_16x16x32_bf16 v[96:99], v[218:221], v[178:181], v[96:99]
	v_mfma_f32_16x16x32_bf16 v[108:111], v[210:213], v[178:181], v[108:111]
	v_mfma_f32_16x16x32_bf16 v[92:95], v[210:213], v[186:189], v[92:95]
	v_mfma_f32_16x16x32_bf16 v[80:83], v[218:221], v[186:189], v[80:83]
	v_mfma_f32_16x16x32_bf16 v[64:67], v[218:221], v[194:197], v[64:67]
	v_mfma_f32_16x16x32_bf16 v[76:79], v[210:213], v[194:197], v[76:79]
	s_barrier
	s_mov_b32 m0, s89
	s_add_u32 s100, s80, 0xfffc0080
	s_addc_u32 s101, s81, -1
	ds_read_b128 v[166:169], v206 offset:49152
	ds_read_b128 v[170:173], v206 offset:50176
	ds_read_b128 v[174:177], v206 offset:51200
	ds_read_b128 v[178:181], v206 offset:52224
	ds_read_b128 v[182:185], v206 offset:53248
	ds_read_b128 v[186:189], v206 offset:54272
	ds_read_b128 v[190:193], v206 offset:55296
	ds_read_b128 v[194:197], v206 offset:56320
	global_load_lds_dwordx4 v132, s[100:101]
	s_mov_b32 m0, s90
	s_nop 0
	global_load_lds_dwordx4 v136, s[100:101]
	s_barrier
	s_waitcnt lgkmcnt(0)
	v_mfma_f32_16x16x32_bf16 v[56:59], v[150:153], v[166:169], v[56:59]
	v_mfma_f32_16x16x32_bf16 v[52:55], v[158:161], v[166:169], v[52:55]
	v_mfma_f32_16x16x32_bf16 v[36:39], v[158:161], v[174:177], v[36:39]
	v_mfma_f32_16x16x32_bf16 v[40:43], v[150:153], v[174:177], v[40:43]
	v_mfma_f32_16x16x32_bf16 v[24:27], v[150:153], v[182:185], v[24:27]
	v_mfma_f32_16x16x32_bf16 v[20:23], v[158:161], v[182:185], v[20:23]
	v_mfma_f32_16x16x32_bf16 v[4:7], v[158:161], v[190:193], v[4:7]
	v_mfma_f32_16x16x32_bf16 v[8:11], v[150:153], v[190:193], v[8:11]
	v_mfma_f32_16x16x32_bf16 v[56:59], v[154:157], v[170:173], v[56:59]
	v_mfma_f32_16x16x32_bf16 v[52:55], v[162:165], v[170:173], v[52:55]
	v_mfma_f32_16x16x32_bf16 v[36:39], v[162:165], v[178:181], v[36:39]
	v_mfma_f32_16x16x32_bf16 v[40:43], v[154:157], v[178:181], v[40:43]
	v_mfma_f32_16x16x32_bf16 v[24:27], v[154:157], v[186:189], v[24:27]
	v_mfma_f32_16x16x32_bf16 v[20:23], v[162:165], v[186:189], v[20:23]
	v_mfma_f32_16x16x32_bf16 v[4:7], v[162:165], v[194:197], v[4:7]
	v_mfma_f32_16x16x32_bf16 v[8:11], v[154:157], v[194:197], v[8:11]
	s_barrier
; #define PG8_STAGE(bufoff, gbase, voff) do { _Pragma("unroll") for (int _i = 0; _i < 2; ++_i) \
;         __builtin_amdgcn_global_load_lds((const unsigned*)((const char*)(gbase) + (voff)[_i]), (LAS unsigned*)(lds + (bufoff) + ldsw + _i * 8192), 16, 0, 0); } while (0)
; #define PG8_LDA(dst, b, h) do { _Pragma("unroll") for (int m = 0; m < 4; ++m) _Pragma("unroll") for (int k = 0; k < 2; ++k) dst[m][k] = *(const LAS bf16x8*)(lds + PG8_SA(b, h) + aoff + m * 2048 + k * 1024); } while (0)
; #define PG8_LDB(dst, b, h) do { _Pragma("unroll") for (int n = 0; n < 2; ++n) _Pragma("unroll") for (int k = 0; k < 2; ++k) dst[n][k] = *(const LAS bf16x8*)(lds + PG8_SB(b, h) + boff + n * 2048 + k * 1024); } while (0)
; #define PG8_WAIT_V(n) asm volatile("s_waitcnt vmcnt(" #n ")" ::: "memory")
; #define PG8_WAIT_L(n) asm volatile("s_waitcnt lgkmcnt(" #n ")" ::: "memory")
; #define PG8_BAR __builtin_amdgcn_s_barrier()
; #define PG8_SCHED __builtin_amdgcn_sched_barrier(0)
; template <class Epi, class Ptrs>
; __device__ __forceinline__ void gemm_phase(LAS unsigned char* lds, const int K, const StaticOrder& S, const Ptrs& P, const Epi& E) {
;     ...
;             PG8_LDB(B0, 0, 0); PG8_SCHED; PG8_LDA(At, 0, 0); PG8_STAGE(PG8_SA(1, 1), a1 + hstep, voffA);
;             PG8_WAIT_L(8); PG8_BAR; PG8_WAIT_L(0); PG8_MMA(0, 0, At, B0); PG8_BAR; PG8_SCHED;
;             PG8_LDB(B1, 0, 1); PG8_STAGE(PG8_SB(0, 0), b2, voffB);
;             PG8_BAR; PG8_WAIT_L(0); PG8_MMA(0, 1, At, B1); PG8_BAR;
;             PG8_LDA(At, 0, 1); PG8_STAGE(PG8_SA(0, 0), a2, voffA);
;             PG8_BAR; PG8_WAIT_L(0); PG8_MMA(1, 0, At, B0); PG8_BAR; PG8_SCHED;
;             PG8_STAGE(PG8_SB(0, 1), b2 + hstep, voffB);
;             PG8_WAIT_V(6); PG8_BAR; PG8_MMA(1, 1, At, B1); PG8_BAR;
;             PG8_LDB(B0, 1, 0); PG8_SCHED; PG8_LDA(At, 1, 0); PG8_STAGE(PG8_SA(0, 1), a2 + hstep, voffA);
;             PG8_WAIT_L(8); PG8_BAR; PG8_WAIT_L(0); PG8_MMA(0, 0, At, B0); PG8_BAR; PG8_SCHED;
;             PG8_LDB(B1, 1, 1); PG8_STAGE(PG8_SB(1, 0), b3, voffB);
;             PG8_BAR; PG8_WAIT_L(0); PG8_MMA(0, 1, At, B1); PG8_BAR;
;             PG8_LDA(At, 1, 1); PG8_STAGE(PG8_SA(1, 0), a3, voffA);
;             PG8_BAR; PG8_WAIT_L(0); PG8_MMA(1, 0, At, B0); PG8_BAR; PG8_SCHED;
;             PG8_STAGE(PG8_SB(1, 1), b3 + hstep, voffB);
;             PG8_WAIT_V(6); PG8_BAR; PG8_MMA(1, 1, At, B1); PG8_BAR;
	s_add_u32 s78, s78, 0x40080
	s_addc_u32 s79, s79, 0
	s_add_i32 s69, s71, s65
	s_mov_b32 m0, s69
	s_nop 0
	global_load_lds_dwordx4 v134, s[78:79]
	s_add_i32 m0, s69, 0x2000
	s_nop 0
	global_load_lds_dwordx4 v138, s[78:79]
	s_waitcnt vmcnt(6)
	s_barrier
	v_mfma_f32_16x16x32_bf16 v[60:63], v[198:201], v[166:169], v[60:63]
	v_mfma_f32_16x16x32_bf16 v[48:51], v[214:217], v[166:169], v[48:51]
	v_mfma_f32_16x16x32_bf16 v[32:35], v[214:217], v[174:177], v[32:35]
	v_mfma_f32_16x16x32_bf16 v[44:47], v[198:201], v[174:177], v[44:47]
	v_mfma_f32_16x16x32_bf16 v[28:31], v[198:201], v[182:185], v[28:31]
	v_mfma_f32_16x16x32_bf16 v[16:19], v[214:217], v[182:185], v[16:19]
	v_mfma_f32_16x16x32_bf16 v[0:3], v[214:217], v[190:193], v[0:3]
	v_mfma_f32_16x16x32_bf16 v[12:15], v[198:201], v[190:193], v[12:15]
	v_mfma_f32_16x16x32_bf16 v[60:63], v[210:213], v[170:173], v[60:63]
	v_mfma_f32_16x16x32_bf16 v[48:51], v[218:221], v[170:173], v[48:51]
	v_mfma_f32_16x16x32_bf16 v[32:35], v[218:221], v[178:181], v[32:35]
	v_mfma_f32_16x16x32_bf16 v[44:47], v[210:213], v[178:181], v[44:47]
	v_mfma_f32_16x16x32_bf16 v[28:31], v[210:213], v[186:189], v[28:31]
	v_mfma_f32_16x16x32_bf16 v[16:19], v[218:221], v[186:189], v[16:19]
	v_mfma_f32_16x16x32_bf16 v[0:3], v[218:221], v[194:197], v[0:3]
	v_mfma_f32_16x16x32_bf16 v[12:15], v[210:213], v[194:197], v[12:15]
	s_barrier
	s_add_i32 s63, s63, 2
	s_add_u32 s6, s6, 0x100
	s_addc_u32 s7, s7, 0
	s_add_u32 s20, s20, 0x100
	s_addc_u32 s25, s25, 0
	s_cmp_gt_u32 s63, 13
.LBB0_127:
	ds_read_b128 v[150:153], v205
	ds_read_b128 v[154:157], v205 offset:1024
	ds_read_b128 v[158:161], v205 offset:2048
	ds_read_b128 v[162:165], v205 offset:3072
	s_add_u32 s69, s6, 0xfffc0080
	s_addc_u32 s71, s7, -1
	s_cmp_eq_u32 s63, 12
	s_cselect_b32 s81, s1, s71
	s_cselect_b32 s80, s0, s69
	s_cselect_b32 s79, s73, s25
	s_cselect_b32 s78, s72, s20
	s_add_i32 m0, s67, 0xc000
	ds_read_b128 v[166:169], v206
	ds_read_b128 v[170:173], v206 offset:1024
	ds_read_b128 v[174:177], v206 offset:2048
	ds_read_b128 v[178:181], v206 offset:3072
	ds_read_b128 v[182:185], v206 offset:4096
	ds_read_b128 v[186:189], v206 offset:5120
	ds_read_b128 v[190:193], v206 offset:6144
	ds_read_b128 v[194:197], v206 offset:7168
	global_load_lds_dwordx4 v142, s[6:7]
	s_add_i32 m0, s67, 0xe000
	s_nop 0
	global_load_lds_dwordx4 v144, s[6:7]
	s_waitcnt lgkmcnt(8)
	s_barrier
	s_waitcnt lgkmcnt(0)
	v_mfma_f32_16x16x32_bf16 v[120:123], v[150:153], v[166:169], v[120:123]
	v_mfma_f32_16x16x32_bf16 v[116:119], v[158:161], v[166:169], v[116:119]
	v_mfma_f32_16x16x32_bf16 v[100:103], v[158:161], v[174:177], v[100:103]
	v_mfma_f32_16x16x32_bf16 v[104:107], v[150:153], v[174:177], v[104:107]
	v_mfma_f32_16x16x32_bf16 v[88:91], v[150:153], v[182:185], v[88:91]
	v_mfma_f32_16x16x32_bf16 v[84:87], v[158:161], v[182:185], v[84:87]
	v_mfma_f32_16x16x32_bf16 v[68:71], v[158:161], v[190:193], v[68:71]
	v_mfma_f32_16x16x32_bf16 v[72:75], v[150:153], v[190:193], v[72:75]
	v_mfma_f32_16x16x32_bf16 v[120:123], v[154:157], v[170:173], v[120:123]
	v_mfma_f32_16x16x32_bf16 v[116:119], v[162:165], v[170:173], v[116:119]
	v_mfma_f32_16x16x32_bf16 v[100:103], v[162:165], v[178:181], v[100:103]
	v_mfma_f32_16x16x32_bf16 v[104:107], v[154:157], v[178:181], v[104:107]
	v_mfma_f32_16x16x32_bf16 v[88:91], v[154:157], v[186:189], v[88:91]
	v_mfma_f32_16x16x32_bf16 v[84:87], v[162:165], v[186:189], v[84:87]
	v_mfma_f32_16x16x32_bf16 v[68:71], v[162:165], v[194:197], v[68:71]
	v_mfma_f32_16x16x32_bf16 v[72:75], v[154:157], v[194:197], v[72:75]
	s_barrier
	s_add_i32 s69, s91, s65
	s_add_u32 s100, s78, 0x80
	s_addc_u32 s101, s79, 0
	s_mov_b32 m0, s69
	ds_read_b128 v[198:201], v207
	ds_read_b128 v[210:213], v207 offset:1024
	ds_read_b128 v[214:217], v207 offset:2048
	ds_read_b128 v[218:221], v207 offset:3072
	global_load_lds_dwordx4 v134, s[78:79]
	s_add_i32 m0, s69, 0x2000
	s_nop 0
	global_load_lds_dwordx4 v138, s[78:79]
	s_barrier
	s_waitcnt lgkmcnt(0)
	v_mfma_f32_16x16x32_bf16 v[124:127], v[198:201], v[166:169], v[124:127]
	v_mfma_f32_16x16x32_bf16 v[112:115], v[214:217], v[166:169], v[112:115]
	v_mfma_f32_16x16x32_bf16 v[96:99], v[214:217], v[174:177], v[96:99]
	v_mfma_f32_16x16x32_bf16 v[108:111], v[198:201], v[174:177], v[108:111]
	v_mfma_f32_16x16x32_bf16 v[92:95], v[198:201], v[182:185], v[92:95]
	v_mfma_f32_16x16x32_bf16 v[80:83], v[214:217], v[182:185], v[80:83]
	v_mfma_f32_16x16x32_bf16 v[64:67], v[214:217], v[190:193], v[64:67]
	v_mfma_f32_16x16x32_bf16 v[76:79], v[198:201], v[190:193], v[76:79]
	v_mfma_f32_16x16x32_bf16 v[124:127], v[210:213], v[170:173], v[124:127]
	v_mfma_f32_16x16x32_bf16 v[112:115], v[218:221], v[170:173], v[112:115]
	v_mfma_f32_16x16x32_bf16 v[96:99], v[218:221], v[178:181], v[96:99]
	v_mfma_f32_16x16x32_bf16 v[108:111], v[210:213], v[178:181], v[108:111]
	v_mfma_f32_16x16x32_bf16 v[92:95], v[210:213], v[186:189], v[92:95]
	v_mfma_f32_16x16x32_bf16 v[80:83], v[218:221], v[186:189], v[80:83]
	v_mfma_f32_16x16x32_bf16 v[64:67], v[218:221], v[194:197], v[64:67]
	v_mfma_f32_16x16x32_bf16 v[76:79], v[210:213], v[194:197], v[76:79]
	s_barrier
	s_mov_b32 m0, s67
	ds_read_b128 v[166:169], v206 offset:16384
	ds_read_b128 v[170:173], v206 offset:17408
	ds_read_b128 v[174:177], v206 offset:18432
	ds_read_b128 v[178:181], v206 offset:19456
	ds_read_b128 v[182:185], v206 offset:20480
	ds_read_b128 v[186:189], v206 offset:21504
	ds_read_b128 v[190:193], v206 offset:22528
	ds_read_b128 v[194:197], v206 offset:23552
	global_load_lds_dwordx4 v132, s[80:81]
	s_mov_b32 m0, s75
	s_nop 0
	global_load_lds_dwordx4 v136, s[80:81]
	s_barrier
; #define PG8_STAGE(bufoff, gbase, voff) do { _Pragma("unroll") for (int _i = 0; _i < 2; ++_i) \
;         __builtin_amdgcn_global_load_lds((const unsigned*)((const char*)(gbase) + (voff)[_i]), (LAS unsigned*)(lds + (bufoff) + ldsw + _i * 8192), 16, 0, 0); } while (0)
; #define PG8_LDA(dst, b, h) do { _Pragma("unroll") for (int m = 0; m < 4; ++m) _Pragma("unroll") for (int k = 0; k < 2; ++k) dst[m][k] = *(const LAS bf16x8*)(lds + PG8_SA(b, h) + aoff + m * 2048 + k * 1024); } while (0)
; #define PG8_LDB(dst, b, h) do { _Pragma("unroll") for (int n = 0; n < 2; ++n) _Pragma("unroll") for (int k = 0; k < 2; ++k) dst[n][k] = *(const LAS bf16x8*)(lds + PG8_SB(b, h) + boff + n * 2048 + k * 1024); } while (0)
; #define PG8_WAIT_V(n) asm volatile("s_waitcnt vmcnt(" #n ")" ::: "memory")
; #define PG8_WAIT_L(n) asm volatile("s_waitcnt lgkmcnt(" #n ")" ::: "memory")
; #define PG8_BAR __builtin_amdgcn_s_barrier()
; #define PG8_SCHED __builtin_amdgcn_sched_barrier(0)
; template <class Epi, class Ptrs>
; __device__ __forceinline__ void gemm_phase(LAS unsigned char* lds, const int K, const StaticOrder& S, const Ptrs& P, const Epi& E) {
;     ...
;             PG8_LDB(B0, 0, 0); PG8_SCHED; PG8_LDA(At, 0, 0); PG8_STAGE(PG8_SA(1, 1), a1 + hstep, voffA);
;             PG8_WAIT_L(8); PG8_BAR; PG8_WAIT_L(0); PG8_MMA(0, 0, At, B0); PG8_BAR; PG8_SCHED;
;             PG8_LDB(B1, 0, 1); PG8_STAGE(PG8_SB(0, 0), b2, voffB);
;             PG8_BAR; PG8_WAIT_L(0); PG8_MMA(0, 1, At, B1); PG8_BAR;
;             PG8_LDA(At, 0, 1); PG8_STAGE(PG8_SA(0, 0), a2, voffA);
;             PG8_BAR; PG8_WAIT_L(0); PG8_MMA(1, 0, At, B0); PG8_BAR; PG8_SCHED;
;             PG8_STAGE(PG8_SB(0, 1), b2 + hstep, voffB);
;             PG8_WAIT_V(6); PG8_BAR; PG8_MMA(1, 1, At, B1); PG8_BAR;
;             PG8_LDB(B0, 1, 0); PG8_SCHED; PG8_LDA(At, 1, 0); PG8_STAGE(PG8_SA(0, 1), a2 + hstep, voffA);
;             PG8_WAIT_L(8); PG8_BAR; PG8_WAIT_L(0); PG8_MMA(0, 0, At, B0); PG8_BAR; PG8_SCHED;
;             PG8_LDB(B1, 1, 1); PG8_STAGE(PG8_SB(1, 0), b3, voffB);
;             PG8_BAR; PG8_WAIT_L(0); PG8_MMA(0, 1, At, B1); PG8_BAR;
;             PG8_LDA(At, 1, 1); PG8_STAGE(PG8_SA(1, 0), a3, voffA);
;             PG8_BAR; PG8_WAIT_L(0); PG8_MMA(1, 0, At, B0); PG8_BAR; PG8_SCHED;
;             PG8_STAGE(PG8_SB(1, 1), b3 + hstep, voffB);
;             PG8_WAIT_V(6); PG8_BAR; PG8_MMA(1, 1, At, B1); PG8_BAR;
	s_waitcnt lgkmcnt(0)
	v_mfma_f32_16x16x32_bf16 v[56:59], v[150:153], v[166:169], v[56:59]
	v_mfma_f32_16x16x32_bf16 v[52:55], v[158:161], v[166:169], v[52:55]
	v_mfma_f32_16x16x32_bf16 v[36:39], v[158:161], v[174:177], v[36:39]
	v_mfma_f32_16x16x32_bf16 v[40:43], v[150:153], v[174:177], v[40:43]
	v_mfma_f32_16x16x32_bf16 v[24:27], v[150:153], v[182:185], v[24:27]
	v_mfma_f32_16x16x32_bf16 v[20:23], v[158:161], v[182:185], v[20:23]
	v_mfma_f32_16x16x32_bf16 v[4:7], v[158:161], v[190:193], v[4:7]
	v_mfma_f32_16x16x32_bf16 v[8:11], v[150:153], v[190:193], v[8:11]
	v_mfma_f32_16x16x32_bf16 v[56:59], v[154:157], v[170:173], v[56:59]
	v_mfma_f32_16x16x32_bf16 v[52:55], v[162:165], v[170:173], v[52:55]
	v_mfma_f32_16x16x32_bf16 v[36:39], v[162:165], v[178:181], v[36:39]
	v_mfma_f32_16x16x32_bf16 v[40:43], v[154:157], v[178:181], v[40:43]
	v_mfma_f32_16x16x32_bf16 v[24:27], v[154:157], v[186:189], v[24:27]
	v_mfma_f32_16x16x32_bf16 v[20:23], v[162:165], v[186:189], v[20:23]
	v_mfma_f32_16x16x32_bf16 v[4:7], v[162:165], v[194:197], v[4:7]
	v_mfma_f32_16x16x32_bf16 v[8:11], v[154:157], v[194:197], v[8:11]
	s_barrier
	s_add_u32 s82, s78, 0x40000
	s_addc_u32 s83, s79, 0
	s_add_i32 s69, s92, s65
	s_mov_b32 m0, s69
	s_nop 0
	global_load_lds_dwordx4 v134, s[82:83]
	s_add_i32 m0, s69, 0x2000
	s_nop 0
	global_load_lds_dwordx4 v138, s[82:83]
	s_waitcnt vmcnt(6)
	s_barrier
	v_mfma_f32_16x16x32_bf16 v[60:63], v[198:201], v[166:169], v[60:63]
	v_mfma_f32_16x16x32_bf16 v[48:51], v[214:217], v[166:169], v[48:51]
	v_mfma_f32_16x16x32_bf16 v[32:35], v[214:217], v[174:177], v[32:35]
	v_mfma_f32_16x16x32_bf16 v[44:47], v[198:201], v[174:177], v[44:47]
	v_mfma_f32_16x16x32_bf16 v[28:31], v[198:201], v[182:185], v[28:31]
	v_mfma_f32_16x16x32_bf16 v[16:19], v[214:217], v[182:185], v[16:19]
	v_mfma_f32_16x16x32_bf16 v[0:3], v[214:217], v[190:193], v[0:3]
	v_mfma_f32_16x16x32_bf16 v[12:15], v[198:201], v[190:193], v[12:15]
	v_mfma_f32_16x16x32_bf16 v[60:63], v[210:213], v[170:173], v[60:63]
	v_mfma_f32_16x16x32_bf16 v[48:51], v[218:221], v[170:173], v[48:51]
	v_mfma_f32_16x16x32_bf16 v[32:35], v[218:221], v[178:181], v[32:35]
	v_mfma_f32_16x16x32_bf16 v[44:47], v[210:213], v[178:181], v[44:47]
	v_mfma_f32_16x16x32_bf16 v[28:31], v[210:213], v[186:189], v[28:31]
	v_mfma_f32_16x16x32_bf16 v[16:19], v[218:221], v[186:189], v[16:19]
	v_mfma_f32_16x16x32_bf16 v[0:3], v[218:221], v[194:197], v[0:3]
	v_mfma_f32_16x16x32_bf16 v[12:15], v[210:213], v[194:197], v[12:15]
	s_barrier
	s_add_i32 s69, 0, 0x18000
	ds_read_b128 v[150:153], v252
	ds_read_b128 v[154:157], v252 offset:1024
	ds_read_b128 v[158:161], v252 offset:2048
	ds_read_b128 v[162:165], v252 offset:3072
	s_add_u32 s80, s80, 0x40000
	s_addc_u32 s81, s81, 0
	s_mov_b32 m0, s77
	ds_read_b128 v[166:169], v206 offset:32768
	ds_read_b128 v[170:173], v206 offset:33792
	ds_read_b128 v[174:177], v206 offset:34816
	ds_read_b128 v[178:181], v206 offset:35840
	ds_read_b128 v[182:185], v206 offset:36864
	ds_read_b128 v[186:189], v206 offset:37888
	ds_read_b128 v[190:193], v206 offset:38912
	ds_read_b128 v[194:197], v206 offset:39936
	global_load_lds_dwordx4 v132, s[80:81]
	s_mov_b32 m0, s85
	s_nop 0
	global_load_lds_dwordx4 v136, s[80:81]
	s_waitcnt lgkmcnt(8)
	s_barrier
	s_waitcnt lgkmcnt(0)
	v_mfma_f32_16x16x32_bf16 v[120:123], v[150:153], v[166:169], v[120:123]
	v_mfma_f32_16x16x32_bf16 v[116:119], v[158:161], v[166:169], v[116:119]
	v_mfma_f32_16x16x32_bf16 v[100:103], v[158:161], v[174:177], v[100:103]
	v_mfma_f32_16x16x32_bf16 v[104:107], v[150:153], v[174:177], v[104:107]
	v_mfma_f32_16x16x32_bf16 v[88:91], v[150:153], v[182:185], v[88:91]
	v_mfma_f32_16x16x32_bf16 v[84:87], v[158:161], v[182:185], v[84:87]
	v_mfma_f32_16x16x32_bf16 v[68:71], v[158:161], v[190:193], v[68:71]
	v_mfma_f32_16x16x32_bf16 v[72:75], v[150:153], v[190:193], v[72:75]
	v_mfma_f32_16x16x32_bf16 v[120:123], v[154:157], v[170:173], v[120:123]
	v_mfma_f32_16x16x32_bf16 v[116:119], v[162:165], v[170:173], v[116:119]
	v_mfma_f32_16x16x32_bf16 v[100:103], v[162:165], v[178:181], v[100:103]
	v_mfma_f32_16x16x32_bf16 v[104:107], v[154:157], v[178:181], v[104:107]
	v_mfma_f32_16x16x32_bf16 v[88:91], v[154:157], v[186:189], v[88:91]
	v_mfma_f32_16x16x32_bf16 v[84:87], v[162:165], v[186:189], v[84:87]
	v_mfma_f32_16x16x32_bf16 v[68:71], v[162:165], v[194:197], v[68:71]
	v_mfma_f32_16x16x32_bf16 v[72:75], v[154:157], v[194:197], v[72:75]
	s_barrier
	s_add_i32 s71, 0, 0x1c000
	s_add_i32 s69, s69, s65
	s_mov_b32 m0, s69
	ds_read_b128 v[198:201], v253
	ds_read_b128 v[210:213], v253 offset:1024
	ds_read_b128 v[214:217], v253 offset:2048
	ds_read_b128 v[218:221], v253 offset:3072
	global_load_lds_dwordx4 v134, s[100:101]
	s_add_i32 m0, s69, 0x2000
	s_nop 0
	global_load_lds_dwordx4 v138, s[100:101]
	s_barrier
; #define PG8_STAGE(bufoff, gbase, voff) do { _Pragma("unroll") for (int _i = 0; _i < 2; ++_i) \
;         __builtin_amdgcn_global_load_lds((const unsigned*)((const char*)(gbase) + (voff)[_i]), (LAS unsigned*)(lds + (bufoff) + ldsw + _i * 8192), 16, 0, 0); } while (0)
; #define PG8_LDA(dst, b, h) do { _Pragma("unroll") for (int m = 0; m < 4; ++m) _Pragma("unroll") for (int k = 0; k < 2; ++k) dst[m][k] = *(const LAS bf16x8*)(lds + PG8_SA(b, h) + aoff + m * 2048 + k * 1024); } while (0)
; #define PG8_WAIT_V(n) asm volatile("s_waitcnt vmcnt(" #n ")" ::: "memory")
; #define PG8_BAR __builtin_amdgcn_s_barrier()
; template <class Epi, class Ptrs>
; __device__ __forceinline__ void gemm_phase(LAS unsigned char* lds, const int K, const StaticOrder& S, const Ptrs& P, const Epi& E) {
;     ...
;             PG8_LDB(B0, 0, 0); PG8_SCHED; PG8_LDA(At, 0, 0); PG8_STAGE(PG8_SA(1, 1), a1 + hstep, voffA);
;             PG8_WAIT_L(8); PG8_BAR; PG8_WAIT_L(0); PG8_MMA(0, 0, At, B0); PG8_BAR; PG8_SCHED;
;             PG8_LDB(B1, 0, 1); PG8_STAGE(PG8_SB(0, 0), b2, voffB);
;             PG8_BAR; PG8_WAIT_L(0); PG8_MMA(0, 1, At, B1); PG8_BAR;
;             PG8_LDA(At, 0, 1); PG8_STAGE(PG8_SA(0, 0), a2, voffA);
;             PG8_BAR; PG8_WAIT_L(0); PG8_MMA(1, 0, At, B0); PG8_BAR; PG8_SCHED;
;             PG8_STAGE(PG8_SB(0, 1), b2 + hstep, voffB);
;             PG8_WAIT_V(6); PG8_BAR; PG8_MMA(1, 1, At, B1); PG8_BAR;
;             PG8_LDB(B0, 1, 0); PG8_SCHED; PG8_LDA(At, 1, 0); PG8_STAGE(PG8_SA(0, 1), a2 + hstep, voffA);
;             PG8_WAIT_L(8); PG8_BAR; PG8_WAIT_L(0); PG8_MMA(0, 0, At, B0); PG8_BAR; PG8_SCHED;
;             PG8_LDB(B1, 1, 1); PG8_STAGE(PG8_SB(1, 0), b3, voffB);
;             PG8_BAR; PG8_WAIT_L(0); PG8_MMA(0, 1, At, B1); PG8_BAR;
;             PG8_LDA(At, 1, 1); PG8_STAGE(PG8_SA(1, 0), a3, voffA);
;             PG8_BAR; PG8_WAIT_L(0); PG8_MMA(1, 0, At, B0); PG8_BAR; PG8_SCHED;
;             PG8_STAGE(PG8_SB(1, 1), b3 + hstep, voffB);
;             PG8_WAIT_V(6); PG8_BAR; PG8_MMA(1, 1, At, B1); PG8_BAR;
;     ...
;         if (!has_next) break;
; #pragma unroll
;         for (int a = 0; a < 2; ++a)
; #pragma unroll
;             for (int b = 0; b < 2; ++b)
; #pragma unroll
;                 for (int m = 0; m < 4; ++m)
; #pragma unroll
;                     for (int n = 0; n < 2; ++n) acc[a][b][m][n] = (f32x4){0.f, 0.f, 0.f, 0.f};
;         cur = nxt; cA = nA; cB = nB; ++ui;
	s_waitcnt lgkmcnt(0)
	v_mfma_f32_16x16x32_bf16 v[124:127], v[198:201], v[166:169], v[124:127]
	v_mfma_f32_16x16x32_bf16 v[112:115], v[214:217], v[166:169], v[112:115]
	v_mfma_f32_16x16x32_bf16 v[96:99], v[214:217], v[174:177], v[96:99]
	v_mfma_f32_16x16x32_bf16 v[108:111], v[198:201], v[174:177], v[108:111]
	v_mfma_f32_16x16x32_bf16 v[92:95], v[198:201], v[182:185], v[92:95]
	v_mfma_f32_16x16x32_bf16 v[80:83], v[214:217], v[182:185], v[80:83]
	v_mfma_f32_16x16x32_bf16 v[64:67], v[214:217], v[190:193], v[64:67]
	v_mfma_f32_16x16x32_bf16 v[76:79], v[198:201], v[190:193], v[76:79]
	v_mfma_f32_16x16x32_bf16 v[124:127], v[210:213], v[170:173], v[124:127]
	v_mfma_f32_16x16x32_bf16 v[112:115], v[218:221], v[170:173], v[112:115]
	v_mfma_f32_16x16x32_bf16 v[96:99], v[218:221], v[178:181], v[96:99]
	v_mfma_f32_16x16x32_bf16 v[108:111], v[210:213], v[178:181], v[108:111]
	v_mfma_f32_16x16x32_bf16 v[92:95], v[210:213], v[186:189], v[92:95]
	v_mfma_f32_16x16x32_bf16 v[80:83], v[218:221], v[186:189], v[80:83]
	v_mfma_f32_16x16x32_bf16 v[64:67], v[218:221], v[194:197], v[64:67]
	v_mfma_f32_16x16x32_bf16 v[76:79], v[210:213], v[194:197], v[76:79]
	s_barrier
	s_mov_b32 m0, s89
	s_add_u32 s100, s80, 0xfffc0080
	s_addc_u32 s101, s81, -1
	ds_read_b128 v[166:169], v206 offset:49152
	ds_read_b128 v[170:173], v206 offset:50176
	ds_read_b128 v[174:177], v206 offset:51200
	ds_read_b128 v[178:181], v206 offset:52224
	ds_read_b128 v[182:185], v206 offset:53248
	ds_read_b128 v[186:189], v206 offset:54272
	ds_read_b128 v[190:193], v206 offset:55296
	ds_read_b128 v[194:197], v206 offset:56320
	global_load_lds_dwordx4 v132, s[100:101]
	s_mov_b32 m0, s90
	s_nop 0
	global_load_lds_dwordx4 v136, s[100:101]
	s_barrier
	s_waitcnt lgkmcnt(0)
	v_mfma_f32_16x16x32_bf16 v[56:59], v[150:153], v[166:169], v[56:59]
	v_mfma_f32_16x16x32_bf16 v[52:55], v[158:161], v[166:169], v[52:55]
	v_mfma_f32_16x16x32_bf16 v[36:39], v[158:161], v[174:177], v[36:39]
	v_mfma_f32_16x16x32_bf16 v[40:43], v[150:153], v[174:177], v[40:43]
	v_mfma_f32_16x16x32_bf16 v[24:27], v[150:153], v[182:185], v[24:27]
	v_mfma_f32_16x16x32_bf16 v[20:23], v[158:161], v[182:185], v[20:23]
	v_mfma_f32_16x16x32_bf16 v[4:7], v[158:161], v[190:193], v[4:7]
	v_mfma_f32_16x16x32_bf16 v[8:11], v[150:153], v[190:193], v[8:11]
	v_mfma_f32_16x16x32_bf16 v[56:59], v[154:157], v[170:173], v[56:59]
	v_mfma_f32_16x16x32_bf16 v[52:55], v[162:165], v[170:173], v[52:55]
	v_mfma_f32_16x16x32_bf16 v[36:39], v[162:165], v[178:181], v[36:39]
	v_mfma_f32_16x16x32_bf16 v[40:43], v[154:157], v[178:181], v[40:43]
	v_mfma_f32_16x16x32_bf16 v[24:27], v[154:157], v[186:189], v[24:27]
	v_mfma_f32_16x16x32_bf16 v[20:23], v[162:165], v[186:189], v[20:23]
	v_mfma_f32_16x16x32_bf16 v[4:7], v[162:165], v[194:197], v[4:7]
	v_mfma_f32_16x16x32_bf16 v[8:11], v[154:157], v[194:197], v[8:11]
	s_barrier
	s_add_u32 s78, s78, 0x40080
	s_addc_u32 s79, s79, 0
	s_add_i32 s69, s71, s65
	s_mov_b32 m0, s69
	s_nop 0
	global_load_lds_dwordx4 v134, s[78:79]
	s_add_i32 m0, s69, 0x2000
	s_nop 0
	global_load_lds_dwordx4 v138, s[78:79]
	s_waitcnt vmcnt(6)
	s_barrier
	v_mfma_f32_16x16x32_bf16 v[60:63], v[198:201], v[166:169], v[60:63]
	v_mfma_f32_16x16x32_bf16 v[48:51], v[214:217], v[166:169], v[48:51]
	v_mfma_f32_16x16x32_bf16 v[32:35], v[214:217], v[174:177], v[32:35]
	v_mfma_f32_16x16x32_bf16 v[44:47], v[198:201], v[174:177], v[44:47]
	v_mfma_f32_16x16x32_bf16 v[28:31], v[198:201], v[182:185], v[28:31]
	v_mfma_f32_16x16x32_bf16 v[16:19], v[214:217], v[182:185], v[16:19]
	v_mfma_f32_16x16x32_bf16 v[0:3], v[214:217], v[190:193], v[0:3]
	v_mfma_f32_16x16x32_bf16 v[12:15], v[198:201], v[190:193], v[12:15]
	v_mfma_f32_16x16x32_bf16 v[60:63], v[210:213], v[170:173], v[60:63]
	v_mfma_f32_16x16x32_bf16 v[48:51], v[218:221], v[170:173], v[48:51]
	v_mfma_f32_16x16x32_bf16 v[32:35], v[218:221], v[178:181], v[32:35]
	v_mfma_f32_16x16x32_bf16 v[44:47], v[210:213], v[178:181], v[44:47]
	v_mfma_f32_16x16x32_bf16 v[28:31], v[210:213], v[186:189], v[28:31]
	v_mfma_f32_16x16x32_bf16 v[16:19], v[218:221], v[186:189], v[16:19]
	v_mfma_f32_16x16x32_bf16 v[0:3], v[218:221], v[194:197], v[0:3]
	v_mfma_f32_16x16x32_bf16 v[12:15], v[210:213], v[194:197], v[12:15]
	s_barrier
	s_add_i32 s63, s63, 2
	s_add_u32 s6, s6, 0x100
	s_addc_u32 s7, s7, 0
	s_add_u32 s20, s20, 0x100
	s_addc_u32 s25, s25, 0
	s_cmp_gt_u32 s63, 13
	s_cbranch_scc0 .LBB0_127
	s_cmp_gt_i32 s74, 7
	s_mov_b64 s[6:7], -1
	s_cbranch_scc0 .LBB0_188
	s_sub_i32 s25, s74, 17
	s_cmp_gt_u32 s25, 3
	s_cbranch_scc0 .LBB0_170
	s_lshl_b32 s69, s76, 8
	s_cmp_gt_u32 s74, 11
	s_cbranch_scc0 .LBB0_135
	s_cmp_eq_u32 s74, 12
	s_mov_b64 s[6:7], 0
	s_cbranch_scc1 .LBB0_134
	s_cmp_gt_u32 s74, 16
	s_cbranch_scc1 .LBB0_191
	s_lshl_b32 s20, s74, 8
	v_readlane_b32 s80, v254, 2
	s_addk_i32 s20, 0xf300
	s_mov_b64 s[78:79], 0x400
	s_mov_b64 s[82:83], -1
	s_mov_b32 s63, s69
	v_readlane_b32 s81, v254, 3
	s_andn2_b64 vcc, exec, s[6:7]
	s_cbranch_vccz .LBB0_136
	s_branch .LBB0_137

; #define PG8_STAGE(bufoff, gbase, voff) do { _Pragma("unroll") for (int _i = 0; _i < 2; ++_i) \
;         __builtin_amdgcn_global_load_lds((const unsigned*)((const char*)(gbase) + (voff)[_i]), (LAS unsigned*)(lds + (bufoff) + ldsw + _i * 8192), 16, 0, 0); } while (0)
; #define PG8_LDA(dst, b, h) do { _Pragma("unroll") for (int m = 0; m < 4; ++m) _Pragma("unroll") for (int k = 0; k < 2; ++k) dst[m][k] = *(const LAS bf16x8*)(lds + PG8_SA(b, h) + aoff + m * 2048 + k * 1024); } while (0)
; #define PG8_LDB(dst, b, h) do { _Pragma("unroll") for (int n = 0; n < 2; ++n) _Pragma("unroll") for (int k = 0; k < 2; ++k) dst[n][k] = *(const LAS bf16x8*)(lds + PG8_SB(b, h) + boff + n * 2048 + k * 1024); } while (0)
; #define PG8_WAIT_V(n) asm volatile("s_waitcnt vmcnt(" #n ")" ::: "memory")
; #define PG8_WAIT_L(n) asm volatile("s_waitcnt lgkmcnt(" #n ")" ::: "memory")
; #define PG8_BAR __builtin_amdgcn_s_barrier()
; template <class Epi, class Ptrs>
; __device__ __forceinline__ void gemm_phase(LAS unsigned char* lds, const int K, const StaticOrder& S, const Ptrs& P, const Epi& E) {
;     ...
;         const char* nA = cA; const char* nB = cB; if (has_next) P.get(nxt, nA, nB);
;         for (int t = 0; t < nt; t += 2) {
;             const bool last = (t == nt - 2);
;             const char* a1 = cA + (size_t)(t + 1) * kstep;
;             const char* a2 = last ? nA : cA + (size_t)(t + 2) * kstep; const char* b2 = last ? nB : cB + (size_t)(t + 2) * kstep;
;             const char* a3 = a2 + kstep; const char* b3 = b2 + kstep;
;             PG8_LDB(B0, 0, 0); PG8_SCHED; PG8_LDA(At, 0, 0); PG8_STAGE(PG8_SA(1, 1), a1 + hstep, voffA);
;             PG8_WAIT_L(8); PG8_BAR; PG8_WAIT_L(0); PG8_MMA(0, 0, At, B0); PG8_BAR; PG8_SCHED;
;             PG8_LDB(B1, 0, 1); PG8_STAGE(PG8_SB(0, 0), b2, voffB);
;             PG8_BAR; PG8_WAIT_L(0); PG8_MMA(0, 1, At, B1); PG8_BAR;
;             PG8_LDA(At, 0, 1); PG8_STAGE(PG8_SA(0, 0), a2, voffA);
;             PG8_BAR; PG8_WAIT_L(0); PG8_MMA(1, 0, At, B0); PG8_BAR; PG8_SCHED;
;             PG8_STAGE(PG8_SB(0, 1), b2 + hstep, voffB);
;             PG8_WAIT_V(6); PG8_BAR; PG8_MMA(1, 1, At, B1); PG8_BAR;
;             PG8_LDB(B0, 1, 0); PG8_SCHED; PG8_LDA(At, 1, 0); PG8_STAGE(PG8_SA(0, 1), a2 + hstep, voffA);
;             PG8_WAIT_L(8); PG8_BAR; PG8_WAIT_L(0); PG8_MMA(0, 0, At, B0); PG8_BAR; PG8_SCHED;
.LBB0_352:
	s_add_u32 s38, s44, 0x40080
	s_addc_u32 s39, s45, 0
	s_add_u32 s21, s42, 0x100
	s_addc_u32 s23, s43, 0
	s_mov_b32 s41, -2
	v_add_u32_e32 v252, 0x18000, v205
	v_add_u32_e32 v253, 0x1c000, v205
	ds_read_b128 v[128:131], v207
	ds_read_b128 v[132:135], v207 offset:1024
	ds_read_b128 v[136:139], v207 offset:2048
	ds_read_b128 v[140:143], v207 offset:3072
	s_add_u32 s42, s38, 0xfffc0080
	s_addc_u32 s43, s39, -1
	s_cmp_eq_u32 s41, 12
	s_cselect_b32 s45, s1, s43
	s_cselect_b32 s44, s0, s42
	s_cselect_b32 s43, s25, s23
	s_cselect_b32 s42, s24, s21
	s_add_i32 m0, s54, 0xc000
	ds_read_b128 v[144:147], v209
	ds_read_b128 v[148:151], v209 offset:1024
	ds_read_b128 v[152:155], v209 offset:2048
	ds_read_b128 v[156:159], v209 offset:3072
	ds_read_b128 v[160:163], v209 offset:4096
	ds_read_b128 v[164:167], v209 offset:5120
	ds_read_b128 v[168:171], v209 offset:6144
	ds_read_b128 v[172:175], v209 offset:7168
	global_load_lds_dwordx4 v184, s[38:39]
	s_add_i32 m0, s54, 0xe000
	s_nop 0
	global_load_lds_dwordx4 v186, s[38:39]
	s_waitcnt lgkmcnt(8)
	s_barrier
	s_waitcnt lgkmcnt(0)
	v_mfma_f32_16x16x32_bf16 v[124:127], v[128:131], v[144:147], 0
	v_mfma_f32_16x16x32_bf16 v[120:123], v[136:139], v[144:147], 0
	v_mfma_f32_16x16x32_bf16 v[104:107], v[136:139], v[152:155], 0
	v_mfma_f32_16x16x32_bf16 v[108:111], v[128:131], v[152:155], 0
	v_mfma_f32_16x16x32_bf16 v[92:95], v[128:131], v[160:163], 0
	v_mfma_f32_16x16x32_bf16 v[88:91], v[136:139], v[160:163], 0
	v_mfma_f32_16x16x32_bf16 v[72:75], v[136:139], v[168:171], 0
	v_mfma_f32_16x16x32_bf16 v[76:79], v[128:131], v[168:171], 0
	v_mfma_f32_16x16x32_bf16 v[124:127], v[132:135], v[148:151], v[124:127]
	v_mfma_f32_16x16x32_bf16 v[120:123], v[140:143], v[148:151], v[120:123]
	v_mfma_f32_16x16x32_bf16 v[104:107], v[140:143], v[156:159], v[104:107]
	v_mfma_f32_16x16x32_bf16 v[108:111], v[132:135], v[156:159], v[108:111]
	v_mfma_f32_16x16x32_bf16 v[92:95], v[132:135], v[164:167], v[92:95]
	v_mfma_f32_16x16x32_bf16 v[88:91], v[140:143], v[164:167], v[88:91]
	v_mfma_f32_16x16x32_bf16 v[72:75], v[140:143], v[172:175], v[72:75]
	v_mfma_f32_16x16x32_bf16 v[76:79], v[132:135], v[172:175], v[76:79]
	s_barrier
	s_add_i32 s69, s66, s51
	s_add_u32 s90, s42, 0x80
	s_addc_u32 s91, s43, 0
	s_mov_b32 m0, s69
	ds_read_b128 v[192:195], v210
	ds_read_b128 v[196:199], v210 offset:1024
	ds_read_b128 v[200:203], v210 offset:2048
	ds_read_b128 v[212:215], v210 offset:3072
	global_load_lds_dwordx4 v178, s[42:43]
	s_add_i32 m0, s69, 0x2000
	s_nop 0
	global_load_lds_dwordx4 v182, s[42:43]
	s_barrier
	s_waitcnt lgkmcnt(0)
	v_mfma_f32_16x16x32_bf16 v[116:119], v[192:195], v[144:147], 0
	v_mfma_f32_16x16x32_bf16 v[112:115], v[200:203], v[144:147], 0
	v_mfma_f32_16x16x32_bf16 v[96:99], v[200:203], v[152:155], 0
	v_mfma_f32_16x16x32_bf16 v[100:103], v[192:195], v[152:155], 0
	v_mfma_f32_16x16x32_bf16 v[84:87], v[192:195], v[160:163], 0
	v_mfma_f32_16x16x32_bf16 v[80:83], v[200:203], v[160:163], 0
	v_mfma_f32_16x16x32_bf16 v[64:67], v[200:203], v[168:171], 0
	v_mfma_f32_16x16x32_bf16 v[68:71], v[192:195], v[168:171], 0
	v_mfma_f32_16x16x32_bf16 v[116:119], v[196:199], v[148:151], v[116:119]
	v_mfma_f32_16x16x32_bf16 v[112:115], v[212:215], v[148:151], v[112:115]
	v_mfma_f32_16x16x32_bf16 v[96:99], v[212:215], v[156:159], v[96:99]
	v_mfma_f32_16x16x32_bf16 v[100:103], v[196:199], v[156:159], v[100:103]
	v_mfma_f32_16x16x32_bf16 v[84:87], v[196:199], v[164:167], v[84:87]
	v_mfma_f32_16x16x32_bf16 v[80:83], v[212:215], v[164:167], v[80:83]
	v_mfma_f32_16x16x32_bf16 v[64:67], v[212:215], v[172:175], v[64:67]
	v_mfma_f32_16x16x32_bf16 v[68:71], v[196:199], v[172:175], v[68:71]
	s_barrier
	s_mov_b32 m0, s54
	s_add_u32 s92, s44, 0x80
	s_addc_u32 s93, s45, 0
	ds_read_b128 v[144:147], v209 offset:16384
	ds_read_b128 v[148:151], v209 offset:17408
	ds_read_b128 v[152:155], v209 offset:18432
	ds_read_b128 v[156:159], v209 offset:19456
	ds_read_b128 v[160:163], v209 offset:20480
	ds_read_b128 v[164:167], v209 offset:21504
	ds_read_b128 v[168:171], v209 offset:22528
	ds_read_b128 v[172:175], v209 offset:23552
	global_load_lds_dwordx4 v176, s[44:45]
	s_mov_b32 m0, s55
	s_nop 0
	global_load_lds_dwordx4 v180, s[44:45]
	s_barrier
	s_waitcnt lgkmcnt(0)
	v_mfma_f32_16x16x32_bf16 v[60:63], v[128:131], v[144:147], 0
	v_mfma_f32_16x16x32_bf16 v[56:59], v[136:139], v[144:147], 0
	v_mfma_f32_16x16x32_bf16 v[40:43], v[136:139], v[152:155], 0
	v_mfma_f32_16x16x32_bf16 v[44:47], v[128:131], v[152:155], 0
	v_mfma_f32_16x16x32_bf16 v[28:31], v[128:131], v[160:163], 0
	v_mfma_f32_16x16x32_bf16 v[24:27], v[136:139], v[160:163], 0
	v_mfma_f32_16x16x32_bf16 v[8:11], v[136:139], v[168:171], 0
	v_mfma_f32_16x16x32_bf16 v[12:15], v[128:131], v[168:171], 0
	v_mfma_f32_16x16x32_bf16 v[60:63], v[132:135], v[148:151], v[60:63]
	v_mfma_f32_16x16x32_bf16 v[56:59], v[140:143], v[148:151], v[56:59]
	v_mfma_f32_16x16x32_bf16 v[40:43], v[140:143], v[156:159], v[40:43]
	v_mfma_f32_16x16x32_bf16 v[44:47], v[132:135], v[156:159], v[44:47]
	v_mfma_f32_16x16x32_bf16 v[28:31], v[132:135], v[164:167], v[28:31]
	v_mfma_f32_16x16x32_bf16 v[24:27], v[140:143], v[164:167], v[24:27]
	v_mfma_f32_16x16x32_bf16 v[8:11], v[140:143], v[172:175], v[8:11]
	v_mfma_f32_16x16x32_bf16 v[12:15], v[132:135], v[172:175], v[12:15]
	s_barrier
	s_add_u32 s70, s42, 0x40000
	s_addc_u32 s71, s43, 0
	s_add_i32 s69, s67, s51
	s_mov_b32 m0, s69
	s_nop 0
	global_load_lds_dwordx4 v178, s[70:71]
	s_add_i32 m0, s69, 0x2000
	s_nop 0
	global_load_lds_dwordx4 v182, s[70:71]
	s_waitcnt vmcnt(6)
	s_barrier
; #define PG8_STAGE(bufoff, gbase, voff) do { _Pragma("unroll") for (int _i = 0; _i < 2; ++_i) \
;         __builtin_amdgcn_global_load_lds((const unsigned*)((const char*)(gbase) + (voff)[_i]), (LAS unsigned*)(lds + (bufoff) + ldsw + _i * 8192), 16, 0, 0); } while (0)
; #define PG8_LDA(dst, b, h) do { _Pragma("unroll") for (int m = 0; m < 4; ++m) _Pragma("unroll") for (int k = 0; k < 2; ++k) dst[m][k] = *(const LAS bf16x8*)(lds + PG8_SA(b, h) + aoff + m * 2048 + k * 1024); } while (0)
; #define PG8_LDB(dst, b, h) do { _Pragma("unroll") for (int n = 0; n < 2; ++n) _Pragma("unroll") for (int k = 0; k < 2; ++k) dst[n][k] = *(const LAS bf16x8*)(lds + PG8_SB(b, h) + boff + n * 2048 + k * 1024); } while (0)
; #define PG8_WAIT_V(n) asm volatile("s_waitcnt vmcnt(" #n ")" ::: "memory")
; #define PG8_WAIT_L(n) asm volatile("s_waitcnt lgkmcnt(" #n ")" ::: "memory")
; #define PG8_BAR __builtin_amdgcn_s_barrier()
; #define PG8_SCHED __builtin_amdgcn_sched_barrier(0)
; template <class Epi, class Ptrs>
; __device__ __forceinline__ void gemm_phase(LAS unsigned char* lds, const int K, const StaticOrder& S, const Ptrs& P, const Epi& E) {
;     ...
;             PG8_LDB(B0, 0, 0); PG8_SCHED; PG8_LDA(At, 0, 0); PG8_STAGE(PG8_SA(1, 1), a1 + hstep, voffA);
;             PG8_WAIT_L(8); PG8_BAR; PG8_WAIT_L(0); PG8_MMA(0, 0, At, B0); PG8_BAR; PG8_SCHED;
;             PG8_LDB(B1, 0, 1); PG8_STAGE(PG8_SB(0, 0), b2, voffB);
;             PG8_BAR; PG8_WAIT_L(0); PG8_MMA(0, 1, At, B1); PG8_BAR;
;             PG8_LDA(At, 0, 1); PG8_STAGE(PG8_SA(0, 0), a2, voffA);
;             PG8_BAR; PG8_WAIT_L(0); PG8_MMA(1, 0, At, B0); PG8_BAR; PG8_SCHED;
;             PG8_STAGE(PG8_SB(0, 1), b2 + hstep, voffB);
;             PG8_WAIT_V(6); PG8_BAR; PG8_MMA(1, 1, At, B1); PG8_BAR;
;             PG8_LDB(B0, 1, 0); PG8_SCHED; PG8_LDA(At, 1, 0); PG8_STAGE(PG8_SA(0, 1), a2 + hstep, voffA);
;             PG8_WAIT_L(8); PG8_BAR; PG8_WAIT_L(0); PG8_MMA(0, 0, At, B0); PG8_BAR; PG8_SCHED;
;             PG8_LDB(B1, 1, 1); PG8_STAGE(PG8_SB(1, 0), b3, voffB);
;             PG8_BAR; PG8_WAIT_L(0); PG8_MMA(0, 1, At, B1); PG8_BAR;
;             PG8_LDA(At, 1, 1); PG8_STAGE(PG8_SA(1, 0), a3, voffA);
;             PG8_BAR; PG8_WAIT_L(0); PG8_MMA(1, 0, At, B0); PG8_BAR; PG8_SCHED;
;             PG8_STAGE(PG8_SB(1, 1), b3 + hstep, voffB);
;             PG8_WAIT_V(6); PG8_BAR; PG8_MMA(1, 1, At, B1); PG8_BAR;
	v_mfma_f32_16x16x32_bf16 v[52:55], v[192:195], v[144:147], 0
	v_mfma_f32_16x16x32_bf16 v[48:51], v[200:203], v[144:147], 0
	v_mfma_f32_16x16x32_bf16 v[32:35], v[200:203], v[152:155], 0
	v_mfma_f32_16x16x32_bf16 v[36:39], v[192:195], v[152:155], 0
	v_mfma_f32_16x16x32_bf16 v[20:23], v[192:195], v[160:163], 0
	v_mfma_f32_16x16x32_bf16 v[16:19], v[200:203], v[160:163], 0
	v_mfma_f32_16x16x32_bf16 v[0:3], v[200:203], v[168:171], 0
	v_mfma_f32_16x16x32_bf16 v[4:7], v[192:195], v[168:171], 0
	v_mfma_f32_16x16x32_bf16 v[52:55], v[196:199], v[148:151], v[52:55]
	v_mfma_f32_16x16x32_bf16 v[48:51], v[212:215], v[148:151], v[48:51]
	v_mfma_f32_16x16x32_bf16 v[32:35], v[212:215], v[156:159], v[32:35]
	v_mfma_f32_16x16x32_bf16 v[36:39], v[196:199], v[156:159], v[36:39]
	v_mfma_f32_16x16x32_bf16 v[20:23], v[196:199], v[164:167], v[20:23]
	v_mfma_f32_16x16x32_bf16 v[16:19], v[212:215], v[164:167], v[16:19]
	v_mfma_f32_16x16x32_bf16 v[0:3], v[212:215], v[172:175], v[0:3]
	v_mfma_f32_16x16x32_bf16 v[4:7], v[196:199], v[172:175], v[4:7]
	s_barrier
	s_add_i32 s69, 0, 0x18000
	ds_read_b128 v[128:131], v252
	ds_read_b128 v[132:135], v252 offset:1024
	ds_read_b128 v[136:139], v252 offset:2048
	ds_read_b128 v[140:143], v252 offset:3072
	s_add_u32 s44, s44, 0x40000
	s_addc_u32 s45, s45, 0
	s_mov_b32 m0, s56
	ds_read_b128 v[144:147], v209 offset:32768
	ds_read_b128 v[148:151], v209 offset:33792
	ds_read_b128 v[152:155], v209 offset:34816
	ds_read_b128 v[156:159], v209 offset:35840
	ds_read_b128 v[160:163], v209 offset:36864
	ds_read_b128 v[164:167], v209 offset:37888
	ds_read_b128 v[168:171], v209 offset:38912
	ds_read_b128 v[172:175], v209 offset:39936
	global_load_lds_dwordx4 v176, s[44:45]
	s_mov_b32 m0, s57
	s_nop 0
	global_load_lds_dwordx4 v180, s[44:45]
	s_waitcnt lgkmcnt(8)
	s_barrier
	s_waitcnt lgkmcnt(0)
	v_mfma_f32_16x16x32_bf16 v[124:127], v[128:131], v[144:147], v[124:127]
	v_mfma_f32_16x16x32_bf16 v[120:123], v[136:139], v[144:147], v[120:123]
	v_mfma_f32_16x16x32_bf16 v[104:107], v[136:139], v[152:155], v[104:107]
	v_mfma_f32_16x16x32_bf16 v[108:111], v[128:131], v[152:155], v[108:111]
	v_mfma_f32_16x16x32_bf16 v[92:95], v[128:131], v[160:163], v[92:95]
	v_mfma_f32_16x16x32_bf16 v[88:91], v[136:139], v[160:163], v[88:91]
	v_mfma_f32_16x16x32_bf16 v[72:75], v[136:139], v[168:171], v[72:75]
	v_mfma_f32_16x16x32_bf16 v[76:79], v[128:131], v[168:171], v[76:79]
	v_mfma_f32_16x16x32_bf16 v[124:127], v[132:135], v[148:151], v[124:127]
	v_mfma_f32_16x16x32_bf16 v[120:123], v[140:143], v[148:151], v[120:123]
	v_mfma_f32_16x16x32_bf16 v[104:107], v[140:143], v[156:159], v[104:107]
	v_mfma_f32_16x16x32_bf16 v[108:111], v[132:135], v[156:159], v[108:111]
	v_mfma_f32_16x16x32_bf16 v[92:95], v[132:135], v[164:167], v[92:95]
	v_mfma_f32_16x16x32_bf16 v[88:91], v[140:143], v[164:167], v[88:91]
	v_mfma_f32_16x16x32_bf16 v[72:75], v[140:143], v[172:175], v[72:75]
	v_mfma_f32_16x16x32_bf16 v[76:79], v[132:135], v[172:175], v[76:79]
	s_barrier
	s_add_i32 s44, 0, 0x1c000
	s_add_i32 s45, s69, s51
	s_mov_b32 m0, s45
	ds_read_b128 v[192:195], v253
	ds_read_b128 v[196:199], v253 offset:1024
	ds_read_b128 v[200:203], v253 offset:2048
	ds_read_b128 v[212:215], v253 offset:3072
	global_load_lds_dwordx4 v178, s[90:91]
	s_add_i32 m0, s45, 0x2000
	s_nop 0
	global_load_lds_dwordx4 v182, s[90:91]
	s_barrier
	s_waitcnt lgkmcnt(0)
	v_mfma_f32_16x16x32_bf16 v[116:119], v[192:195], v[144:147], v[116:119]
	v_mfma_f32_16x16x32_bf16 v[112:115], v[200:203], v[144:147], v[112:115]
	v_mfma_f32_16x16x32_bf16 v[96:99], v[200:203], v[152:155], v[96:99]
	v_mfma_f32_16x16x32_bf16 v[100:103], v[192:195], v[152:155], v[100:103]
	v_mfma_f32_16x16x32_bf16 v[84:87], v[192:195], v[160:163], v[84:87]
	v_mfma_f32_16x16x32_bf16 v[80:83], v[200:203], v[160:163], v[80:83]
	v_mfma_f32_16x16x32_bf16 v[64:67], v[200:203], v[168:171], v[64:67]
	v_mfma_f32_16x16x32_bf16 v[68:71], v[192:195], v[168:171], v[68:71]
	v_mfma_f32_16x16x32_bf16 v[116:119], v[196:199], v[148:151], v[116:119]
	v_mfma_f32_16x16x32_bf16 v[112:115], v[212:215], v[148:151], v[112:115]
	v_mfma_f32_16x16x32_bf16 v[96:99], v[212:215], v[156:159], v[96:99]
	v_mfma_f32_16x16x32_bf16 v[100:103], v[196:199], v[156:159], v[100:103]
	v_mfma_f32_16x16x32_bf16 v[84:87], v[196:199], v[164:167], v[84:87]
	v_mfma_f32_16x16x32_bf16 v[80:83], v[212:215], v[164:167], v[80:83]
	v_mfma_f32_16x16x32_bf16 v[64:67], v[212:215], v[172:175], v[64:67]
	v_mfma_f32_16x16x32_bf16 v[68:71], v[196:199], v[172:175], v[68:71]
	s_barrier
	s_mov_b32 m0, s63
	ds_read_b128 v[144:147], v209 offset:49152
	ds_read_b128 v[148:151], v209 offset:50176
	ds_read_b128 v[152:155], v209 offset:51200
	ds_read_b128 v[156:159], v209 offset:52224
	ds_read_b128 v[160:163], v209 offset:53248
	ds_read_b128 v[164:167], v209 offset:54272
	ds_read_b128 v[168:171], v209 offset:55296
	ds_read_b128 v[172:175], v209 offset:56320
	global_load_lds_dwordx4 v176, s[92:93]
	s_mov_b32 m0, s64
	s_nop 0
	global_load_lds_dwordx4 v180, s[92:93]
	s_barrier
	s_waitcnt lgkmcnt(0)
	v_mfma_f32_16x16x32_bf16 v[60:63], v[128:131], v[144:147], v[60:63]
	v_mfma_f32_16x16x32_bf16 v[56:59], v[136:139], v[144:147], v[56:59]
	v_mfma_f32_16x16x32_bf16 v[40:43], v[136:139], v[152:155], v[40:43]
	v_mfma_f32_16x16x32_bf16 v[44:47], v[128:131], v[152:155], v[44:47]
	v_mfma_f32_16x16x32_bf16 v[28:31], v[128:131], v[160:163], v[28:31]
	v_mfma_f32_16x16x32_bf16 v[24:27], v[136:139], v[160:163], v[24:27]
	v_mfma_f32_16x16x32_bf16 v[8:11], v[136:139], v[168:171], v[8:11]
	v_mfma_f32_16x16x32_bf16 v[12:15], v[128:131], v[168:171], v[12:15]
	v_mfma_f32_16x16x32_bf16 v[60:63], v[132:135], v[148:151], v[60:63]
	v_mfma_f32_16x16x32_bf16 v[56:59], v[140:143], v[148:151], v[56:59]
	v_mfma_f32_16x16x32_bf16 v[40:43], v[140:143], v[156:159], v[40:43]
	v_mfma_f32_16x16x32_bf16 v[44:47], v[132:135], v[156:159], v[44:47]
	v_mfma_f32_16x16x32_bf16 v[28:31], v[132:135], v[164:167], v[28:31]
	v_mfma_f32_16x16x32_bf16 v[24:27], v[140:143], v[164:167], v[24:27]
	v_mfma_f32_16x16x32_bf16 v[8:11], v[140:143], v[172:175], v[8:11]
	v_mfma_f32_16x16x32_bf16 v[12:15], v[132:135], v[172:175], v[12:15]
	s_barrier
; #define PG8_STAGE(bufoff, gbase, voff) do { _Pragma("unroll") for (int _i = 0; _i < 2; ++_i) \
;         __builtin_amdgcn_global_load_lds((const unsigned*)((const char*)(gbase) + (voff)[_i]), (LAS unsigned*)(lds + (bufoff) + ldsw + _i * 8192), 16, 0, 0); } while (0)
; #define PG8_LDA(dst, b, h) do { _Pragma("unroll") for (int m = 0; m < 4; ++m) _Pragma("unroll") for (int k = 0; k < 2; ++k) dst[m][k] = *(const LAS bf16x8*)(lds + PG8_SA(b, h) + aoff + m * 2048 + k * 1024); } while (0)
; #define PG8_LDB(dst, b, h) do { _Pragma("unroll") for (int n = 0; n < 2; ++n) _Pragma("unroll") for (int k = 0; k < 2; ++k) dst[n][k] = *(const LAS bf16x8*)(lds + PG8_SB(b, h) + boff + n * 2048 + k * 1024); } while (0)
; #define PG8_WAIT_V(n) asm volatile("s_waitcnt vmcnt(" #n ")" ::: "memory")
; #define PG8_WAIT_L(n) asm volatile("s_waitcnt lgkmcnt(" #n ")" ::: "memory")
; #define PG8_BAR __builtin_amdgcn_s_barrier()
; #define PG8_SCHED __builtin_amdgcn_sched_barrier(0)
; template <class Epi, class Ptrs>
; __device__ __forceinline__ void gemm_phase(LAS unsigned char* lds, const int K, const StaticOrder& S, const Ptrs& P, const Epi& E) {
;     ...
;         for (int t = 0; t < nt; t += 2) {
;             const bool last = (t == nt - 2);
;             const char* a1 = cA + (size_t)(t + 1) * kstep;
;             const char* a2 = last ? nA : cA + (size_t)(t + 2) * kstep; const char* b2 = last ? nB : cB + (size_t)(t + 2) * kstep;
;             const char* a3 = a2 + kstep; const char* b3 = b2 + kstep;
;             PG8_LDB(B0, 0, 0); PG8_SCHED; PG8_LDA(At, 0, 0); PG8_STAGE(PG8_SA(1, 1), a1 + hstep, voffA);
;             PG8_WAIT_L(8); PG8_BAR; PG8_WAIT_L(0); PG8_MMA(0, 0, At, B0); PG8_BAR; PG8_SCHED;
;             PG8_LDB(B1, 0, 1); PG8_STAGE(PG8_SB(0, 0), b2, voffB);
;             PG8_BAR; PG8_WAIT_L(0); PG8_MMA(0, 1, At, B1); PG8_BAR;
;             PG8_LDA(At, 0, 1); PG8_STAGE(PG8_SA(0, 0), a2, voffA);
;             PG8_BAR; PG8_WAIT_L(0); PG8_MMA(1, 0, At, B0); PG8_BAR; PG8_SCHED;
;             PG8_STAGE(PG8_SB(0, 1), b2 + hstep, voffB);
;             PG8_WAIT_V(6); PG8_BAR; PG8_MMA(1, 1, At, B1); PG8_BAR;
;             PG8_LDB(B0, 1, 0); PG8_SCHED; PG8_LDA(At, 1, 0); PG8_STAGE(PG8_SA(0, 1), a2 + hstep, voffA);
;             PG8_WAIT_L(8); PG8_BAR; PG8_WAIT_L(0); PG8_MMA(0, 0, At, B0); PG8_BAR; PG8_SCHED;
	s_add_u32 s42, s42, 0x40080
	s_addc_u32 s43, s43, 0
	s_add_i32 s44, s44, s51
	s_mov_b32 m0, s44
	s_nop 0
	global_load_lds_dwordx4 v178, s[42:43]
	s_add_i32 m0, s44, 0x2000
	s_nop 0
	global_load_lds_dwordx4 v182, s[42:43]
	s_waitcnt vmcnt(6)
	s_barrier
	v_mfma_f32_16x16x32_bf16 v[52:55], v[192:195], v[144:147], v[52:55]
	v_mfma_f32_16x16x32_bf16 v[48:51], v[200:203], v[144:147], v[48:51]
	v_mfma_f32_16x16x32_bf16 v[32:35], v[200:203], v[152:155], v[32:35]
	v_mfma_f32_16x16x32_bf16 v[36:39], v[192:195], v[152:155], v[36:39]
	v_mfma_f32_16x16x32_bf16 v[20:23], v[192:195], v[160:163], v[20:23]
	v_mfma_f32_16x16x32_bf16 v[16:19], v[200:203], v[160:163], v[16:19]
	v_mfma_f32_16x16x32_bf16 v[0:3], v[200:203], v[168:171], v[0:3]
	v_mfma_f32_16x16x32_bf16 v[4:7], v[192:195], v[168:171], v[4:7]
	v_mfma_f32_16x16x32_bf16 v[52:55], v[196:199], v[148:151], v[52:55]
	v_mfma_f32_16x16x32_bf16 v[48:51], v[212:215], v[148:151], v[48:51]
	v_mfma_f32_16x16x32_bf16 v[32:35], v[212:215], v[156:159], v[32:35]
	v_mfma_f32_16x16x32_bf16 v[36:39], v[196:199], v[156:159], v[36:39]
	v_mfma_f32_16x16x32_bf16 v[20:23], v[196:199], v[164:167], v[20:23]
	v_mfma_f32_16x16x32_bf16 v[16:19], v[212:215], v[164:167], v[16:19]
	v_mfma_f32_16x16x32_bf16 v[0:3], v[212:215], v[172:175], v[0:3]
	v_mfma_f32_16x16x32_bf16 v[4:7], v[196:199], v[172:175], v[4:7]
	s_barrier
	s_add_i32 s41, s41, 2
	s_add_u32 s38, s38, 0x100
	s_addc_u32 s39, s39, 0
	s_add_u32 s21, s21, 0x100
	s_addc_u32 s23, s23, 0
	s_cmp_gt_u32 s41, 13
.LBB0_353:
	ds_read_b128 v[128:131], v207
	ds_read_b128 v[132:135], v207 offset:1024
	ds_read_b128 v[136:139], v207 offset:2048
	ds_read_b128 v[140:143], v207 offset:3072
	s_add_u32 s42, s38, 0xfffc0080
	s_addc_u32 s43, s39, -1
	s_cmp_eq_u32 s41, 12
	s_cselect_b32 s45, s1, s43
	s_cselect_b32 s44, s0, s42
	s_cselect_b32 s43, s25, s23
	s_cselect_b32 s42, s24, s21
	s_add_i32 m0, s54, 0xc000
	ds_read_b128 v[144:147], v209
	ds_read_b128 v[148:151], v209 offset:1024
	ds_read_b128 v[152:155], v209 offset:2048
	ds_read_b128 v[156:159], v209 offset:3072
	ds_read_b128 v[160:163], v209 offset:4096
	ds_read_b128 v[164:167], v209 offset:5120
	ds_read_b128 v[168:171], v209 offset:6144
	ds_read_b128 v[172:175], v209 offset:7168
	global_load_lds_dwordx4 v184, s[38:39]
	s_add_i32 m0, s54, 0xe000
	s_nop 0
	global_load_lds_dwordx4 v186, s[38:39]
	s_waitcnt lgkmcnt(8)
	s_barrier
	s_waitcnt lgkmcnt(0)
	v_mfma_f32_16x16x32_bf16 v[124:127], v[128:131], v[144:147], v[124:127]
	v_mfma_f32_16x16x32_bf16 v[120:123], v[136:139], v[144:147], v[120:123]
	v_mfma_f32_16x16x32_bf16 v[104:107], v[136:139], v[152:155], v[104:107]
	v_mfma_f32_16x16x32_bf16 v[108:111], v[128:131], v[152:155], v[108:111]
	v_mfma_f32_16x16x32_bf16 v[92:95], v[128:131], v[160:163], v[92:95]
	v_mfma_f32_16x16x32_bf16 v[88:91], v[136:139], v[160:163], v[88:91]
	v_mfma_f32_16x16x32_bf16 v[72:75], v[136:139], v[168:171], v[72:75]
	v_mfma_f32_16x16x32_bf16 v[76:79], v[128:131], v[168:171], v[76:79]
	v_mfma_f32_16x16x32_bf16 v[124:127], v[132:135], v[148:151], v[124:127]
	v_mfma_f32_16x16x32_bf16 v[120:123], v[140:143], v[148:151], v[120:123]
	v_mfma_f32_16x16x32_bf16 v[104:107], v[140:143], v[156:159], v[104:107]
	v_mfma_f32_16x16x32_bf16 v[108:111], v[132:135], v[156:159], v[108:111]
	v_mfma_f32_16x16x32_bf16 v[92:95], v[132:135], v[164:167], v[92:95]
	v_mfma_f32_16x16x32_bf16 v[88:91], v[140:143], v[164:167], v[88:91]
	v_mfma_f32_16x16x32_bf16 v[72:75], v[140:143], v[172:175], v[72:75]
	v_mfma_f32_16x16x32_bf16 v[76:79], v[132:135], v[172:175], v[76:79]
	s_barrier
	s_add_i32 s69, s66, s51
	s_add_u32 s90, s42, 0x80
	s_addc_u32 s91, s43, 0
	s_mov_b32 m0, s69
	ds_read_b128 v[192:195], v210
	ds_read_b128 v[196:199], v210 offset:1024
	ds_read_b128 v[200:203], v210 offset:2048
	ds_read_b128 v[212:215], v210 offset:3072
	global_load_lds_dwordx4 v178, s[42:43]
	s_add_i32 m0, s69, 0x2000
	s_nop 0
	global_load_lds_dwordx4 v182, s[42:43]
	s_barrier
	s_waitcnt lgkmcnt(0)
	v_mfma_f32_16x16x32_bf16 v[116:119], v[192:195], v[144:147], v[116:119]
	v_mfma_f32_16x16x32_bf16 v[112:115], v[200:203], v[144:147], v[112:115]
	v_mfma_f32_16x16x32_bf16 v[96:99], v[200:203], v[152:155], v[96:99]
	v_mfma_f32_16x16x32_bf16 v[100:103], v[192:195], v[152:155], v[100:103]
	v_mfma_f32_16x16x32_bf16 v[84:87], v[192:195], v[160:163], v[84:87]
	v_mfma_f32_16x16x32_bf16 v[80:83], v[200:203], v[160:163], v[80:83]
	v_mfma_f32_16x16x32_bf16 v[64:67], v[200:203], v[168:171], v[64:67]
	v_mfma_f32_16x16x32_bf16 v[68:71], v[192:195], v[168:171], v[68:71]
	v_mfma_f32_16x16x32_bf16 v[116:119], v[196:199], v[148:151], v[116:119]
	v_mfma_f32_16x16x32_bf16 v[112:115], v[212:215], v[148:151], v[112:115]
	v_mfma_f32_16x16x32_bf16 v[96:99], v[212:215], v[156:159], v[96:99]
	v_mfma_f32_16x16x32_bf16 v[100:103], v[196:199], v[156:159], v[100:103]
	v_mfma_f32_16x16x32_bf16 v[84:87], v[196:199], v[164:167], v[84:87]
	v_mfma_f32_16x16x32_bf16 v[80:83], v[212:215], v[164:167], v[80:83]
	v_mfma_f32_16x16x32_bf16 v[64:67], v[212:215], v[172:175], v[64:67]
	v_mfma_f32_16x16x32_bf16 v[68:71], v[196:199], v[172:175], v[68:71]
	s_barrier
	s_mov_b32 m0, s54
	s_add_u32 s92, s44, 0x80
	s_addc_u32 s93, s45, 0
	ds_read_b128 v[144:147], v209 offset:16384
	ds_read_b128 v[148:151], v209 offset:17408
	ds_read_b128 v[152:155], v209 offset:18432
	ds_read_b128 v[156:159], v209 offset:19456
	ds_read_b128 v[160:163], v209 offset:20480
	ds_read_b128 v[164:167], v209 offset:21504
	ds_read_b128 v[168:171], v209 offset:22528
	ds_read_b128 v[172:175], v209 offset:23552
	global_load_lds_dwordx4 v176, s[44:45]
	s_mov_b32 m0, s55
	s_nop 0
	global_load_lds_dwordx4 v180, s[44:45]
	s_barrier
; #define PG8_STAGE(bufoff, gbase, voff) do { _Pragma("unroll") for (int _i = 0; _i < 2; ++_i) \
;         __builtin_amdgcn_global_load_lds((const unsigned*)((const char*)(gbase) + (voff)[_i]), (LAS unsigned*)(lds + (bufoff) + ldsw + _i * 8192), 16, 0, 0); } while (0)
; #define PG8_LDA(dst, b, h) do { _Pragma("unroll") for (int m = 0; m < 4; ++m) _Pragma("unroll") for (int k = 0; k < 2; ++k) dst[m][k] = *(const LAS bf16x8*)(lds + PG8_SA(b, h) + aoff + m * 2048 + k * 1024); } while (0)
; #define PG8_LDB(dst, b, h) do { _Pragma("unroll") for (int n = 0; n < 2; ++n) _Pragma("unroll") for (int k = 0; k < 2; ++k) dst[n][k] = *(const LAS bf16x8*)(lds + PG8_SB(b, h) + boff + n * 2048 + k * 1024); } while (0)
; #define PG8_MMA(ai, bj, At, Bt) do { __builtin_amdgcn_s_setprio(1); _Pragma("unroll") for (int m = 0; m < 4; ++m) _Pragma("unroll") for (int n = 0; n < 2; ++n) _Pragma("unroll") for (int k = 0; k < 2; ++k) \
;         acc[ai][bj][m][n] = __builtin_amdgcn_mfma_f32_16x16x32_bf16(Bt[n][k], At[m][k], acc[ai][bj][m][n], 0, 0, 0); __builtin_amdgcn_s_setprio(0); } while (0)
; #define PG8_WAIT_V(n) asm volatile("s_waitcnt vmcnt(" #n ")" ::: "memory")
; #define PG8_WAIT_L(n) asm volatile("s_waitcnt lgkmcnt(" #n ")" ::: "memory")
; #define PG8_BAR __builtin_amdgcn_s_barrier()
; #define PG8_SCHED __builtin_amdgcn_sched_barrier(0)
; template <class Epi, class Ptrs>
; __device__ __forceinline__ void gemm_phase(LAS unsigned char* lds, const int K, const StaticOrder& S, const Ptrs& P, const Epi& E) {
;     ...
;             PG8_LDA(At, 0, 1); PG8_STAGE(PG8_SA(0, 0), a2, voffA);
;             PG8_BAR; PG8_WAIT_L(0); PG8_MMA(1, 0, At, B0); PG8_BAR; PG8_SCHED;
;             PG8_STAGE(PG8_SB(0, 1), b2 + hstep, voffB);
;             PG8_WAIT_V(6); PG8_BAR; PG8_MMA(1, 1, At, B1); PG8_BAR;
;             PG8_LDB(B0, 1, 0); PG8_SCHED; PG8_LDA(At, 1, 0); PG8_STAGE(PG8_SA(0, 1), a2 + hstep, voffA);
;             PG8_WAIT_L(8); PG8_BAR; PG8_WAIT_L(0); PG8_MMA(0, 0, At, B0); PG8_BAR; PG8_SCHED;
;             PG8_LDB(B1, 1, 1); PG8_STAGE(PG8_SB(1, 0), b3, voffB);
;             PG8_BAR; PG8_WAIT_L(0); PG8_MMA(0, 1, At, B1); PG8_BAR;
;             PG8_LDA(At, 1, 1); PG8_STAGE(PG8_SA(1, 0), a3, voffA);
;             PG8_BAR; PG8_WAIT_L(0); PG8_MMA(1, 0, At, B0); PG8_BAR; PG8_SCHED;
	s_waitcnt lgkmcnt(0)
	v_mfma_f32_16x16x32_bf16 v[60:63], v[128:131], v[144:147], v[60:63]
	v_mfma_f32_16x16x32_bf16 v[56:59], v[136:139], v[144:147], v[56:59]
	v_mfma_f32_16x16x32_bf16 v[40:43], v[136:139], v[152:155], v[40:43]
	v_mfma_f32_16x16x32_bf16 v[44:47], v[128:131], v[152:155], v[44:47]
	v_mfma_f32_16x16x32_bf16 v[28:31], v[128:131], v[160:163], v[28:31]
	v_mfma_f32_16x16x32_bf16 v[24:27], v[136:139], v[160:163], v[24:27]
	v_mfma_f32_16x16x32_bf16 v[8:11], v[136:139], v[168:171], v[8:11]
	v_mfma_f32_16x16x32_bf16 v[12:15], v[128:131], v[168:171], v[12:15]
	v_mfma_f32_16x16x32_bf16 v[60:63], v[132:135], v[148:151], v[60:63]
	v_mfma_f32_16x16x32_bf16 v[56:59], v[140:143], v[148:151], v[56:59]
	v_mfma_f32_16x16x32_bf16 v[40:43], v[140:143], v[156:159], v[40:43]
	v_mfma_f32_16x16x32_bf16 v[44:47], v[132:135], v[156:159], v[44:47]
	v_mfma_f32_16x16x32_bf16 v[28:31], v[132:135], v[164:167], v[28:31]
	v_mfma_f32_16x16x32_bf16 v[24:27], v[140:143], v[164:167], v[24:27]
	v_mfma_f32_16x16x32_bf16 v[8:11], v[140:143], v[172:175], v[8:11]
	v_mfma_f32_16x16x32_bf16 v[12:15], v[132:135], v[172:175], v[12:15]
	s_barrier
	s_add_u32 s70, s42, 0x40000
	s_addc_u32 s71, s43, 0
	s_add_i32 s69, s67, s51
	s_mov_b32 m0, s69
	s_nop 0
	global_load_lds_dwordx4 v178, s[70:71]
	s_add_i32 m0, s69, 0x2000
	s_nop 0
	global_load_lds_dwordx4 v182, s[70:71]
	s_waitcnt vmcnt(6)
	s_barrier
	v_mfma_f32_16x16x32_bf16 v[52:55], v[192:195], v[144:147], v[52:55]
	v_mfma_f32_16x16x32_bf16 v[48:51], v[200:203], v[144:147], v[48:51]
	v_mfma_f32_16x16x32_bf16 v[32:35], v[200:203], v[152:155], v[32:35]
	v_mfma_f32_16x16x32_bf16 v[36:39], v[192:195], v[152:155], v[36:39]
	v_mfma_f32_16x16x32_bf16 v[20:23], v[192:195], v[160:163], v[20:23]
	v_mfma_f32_16x16x32_bf16 v[16:19], v[200:203], v[160:163], v[16:19]
	v_mfma_f32_16x16x32_bf16 v[0:3], v[200:203], v[168:171], v[0:3]
	v_mfma_f32_16x16x32_bf16 v[4:7], v[192:195], v[168:171], v[4:7]
	v_mfma_f32_16x16x32_bf16 v[52:55], v[196:199], v[148:151], v[52:55]
	v_mfma_f32_16x16x32_bf16 v[48:51], v[212:215], v[148:151], v[48:51]
	v_mfma_f32_16x16x32_bf16 v[32:35], v[212:215], v[156:159], v[32:35]
	v_mfma_f32_16x16x32_bf16 v[36:39], v[196:199], v[156:159], v[36:39]
	v_mfma_f32_16x16x32_bf16 v[20:23], v[196:199], v[164:167], v[20:23]
	v_mfma_f32_16x16x32_bf16 v[16:19], v[212:215], v[164:167], v[16:19]
	v_mfma_f32_16x16x32_bf16 v[0:3], v[212:215], v[172:175], v[0:3]
	v_mfma_f32_16x16x32_bf16 v[4:7], v[196:199], v[172:175], v[4:7]
	s_barrier
	s_add_i32 s69, 0, 0x18000
	ds_read_b128 v[128:131], v252
	ds_read_b128 v[132:135], v252 offset:1024
	ds_read_b128 v[136:139], v252 offset:2048
	ds_read_b128 v[140:143], v252 offset:3072
	s_add_u32 s44, s44, 0x40000
	s_addc_u32 s45, s45, 0
	s_mov_b32 m0, s56
	ds_read_b128 v[144:147], v209 offset:32768
	ds_read_b128 v[148:151], v209 offset:33792
	ds_read_b128 v[152:155], v209 offset:34816
	ds_read_b128 v[156:159], v209 offset:35840
	ds_read_b128 v[160:163], v209 offset:36864
	ds_read_b128 v[164:167], v209 offset:37888
	ds_read_b128 v[168:171], v209 offset:38912
	ds_read_b128 v[172:175], v209 offset:39936
	global_load_lds_dwordx4 v176, s[44:45]
	s_mov_b32 m0, s57
	s_nop 0
	global_load_lds_dwordx4 v180, s[44:45]
	s_waitcnt lgkmcnt(8)
	s_barrier
	s_waitcnt lgkmcnt(0)
	v_mfma_f32_16x16x32_bf16 v[124:127], v[128:131], v[144:147], v[124:127]
	v_mfma_f32_16x16x32_bf16 v[120:123], v[136:139], v[144:147], v[120:123]
	v_mfma_f32_16x16x32_bf16 v[104:107], v[136:139], v[152:155], v[104:107]
	v_mfma_f32_16x16x32_bf16 v[108:111], v[128:131], v[152:155], v[108:111]
	v_mfma_f32_16x16x32_bf16 v[92:95], v[128:131], v[160:163], v[92:95]
	v_mfma_f32_16x16x32_bf16 v[88:91], v[136:139], v[160:163], v[88:91]
	v_mfma_f32_16x16x32_bf16 v[72:75], v[136:139], v[168:171], v[72:75]
	v_mfma_f32_16x16x32_bf16 v[76:79], v[128:131], v[168:171], v[76:79]
	v_mfma_f32_16x16x32_bf16 v[124:127], v[132:135], v[148:151], v[124:127]
	v_mfma_f32_16x16x32_bf16 v[120:123], v[140:143], v[148:151], v[120:123]
	v_mfma_f32_16x16x32_bf16 v[104:107], v[140:143], v[156:159], v[104:107]
	v_mfma_f32_16x16x32_bf16 v[108:111], v[132:135], v[156:159], v[108:111]
	v_mfma_f32_16x16x32_bf16 v[92:95], v[132:135], v[164:167], v[92:95]
	v_mfma_f32_16x16x32_bf16 v[88:91], v[140:143], v[164:167], v[88:91]
	v_mfma_f32_16x16x32_bf16 v[72:75], v[140:143], v[172:175], v[72:75]
	v_mfma_f32_16x16x32_bf16 v[76:79], v[132:135], v[172:175], v[76:79]
	s_barrier
	s_add_i32 s44, 0, 0x1c000
	s_add_i32 s45, s69, s51
	s_mov_b32 m0, s45
	ds_read_b128 v[192:195], v253
	ds_read_b128 v[196:199], v253 offset:1024
	ds_read_b128 v[200:203], v253 offset:2048
	ds_read_b128 v[212:215], v253 offset:3072
	global_load_lds_dwordx4 v178, s[90:91]
	s_add_i32 m0, s45, 0x2000
	s_nop 0
	global_load_lds_dwordx4 v182, s[90:91]
	s_barrier
	s_waitcnt lgkmcnt(0)
	v_mfma_f32_16x16x32_bf16 v[116:119], v[192:195], v[144:147], v[116:119]
	v_mfma_f32_16x16x32_bf16 v[112:115], v[200:203], v[144:147], v[112:115]
	v_mfma_f32_16x16x32_bf16 v[96:99], v[200:203], v[152:155], v[96:99]
	v_mfma_f32_16x16x32_bf16 v[100:103], v[192:195], v[152:155], v[100:103]
	v_mfma_f32_16x16x32_bf16 v[84:87], v[192:195], v[160:163], v[84:87]
	v_mfma_f32_16x16x32_bf16 v[80:83], v[200:203], v[160:163], v[80:83]
	v_mfma_f32_16x16x32_bf16 v[64:67], v[200:203], v[168:171], v[64:67]
	v_mfma_f32_16x16x32_bf16 v[68:71], v[192:195], v[168:171], v[68:71]
	v_mfma_f32_16x16x32_bf16 v[116:119], v[196:199], v[148:151], v[116:119]
	v_mfma_f32_16x16x32_bf16 v[112:115], v[212:215], v[148:151], v[112:115]
	v_mfma_f32_16x16x32_bf16 v[96:99], v[212:215], v[156:159], v[96:99]
	v_mfma_f32_16x16x32_bf16 v[100:103], v[196:199], v[156:159], v[100:103]
	v_mfma_f32_16x16x32_bf16 v[84:87], v[196:199], v[164:167], v[84:87]
	v_mfma_f32_16x16x32_bf16 v[80:83], v[212:215], v[164:167], v[80:83]
	v_mfma_f32_16x16x32_bf16 v[64:67], v[212:215], v[172:175], v[64:67]
	v_mfma_f32_16x16x32_bf16 v[68:71], v[196:199], v[172:175], v[68:71]
	s_barrier
; #define PG8_STAGE(bufoff, gbase, voff) do { _Pragma("unroll") for (int _i = 0; _i < 2; ++_i) \
;         __builtin_amdgcn_global_load_lds((const unsigned*)((const char*)(gbase) + (voff)[_i]), (LAS unsigned*)(lds + (bufoff) + ldsw + _i * 8192), 16, 0, 0); } while (0)
; #define PG8_LDA(dst, b, h) do { _Pragma("unroll") for (int m = 0; m < 4; ++m) _Pragma("unroll") for (int k = 0; k < 2; ++k) dst[m][k] = *(const LAS bf16x8*)(lds + PG8_SA(b, h) + aoff + m * 2048 + k * 1024); } while (0)
; #define PG8_MMA(ai, bj, At, Bt) do { __builtin_amdgcn_s_setprio(1); _Pragma("unroll") for (int m = 0; m < 4; ++m) _Pragma("unroll") for (int n = 0; n < 2; ++n) _Pragma("unroll") for (int k = 0; k < 2; ++k) \
;         acc[ai][bj][m][n] = __builtin_amdgcn_mfma_f32_16x16x32_bf16(Bt[n][k], At[m][k], acc[ai][bj][m][n], 0, 0, 0); __builtin_amdgcn_s_setprio(0); } while (0)
; #define PG8_WAIT_V(n) asm volatile("s_waitcnt vmcnt(" #n ")" ::: "memory")
; #define PG8_WAIT_L(n) asm volatile("s_waitcnt lgkmcnt(" #n ")" ::: "memory")
; #define PG8_BAR __builtin_amdgcn_s_barrier()
; #define PG8_SCHED __builtin_amdgcn_sched_barrier(0)
; template <class Epi, class Ptrs>
; __device__ __forceinline__ void gemm_phase(LAS unsigned char* lds, const int K, const StaticOrder& S, const Ptrs& P, const Epi& E) {
;     ...
;             PG8_LDA(At, 1, 1); PG8_STAGE(PG8_SA(1, 0), a3, voffA);
;             PG8_BAR; PG8_WAIT_L(0); PG8_MMA(1, 0, At, B0); PG8_BAR; PG8_SCHED;
;             PG8_STAGE(PG8_SB(1, 1), b3 + hstep, voffB);
;             PG8_WAIT_V(6); PG8_BAR; PG8_MMA(1, 1, At, B1); PG8_BAR;
;         }
	s_mov_b32 m0, s63
	ds_read_b128 v[144:147], v209 offset:49152
	ds_read_b128 v[148:151], v209 offset:50176
	ds_read_b128 v[152:155], v209 offset:51200
	ds_read_b128 v[156:159], v209 offset:52224
	ds_read_b128 v[160:163], v209 offset:53248
	ds_read_b128 v[164:167], v209 offset:54272
	ds_read_b128 v[168:171], v209 offset:55296
	ds_read_b128 v[172:175], v209 offset:56320
	global_load_lds_dwordx4 v176, s[92:93]
	s_mov_b32 m0, s64
	s_nop 0
	global_load_lds_dwordx4 v180, s[92:93]
	s_barrier
	s_waitcnt lgkmcnt(0)
	v_mfma_f32_16x16x32_bf16 v[60:63], v[128:131], v[144:147], v[60:63]
	v_mfma_f32_16x16x32_bf16 v[56:59], v[136:139], v[144:147], v[56:59]
	v_mfma_f32_16x16x32_bf16 v[40:43], v[136:139], v[152:155], v[40:43]
	v_mfma_f32_16x16x32_bf16 v[44:47], v[128:131], v[152:155], v[44:47]
	v_mfma_f32_16x16x32_bf16 v[28:31], v[128:131], v[160:163], v[28:31]
	v_mfma_f32_16x16x32_bf16 v[24:27], v[136:139], v[160:163], v[24:27]
	v_mfma_f32_16x16x32_bf16 v[8:11], v[136:139], v[168:171], v[8:11]
	v_mfma_f32_16x16x32_bf16 v[12:15], v[128:131], v[168:171], v[12:15]
	v_mfma_f32_16x16x32_bf16 v[60:63], v[132:135], v[148:151], v[60:63]
	v_mfma_f32_16x16x32_bf16 v[56:59], v[140:143], v[148:151], v[56:59]
	v_mfma_f32_16x16x32_bf16 v[40:43], v[140:143], v[156:159], v[40:43]
	v_mfma_f32_16x16x32_bf16 v[44:47], v[132:135], v[156:159], v[44:47]
	v_mfma_f32_16x16x32_bf16 v[28:31], v[132:135], v[164:167], v[28:31]
	v_mfma_f32_16x16x32_bf16 v[24:27], v[140:143], v[164:167], v[24:27]
	v_mfma_f32_16x16x32_bf16 v[8:11], v[140:143], v[172:175], v[8:11]
	v_mfma_f32_16x16x32_bf16 v[12:15], v[132:135], v[172:175], v[12:15]
	s_barrier
	s_add_u32 s42, s42, 0x40080
	s_addc_u32 s43, s43, 0
	s_add_i32 s44, s44, s51
	s_mov_b32 m0, s44
	s_nop 0
	global_load_lds_dwordx4 v178, s[42:43]
	s_add_i32 m0, s44, 0x2000
	s_nop 0
	global_load_lds_dwordx4 v182, s[42:43]
	s_waitcnt vmcnt(6)
	s_barrier
	v_mfma_f32_16x16x32_bf16 v[52:55], v[192:195], v[144:147], v[52:55]
	v_mfma_f32_16x16x32_bf16 v[48:51], v[200:203], v[144:147], v[48:51]
	v_mfma_f32_16x16x32_bf16 v[32:35], v[200:203], v[152:155], v[32:35]
	v_mfma_f32_16x16x32_bf16 v[36:39], v[192:195], v[152:155], v[36:39]
	v_mfma_f32_16x16x32_bf16 v[20:23], v[192:195], v[160:163], v[20:23]
	v_mfma_f32_16x16x32_bf16 v[16:19], v[200:203], v[160:163], v[16:19]
	v_mfma_f32_16x16x32_bf16 v[0:3], v[200:203], v[168:171], v[0:3]
	v_mfma_f32_16x16x32_bf16 v[4:7], v[192:195], v[168:171], v[4:7]
	v_mfma_f32_16x16x32_bf16 v[52:55], v[196:199], v[148:151], v[52:55]
	v_mfma_f32_16x16x32_bf16 v[48:51], v[212:215], v[148:151], v[48:51]
	v_mfma_f32_16x16x32_bf16 v[32:35], v[212:215], v[156:159], v[32:35]
	v_mfma_f32_16x16x32_bf16 v[36:39], v[196:199], v[156:159], v[36:39]
	v_mfma_f32_16x16x32_bf16 v[20:23], v[196:199], v[164:167], v[20:23]
	v_mfma_f32_16x16x32_bf16 v[16:19], v[212:215], v[164:167], v[16:19]
	v_mfma_f32_16x16x32_bf16 v[0:3], v[212:215], v[172:175], v[0:3]
	v_mfma_f32_16x16x32_bf16 v[4:7], v[196:199], v[172:175], v[4:7]
	s_barrier
	s_add_i32 s41, s41, 2
	s_add_u32 s38, s38, 0x100
	s_addc_u32 s39, s39, 0
	s_add_u32 s21, s21, 0x100
	s_addc_u32 s23, s23, 0
	s_cmp_gt_u32 s41, 13
	s_cbranch_scc0 .LBB0_353
; __device__ __forceinline__ unsigned cvt_pk_bf16(float lo, float hi) { unsigned r; asm volatile("v_cvt_pk_bf16_f32 %0, %1, %2" : "=v"(r) : "v"(lo), "v"(hi)); return r; }
; __device__ __forceinline__ float x16_sum(float x) { auto s = __builtin_amdgcn_permlane16_swap(__float_as_uint(x), __float_as_uint(x), false, false); return __uint_as_float(s[0]) + __uint_as_float(s[1]); }
; __device__ __forceinline__ float x32_sum(float x) { auto s = __builtin_amdgcn_permlane32_swap(__float_as_uint(x), __float_as_uint(x), false, false); return __uint_as_float(s[0]) + __uint_as_float(s[1]); }
;     __device__ __forceinline__ void operator()(const f32x4 (&acc)[2][2][4][2], const Unit& u, int ui, int wr, int wc, int fr, int fq) const {
;         const int row0 = u.pm * 256 + wr * 64 + fr, col0 = u.pn * 256 + wc * 32 + 8 * fq;
;         const float* xb0 = (u.pm * 256 < MP) ? xp : xs - (size_t)MP * DM;
; #pragma unroll
;         for (int ai = 0; ai < 2; ++ai) {
;             f32x4 xv[4][2][2];
; #pragma unroll
;             for (int m = 0; m < 4; ++m)
; #pragma unroll
;                 for (int bj = 0; bj < 2; ++bj) { const float* p = xb0 + (size_t)(row0 + ai * 128 + m * 16) * DM + col0 + bj * 128; xv[m][bj][0] = *(const f32x4*)p; xv[m][bj][1] = *(const f32x4*)(p + 4); }
; #pragma unroll
;             for (int m = 0; m < 4; ++m) { const int row = row0 + ai * 128 + m * 16; const size_t off = (size_t)row * DM + col0; float ss = 0.f;
; #pragma unroll
;                 for (int bj = 0; bj < 2; ++bj) {
;                     const f32x4 v0 = acc[ai][bj][m][0] + xv[m][bj][0], v1 = acc[ai][bj][m][1] + xv[m][bj][1];
;                     u32x4 w; w.x = cvt_pk_bf16(v0[0], v0[1]); w.y = cvt_pk_bf16(v0[2], v0[3]); w.z = cvt_pk_bf16(v1[0], v1[1]); w.w = cvt_pk_bf16(v1[2], v1[3]);
;                     *(u32x4*)(xb + off + bj * 128) = w;
;                     ss += (v0[0] * v0[0] + v0[1] * v0[1]) + (v0[2] * v0[2] + v0[3] * v0[3]) + (v1[0] * v1[0] + v1[1] * v1[1]) + (v1[2] * v1[2] + v1[3] * v1[3]); }
;                 ss = x32_sum(x16_sum(ss));
;                 if (fq == 0) part[(size_t)row * 16 + u.pn * 4 + wc] = ss; }
	s_cmpk_lt_i32 s40, 0x80
	v_lshl_add_u32 v194, s40, 8, v204
	v_lshl_or_b32 v192, s12, 8, v206
	s_cselect_b32 s21, s37, s61
	s_cselect_b32 s23, s36, s60
	v_mov_b32_e32 v128, s23
	v_mov_b32_e32 v129, s21
	v_ashrrev_i32_e32 v193, 31, v192
	v_ashrrev_i32_e32 v195, 31, v194
	v_lshl_add_u64 v[196:197], v[192:193], 2, v[128:129]
	v_lshlrev_b64 v[128:129], 12, v[194:195]
	v_or_b32_e32 v202, 16, v194
	v_or_b32_e32 v200, 32, v194
	v_or_b32_e32 v198, 48, v194
	v_lshl_add_u64 v[128:129], v[196:197], 0, v[128:129]
	v_ashrrev_i32_e32 v203, 31, v202
	v_ashrrev_i32_e32 v201, 31, v200
	v_ashrrev_i32_e32 v199, 31, v198
	global_load_dwordx4 v[212:215], v[128:129], off
	global_load_dwordx4 v[216:219], v[128:129], off offset:16
	global_load_dwordx4 v[220:223], v[128:129], off offset:512
	global_load_dwordx4 v[224:227], v[128:129], off offset:528
	v_lshlrev_b64 v[128:129], 12, v[202:203]
	v_lshlrev_b64 v[130:131], 12, v[200:201]
	v_lshlrev_b64 v[132:133], 12, v[198:199]
	v_lshl_add_u64 v[128:129], v[196:197], 0, v[128:129]
	v_lshl_add_u64 v[130:131], v[196:197], 0, v[130:131]
	v_lshl_add_u64 v[132:133], v[196:197], 0, v[132:133]
	global_load_dwordx4 v[168:171], v[128:129], off offset:16
	global_load_dwordx4 v[172:175], v[128:129], off
	global_load_dwordx4 v[160:163], v[128:129], off offset:528
	global_load_dwordx4 v[164:167], v[128:129], off offset:512
	global_load_dwordx4 v[152:155], v[130:131], off offset:16
	global_load_dwordx4 v[156:159], v[130:131], off
	global_load_dwordx4 v[144:147], v[130:131], off offset:528
	global_load_dwordx4 v[148:151], v[130:131], off offset:512
	global_load_dwordx4 v[136:139], v[132:133], off offset:16
	global_load_dwordx4 v[140:143], v[132:133], off
	s_nop 0
	global_load_dwordx4 v[128:131], v[132:133], off offset:528
	s_nop 0
	global_load_dwordx4 v[132:135], v[132:133], off offset:512
	v_lshlrev_b64 v[228:229], 11, v[194:195]
	v_lshl_add_u64 v[228:229], s[14:15], 0, v[228:229]
	v_lshl_add_u64 v[228:229], v[192:193], 1, v[228:229]
	s_lshl_b32 s38, s12, 2
	s_ashr_i32 s39, s38, 31
	s_waitcnt vmcnt(0)
	v_pk_add_f32 v[126:127], v[126:127], v[214:215]
	v_pk_add_f32 v[124:125], v[124:125], v[212:213]
	v_pk_add_f32 v[118:119], v[118:119], v[222:223]
	v_pk_add_f32 v[116:117], v[116:117], v[220:221]
	v_pk_add_f32 v[120:121], v[120:121], v[216:217]
	v_pk_add_f32 v[214:215], v[112:113], v[224:225]
	v_cvt_pk_bf16_f32 v112, v124, v125
	v_cvt_pk_bf16_f32 v113, v126, v127
	v_mul_f32_e32 v125, v125, v125
	v_mul_f32_e32 v127, v127, v127
	v_mul_f32_e32 v211, v117, v117
	v_mul_f32_e32 v216, v119, v119
	v_pk_add_f32 v[122:123], v[122:123], v[218:219]
	v_pk_add_f32 v[212:213], v[114:115], v[226:227]
	v_cvt_pk_bf16_f32 v114, v120, v121
	v_cvt_pk_bf16_f32 v115, v122, v123
	v_mul_f32_e32 v121, v121, v121
	v_mul_f32_e32 v217, v215, v215
	global_store_dwordx4 v[228:229], v[112:115], off
	v_fmac_f32_e32 v125, v124, v124
	v_fmac_f32_e32 v127, v126, v126
	v_cvt_pk_bf16_f32 v112, v116, v117
	v_fmac_f32_e32 v211, v116, v116
	v_fmac_f32_e32 v216, v118, v118
	v_mul_f32_e32 v123, v123, v123
	v_mul_f32_e32 v218, v213, v213
	v_fmac_f32_e32 v121, v120, v120
	v_cvt_pk_bf16_f32 v113, v118, v119
	v_cvt_pk_bf16_f32 v114, v214, v215
	v_cvt_pk_bf16_f32 v115, v212, v213
	v_fmac_f32_e32 v217, v214, v214
	v_add_f32_e32 v116, v125, v127
	global_store_dwordx4 v[228:229], v[112:115], off offset:256
	v_fmac_f32_e32 v123, v122, v122
	v_fmac_f32_e32 v218, v212, v212
	v_add_f32_e32 v112, v211, v216
	v_add_f32_e32 v113, v116, v121
	v_add_f32_e32 v112, v112, v217
	v_add_f32_e32 v113, v123, v113
	v_add_f32_e32 v112, v218, v112
	v_add_f32_e32 v112, v113, v112
	v_mov_b32_e32 v113, v112
	s_nop 1
	v_permlane16_swap_b32_e32 v112, v113
	v_add_f32_e32 v112, v112, v113
	v_mov_b32_e32 v113, v112
	s_nop 1
	v_permlane32_swap_b32_e32 v112, v113
	s_and_saveexec_b64 s[40:41], s[6:7]
	s_cbranch_execz .LBB0_356
	v_lshlrev_b64 v[114:115], 6, v[194:195]
	v_lshl_add_u64 v[114:115], s[16:17], 0, v[114:115]
	v_lshl_add_u64 v[114:115], s[38:39], 2, v[114:115]
	s_lshl_b32 s12, s62, 2
	v_lshl_add_u64 v[114:115], v[114:115], 0, s[12:13]
	v_add_f32_e32 v112, v112, v113
	global_store_dword v[114:115], v112, off

; #define PG8_STAGE(bufoff, gbase, voff) do { _Pragma("unroll") for (int _i = 0; _i < 2; ++_i) \
;         __builtin_amdgcn_global_load_lds((const unsigned*)((const char*)(gbase) + (voff)[_i]), (LAS unsigned*)(lds + (bufoff) + ldsw + _i * 8192), 16, 0, 0); } while (0)
; #define PG8_LDA(dst, b, h) do { _Pragma("unroll") for (int m = 0; m < 4; ++m) _Pragma("unroll") for (int k = 0; k < 2; ++k) dst[m][k] = *(const LAS bf16x8*)(lds + PG8_SA(b, h) + aoff + m * 2048 + k * 1024); } while (0)
; #define PG8_LDB(dst, b, h) do { _Pragma("unroll") for (int n = 0; n < 2; ++n) _Pragma("unroll") for (int k = 0; k < 2; ++k) dst[n][k] = *(const LAS bf16x8*)(lds + PG8_SB(b, h) + boff + n * 2048 + k * 1024); } while (0)
; #define PG8_WAIT_V(n) asm volatile("s_waitcnt vmcnt(" #n ")" ::: "memory")
; #define PG8_WAIT_L(n) asm volatile("s_waitcnt lgkmcnt(" #n ")" ::: "memory")
; #define PG8_BAR __builtin_amdgcn_s_barrier()
; template <class Epi, class Ptrs>
; __device__ __forceinline__ void gemm_phase(LAS unsigned char* lds, const int K, const StaticOrder& S, const Ptrs& P, const Epi& E) {
;     ...
;         const char* nA = cA; const char* nB = cB; if (has_next) P.get(nxt, nA, nB);
;         for (int t = 0; t < nt; t += 2) {
;             const bool last = (t == nt - 2);
;             const char* a1 = cA + (size_t)(t + 1) * kstep;
;             const char* a2 = last ? nA : cA + (size_t)(t + 2) * kstep; const char* b2 = last ? nB : cB + (size_t)(t + 2) * kstep;
;             const char* a3 = a2 + kstep; const char* b3 = b2 + kstep;
;             PG8_LDB(B0, 0, 0); PG8_SCHED; PG8_LDA(At, 0, 0); PG8_STAGE(PG8_SA(1, 1), a1 + hstep, voffA);
;             PG8_WAIT_L(8); PG8_BAR; PG8_WAIT_L(0); PG8_MMA(0, 0, At, B0); PG8_BAR; PG8_SCHED;
;             PG8_LDB(B1, 0, 1); PG8_STAGE(PG8_SB(0, 0), b2, voffB);
;             PG8_BAR; PG8_WAIT_L(0); PG8_MMA(0, 1, At, B1); PG8_BAR;
;             PG8_LDA(At, 0, 1); PG8_STAGE(PG8_SA(0, 0), a2, voffA);
;             PG8_BAR; PG8_WAIT_L(0); PG8_MMA(1, 0, At, B0); PG8_BAR; PG8_SCHED;
;             PG8_STAGE(PG8_SB(0, 1), b2 + hstep, voffB);
;             PG8_WAIT_V(6); PG8_BAR; PG8_MMA(1, 1, At, B1); PG8_BAR;
;             PG8_LDB(B0, 1, 0); PG8_SCHED; PG8_LDA(At, 1, 0); PG8_STAGE(PG8_SA(0, 1), a2 + hstep, voffA);
;             PG8_WAIT_L(8); PG8_BAR; PG8_WAIT_L(0); PG8_MMA(0, 0, At, B0); PG8_BAR; PG8_SCHED;
.LBB0_432:
	s_add_u32 s40, s40, 0x40080
	s_addc_u32 s41, s41, 0
	s_add_u32 s23, s42, 0x100
	s_addc_u32 s25, s43, 0
	s_mov_b32 s70, -2
	v_add_u32_e32 v252, 0x18000, v147
	v_add_u32_e32 v253, 0x1c000, v147
	ds_read_b128 v[152:155], v149
	ds_read_b128 v[156:159], v149 offset:1024
	ds_read_b128 v[160:163], v149 offset:2048
	ds_read_b128 v[164:167], v149 offset:3072
	s_add_u32 s42, s40, 0xfffc0080
	s_addc_u32 s43, s41, -1
	s_cmp_eq_u32 s70, 12
	s_cselect_b32 s45, s1, s43
	s_cselect_b32 s44, s0, s42
	s_cselect_b32 s43, s37, s25
	s_cselect_b32 s42, s36, s23
	s_add_i32 m0, s39, 0xc000
	ds_read_b128 v[168:171], v150
	ds_read_b128 v[172:175], v150 offset:1024
	ds_read_b128 v[176:179], v150 offset:2048
	ds_read_b128 v[180:183], v150 offset:3072
	ds_read_b128 v[184:187], v150 offset:4096
	ds_read_b128 v[188:191], v150 offset:5120
	ds_read_b128 v[192:195], v150 offset:6144
	ds_read_b128 v[196:199], v150 offset:7168
	global_load_lds_dwordx4 v136, s[40:41]
	s_add_i32 m0, s39, 0xe000
	s_nop 0
	global_load_lds_dwordx4 v138, s[40:41]
	s_waitcnt lgkmcnt(8)
	s_barrier
	s_waitcnt lgkmcnt(0)
	v_mfma_f32_16x16x32_bf16 v[124:127], v[152:155], v[168:171], 0
	v_mfma_f32_16x16x32_bf16 v[120:123], v[160:163], v[168:171], 0
	v_mfma_f32_16x16x32_bf16 v[104:107], v[160:163], v[176:179], 0
	v_mfma_f32_16x16x32_bf16 v[108:111], v[152:155], v[176:179], 0
	v_mfma_f32_16x16x32_bf16 v[92:95], v[152:155], v[184:187], 0
	v_mfma_f32_16x16x32_bf16 v[88:91], v[160:163], v[184:187], 0
	v_mfma_f32_16x16x32_bf16 v[72:75], v[160:163], v[192:195], 0
	v_mfma_f32_16x16x32_bf16 v[76:79], v[152:155], v[192:195], 0
	v_mfma_f32_16x16x32_bf16 v[124:127], v[156:159], v[172:175], v[124:127]
	v_mfma_f32_16x16x32_bf16 v[120:123], v[164:167], v[172:175], v[120:123]
	v_mfma_f32_16x16x32_bf16 v[104:107], v[164:167], v[180:183], v[104:107]
	v_mfma_f32_16x16x32_bf16 v[108:111], v[156:159], v[180:183], v[108:111]
	v_mfma_f32_16x16x32_bf16 v[92:95], v[156:159], v[188:191], v[92:95]
	v_mfma_f32_16x16x32_bf16 v[88:91], v[164:167], v[188:191], v[88:91]
	v_mfma_f32_16x16x32_bf16 v[72:75], v[164:167], v[196:199], v[72:75]
	v_mfma_f32_16x16x32_bf16 v[76:79], v[156:159], v[196:199], v[76:79]
	s_barrier
	s_add_i32 s71, s63, s51
	s_add_u32 s76, s42, 0x80
	s_addc_u32 s77, s43, 0
	s_mov_b32 m0, s71
	ds_read_b128 v[200:203], v151
	ds_read_b128 v[204:207], v151 offset:1024
	ds_read_b128 v[210:213], v151 offset:2048
	ds_read_b128 v[214:217], v151 offset:3072
	global_load_lds_dwordx4 v130, s[42:43]
	s_add_i32 m0, s71, 0x2000
	s_nop 0
	global_load_lds_dwordx4 v134, s[42:43]
	s_barrier
	s_waitcnt lgkmcnt(0)
	v_mfma_f32_16x16x32_bf16 v[116:119], v[200:203], v[168:171], 0
	v_mfma_f32_16x16x32_bf16 v[112:115], v[210:213], v[168:171], 0
	v_mfma_f32_16x16x32_bf16 v[96:99], v[210:213], v[176:179], 0
	v_mfma_f32_16x16x32_bf16 v[100:103], v[200:203], v[176:179], 0
	v_mfma_f32_16x16x32_bf16 v[84:87], v[200:203], v[184:187], 0
	v_mfma_f32_16x16x32_bf16 v[80:83], v[210:213], v[184:187], 0
	v_mfma_f32_16x16x32_bf16 v[64:67], v[210:213], v[192:195], 0
	v_mfma_f32_16x16x32_bf16 v[68:71], v[200:203], v[192:195], 0
	v_mfma_f32_16x16x32_bf16 v[116:119], v[204:207], v[172:175], v[116:119]
	v_mfma_f32_16x16x32_bf16 v[112:115], v[214:217], v[172:175], v[112:115]
	v_mfma_f32_16x16x32_bf16 v[96:99], v[214:217], v[180:183], v[96:99]
	v_mfma_f32_16x16x32_bf16 v[100:103], v[204:207], v[180:183], v[100:103]
	v_mfma_f32_16x16x32_bf16 v[84:87], v[204:207], v[188:191], v[84:87]
	v_mfma_f32_16x16x32_bf16 v[80:83], v[214:217], v[188:191], v[80:83]
	v_mfma_f32_16x16x32_bf16 v[64:67], v[214:217], v[196:199], v[64:67]
	v_mfma_f32_16x16x32_bf16 v[68:71], v[204:207], v[196:199], v[68:71]
	s_barrier
	s_mov_b32 m0, s39
	s_add_u32 s78, s44, 0x80
	s_addc_u32 s79, s45, 0
	ds_read_b128 v[168:171], v150 offset:16384
	ds_read_b128 v[172:175], v150 offset:17408
	ds_read_b128 v[176:179], v150 offset:18432
	ds_read_b128 v[180:183], v150 offset:19456
	ds_read_b128 v[184:187], v150 offset:20480
	ds_read_b128 v[188:191], v150 offset:21504
	ds_read_b128 v[192:195], v150 offset:22528
	ds_read_b128 v[196:199], v150 offset:23552
	global_load_lds_dwordx4 v128, s[44:45]
	s_mov_b32 m0, s56
	s_nop 0
	global_load_lds_dwordx4 v132, s[44:45]
	s_barrier
	s_waitcnt lgkmcnt(0)
	v_mfma_f32_16x16x32_bf16 v[60:63], v[152:155], v[168:171], 0
	v_mfma_f32_16x16x32_bf16 v[56:59], v[160:163], v[168:171], 0
	v_mfma_f32_16x16x32_bf16 v[40:43], v[160:163], v[176:179], 0
	v_mfma_f32_16x16x32_bf16 v[44:47], v[152:155], v[176:179], 0
	v_mfma_f32_16x16x32_bf16 v[28:31], v[152:155], v[184:187], 0
	v_mfma_f32_16x16x32_bf16 v[24:27], v[160:163], v[184:187], 0
	v_mfma_f32_16x16x32_bf16 v[8:11], v[160:163], v[192:195], 0
	v_mfma_f32_16x16x32_bf16 v[12:15], v[152:155], v[192:195], 0
	v_mfma_f32_16x16x32_bf16 v[60:63], v[156:159], v[172:175], v[60:63]
	v_mfma_f32_16x16x32_bf16 v[56:59], v[164:167], v[172:175], v[56:59]
	v_mfma_f32_16x16x32_bf16 v[40:43], v[164:167], v[180:183], v[40:43]
	v_mfma_f32_16x16x32_bf16 v[44:47], v[156:159], v[180:183], v[44:47]
	v_mfma_f32_16x16x32_bf16 v[28:31], v[156:159], v[188:191], v[28:31]
	v_mfma_f32_16x16x32_bf16 v[24:27], v[164:167], v[188:191], v[24:27]
	v_mfma_f32_16x16x32_bf16 v[8:11], v[164:167], v[196:199], v[8:11]
	v_mfma_f32_16x16x32_bf16 v[12:15], v[156:159], v[196:199], v[12:15]
	s_barrier
	s_add_u32 s72, s42, 0x40000
	s_addc_u32 s73, s43, 0
	s_add_i32 s71, s64, s51
	s_mov_b32 m0, s71
	s_nop 0
	global_load_lds_dwordx4 v130, s[72:73]
	s_add_i32 m0, s71, 0x2000
	s_nop 0
	global_load_lds_dwordx4 v134, s[72:73]
	s_waitcnt vmcnt(6)
	s_barrier
; #define PG8_STAGE(bufoff, gbase, voff) do { _Pragma("unroll") for (int _i = 0; _i < 2; ++_i) \
;         __builtin_amdgcn_global_load_lds((const unsigned*)((const char*)(gbase) + (voff)[_i]), (LAS unsigned*)(lds + (bufoff) + ldsw + _i * 8192), 16, 0, 0); } while (0)
; #define PG8_LDA(dst, b, h) do { _Pragma("unroll") for (int m = 0; m < 4; ++m) _Pragma("unroll") for (int k = 0; k < 2; ++k) dst[m][k] = *(const LAS bf16x8*)(lds + PG8_SA(b, h) + aoff + m * 2048 + k * 1024); } while (0)
; #define PG8_LDB(dst, b, h) do { _Pragma("unroll") for (int n = 0; n < 2; ++n) _Pragma("unroll") for (int k = 0; k < 2; ++k) dst[n][k] = *(const LAS bf16x8*)(lds + PG8_SB(b, h) + boff + n * 2048 + k * 1024); } while (0)
; #define PG8_WAIT_V(n) asm volatile("s_waitcnt vmcnt(" #n ")" ::: "memory")
; #define PG8_WAIT_L(n) asm volatile("s_waitcnt lgkmcnt(" #n ")" ::: "memory")
; #define PG8_BAR __builtin_amdgcn_s_barrier()
; #define PG8_SCHED __builtin_amdgcn_sched_barrier(0)
; template <class Epi, class Ptrs>
; __device__ __forceinline__ void gemm_phase(LAS unsigned char* lds, const int K, const StaticOrder& S, const Ptrs& P, const Epi& E) {
;     ...
;             PG8_LDB(B0, 0, 0); PG8_SCHED; PG8_LDA(At, 0, 0); PG8_STAGE(PG8_SA(1, 1), a1 + hstep, voffA);
;             PG8_WAIT_L(8); PG8_BAR; PG8_WAIT_L(0); PG8_MMA(0, 0, At, B0); PG8_BAR; PG8_SCHED;
;             PG8_LDB(B1, 0, 1); PG8_STAGE(PG8_SB(0, 0), b2, voffB);
;             PG8_BAR; PG8_WAIT_L(0); PG8_MMA(0, 1, At, B1); PG8_BAR;
;             PG8_LDA(At, 0, 1); PG8_STAGE(PG8_SA(0, 0), a2, voffA);
;             PG8_BAR; PG8_WAIT_L(0); PG8_MMA(1, 0, At, B0); PG8_BAR; PG8_SCHED;
;             PG8_STAGE(PG8_SB(0, 1), b2 + hstep, voffB);
;             PG8_WAIT_V(6); PG8_BAR; PG8_MMA(1, 1, At, B1); PG8_BAR;
;             PG8_LDB(B0, 1, 0); PG8_SCHED; PG8_LDA(At, 1, 0); PG8_STAGE(PG8_SA(0, 1), a2 + hstep, voffA);
;             PG8_WAIT_L(8); PG8_BAR; PG8_WAIT_L(0); PG8_MMA(0, 0, At, B0); PG8_BAR; PG8_SCHED;
;             PG8_LDB(B1, 1, 1); PG8_STAGE(PG8_SB(1, 0), b3, voffB);
;             PG8_BAR; PG8_WAIT_L(0); PG8_MMA(0, 1, At, B1); PG8_BAR;
;             PG8_LDA(At, 1, 1); PG8_STAGE(PG8_SA(1, 0), a3, voffA);
;             PG8_BAR; PG8_WAIT_L(0); PG8_MMA(1, 0, At, B0); PG8_BAR; PG8_SCHED;
;             PG8_STAGE(PG8_SB(1, 1), b3 + hstep, voffB);
;             PG8_WAIT_V(6); PG8_BAR; PG8_MMA(1, 1, At, B1); PG8_BAR;
	v_mfma_f32_16x16x32_bf16 v[52:55], v[200:203], v[168:171], 0
	v_mfma_f32_16x16x32_bf16 v[48:51], v[210:213], v[168:171], 0
	v_mfma_f32_16x16x32_bf16 v[32:35], v[210:213], v[176:179], 0
	v_mfma_f32_16x16x32_bf16 v[36:39], v[200:203], v[176:179], 0
	v_mfma_f32_16x16x32_bf16 v[20:23], v[200:203], v[184:187], 0
	v_mfma_f32_16x16x32_bf16 v[16:19], v[210:213], v[184:187], 0
	v_mfma_f32_16x16x32_bf16 v[0:3], v[210:213], v[192:195], 0
	v_mfma_f32_16x16x32_bf16 v[4:7], v[200:203], v[192:195], 0
	v_mfma_f32_16x16x32_bf16 v[52:55], v[204:207], v[172:175], v[52:55]
	v_mfma_f32_16x16x32_bf16 v[48:51], v[214:217], v[172:175], v[48:51]
	v_mfma_f32_16x16x32_bf16 v[32:35], v[214:217], v[180:183], v[32:35]
	v_mfma_f32_16x16x32_bf16 v[36:39], v[204:207], v[180:183], v[36:39]
	v_mfma_f32_16x16x32_bf16 v[20:23], v[204:207], v[188:191], v[20:23]
	v_mfma_f32_16x16x32_bf16 v[16:19], v[214:217], v[188:191], v[16:19]
	v_mfma_f32_16x16x32_bf16 v[0:3], v[214:217], v[196:199], v[0:3]
	v_mfma_f32_16x16x32_bf16 v[4:7], v[204:207], v[196:199], v[4:7]
	s_barrier
	s_add_i32 s71, 0, 0x18000
	ds_read_b128 v[152:155], v252
	ds_read_b128 v[156:159], v252 offset:1024
	ds_read_b128 v[160:163], v252 offset:2048
	ds_read_b128 v[164:167], v252 offset:3072
	s_add_u32 s44, s44, 0x40000
	s_addc_u32 s45, s45, 0
	s_mov_b32 m0, s57
	ds_read_b128 v[168:171], v150 offset:32768
	ds_read_b128 v[172:175], v150 offset:33792
	ds_read_b128 v[176:179], v150 offset:34816
	ds_read_b128 v[180:183], v150 offset:35840
	ds_read_b128 v[184:187], v150 offset:36864
	ds_read_b128 v[188:191], v150 offset:37888
	ds_read_b128 v[192:195], v150 offset:38912
	ds_read_b128 v[196:199], v150 offset:39936
	global_load_lds_dwordx4 v128, s[44:45]
	s_mov_b32 m0, s58
	s_nop 0
	global_load_lds_dwordx4 v132, s[44:45]
	s_waitcnt lgkmcnt(8)
	s_barrier
	s_waitcnt lgkmcnt(0)
	v_mfma_f32_16x16x32_bf16 v[124:127], v[152:155], v[168:171], v[124:127]
	v_mfma_f32_16x16x32_bf16 v[120:123], v[160:163], v[168:171], v[120:123]
	v_mfma_f32_16x16x32_bf16 v[104:107], v[160:163], v[176:179], v[104:107]
	v_mfma_f32_16x16x32_bf16 v[108:111], v[152:155], v[176:179], v[108:111]
	v_mfma_f32_16x16x32_bf16 v[92:95], v[152:155], v[184:187], v[92:95]
	v_mfma_f32_16x16x32_bf16 v[88:91], v[160:163], v[184:187], v[88:91]
	v_mfma_f32_16x16x32_bf16 v[72:75], v[160:163], v[192:195], v[72:75]
	v_mfma_f32_16x16x32_bf16 v[76:79], v[152:155], v[192:195], v[76:79]
	v_mfma_f32_16x16x32_bf16 v[124:127], v[156:159], v[172:175], v[124:127]
	v_mfma_f32_16x16x32_bf16 v[120:123], v[164:167], v[172:175], v[120:123]
	v_mfma_f32_16x16x32_bf16 v[104:107], v[164:167], v[180:183], v[104:107]
	v_mfma_f32_16x16x32_bf16 v[108:111], v[156:159], v[180:183], v[108:111]
	v_mfma_f32_16x16x32_bf16 v[92:95], v[156:159], v[188:191], v[92:95]
	v_mfma_f32_16x16x32_bf16 v[88:91], v[164:167], v[188:191], v[88:91]
	v_mfma_f32_16x16x32_bf16 v[72:75], v[164:167], v[196:199], v[72:75]
	v_mfma_f32_16x16x32_bf16 v[76:79], v[156:159], v[196:199], v[76:79]
	s_barrier
	s_add_i32 s44, 0, 0x1c000
	s_add_i32 s45, s71, s51
	s_mov_b32 m0, s45
	ds_read_b128 v[200:203], v253
	ds_read_b128 v[204:207], v253 offset:1024
	ds_read_b128 v[210:213], v253 offset:2048
	ds_read_b128 v[214:217], v253 offset:3072
	global_load_lds_dwordx4 v130, s[76:77]
	s_add_i32 m0, s45, 0x2000
	s_nop 0
	global_load_lds_dwordx4 v134, s[76:77]
	s_barrier
	s_waitcnt lgkmcnt(0)
	v_mfma_f32_16x16x32_bf16 v[116:119], v[200:203], v[168:171], v[116:119]
	v_mfma_f32_16x16x32_bf16 v[112:115], v[210:213], v[168:171], v[112:115]
	v_mfma_f32_16x16x32_bf16 v[96:99], v[210:213], v[176:179], v[96:99]
	v_mfma_f32_16x16x32_bf16 v[100:103], v[200:203], v[176:179], v[100:103]
	v_mfma_f32_16x16x32_bf16 v[84:87], v[200:203], v[184:187], v[84:87]
	v_mfma_f32_16x16x32_bf16 v[80:83], v[210:213], v[184:187], v[80:83]
	v_mfma_f32_16x16x32_bf16 v[64:67], v[210:213], v[192:195], v[64:67]
	v_mfma_f32_16x16x32_bf16 v[68:71], v[200:203], v[192:195], v[68:71]
	v_mfma_f32_16x16x32_bf16 v[116:119], v[204:207], v[172:175], v[116:119]
	v_mfma_f32_16x16x32_bf16 v[112:115], v[214:217], v[172:175], v[112:115]
	v_mfma_f32_16x16x32_bf16 v[96:99], v[214:217], v[180:183], v[96:99]
	v_mfma_f32_16x16x32_bf16 v[100:103], v[204:207], v[180:183], v[100:103]
	v_mfma_f32_16x16x32_bf16 v[84:87], v[204:207], v[188:191], v[84:87]
	v_mfma_f32_16x16x32_bf16 v[80:83], v[214:217], v[188:191], v[80:83]
	v_mfma_f32_16x16x32_bf16 v[64:67], v[214:217], v[196:199], v[64:67]
	v_mfma_f32_16x16x32_bf16 v[68:71], v[204:207], v[196:199], v[68:71]
	s_barrier
	s_mov_b32 m0, s61
	ds_read_b128 v[168:171], v150 offset:49152
	ds_read_b128 v[172:175], v150 offset:50176
	ds_read_b128 v[176:179], v150 offset:51200
	ds_read_b128 v[180:183], v150 offset:52224
	ds_read_b128 v[184:187], v150 offset:53248
	ds_read_b128 v[188:191], v150 offset:54272
	ds_read_b128 v[192:195], v150 offset:55296
	ds_read_b128 v[196:199], v150 offset:56320
	global_load_lds_dwordx4 v128, s[78:79]
	s_mov_b32 m0, s62
	s_nop 0
	global_load_lds_dwordx4 v132, s[78:79]
	s_barrier
	s_waitcnt lgkmcnt(0)
	v_mfma_f32_16x16x32_bf16 v[60:63], v[152:155], v[168:171], v[60:63]
	v_mfma_f32_16x16x32_bf16 v[56:59], v[160:163], v[168:171], v[56:59]
	v_mfma_f32_16x16x32_bf16 v[40:43], v[160:163], v[176:179], v[40:43]
	v_mfma_f32_16x16x32_bf16 v[44:47], v[152:155], v[176:179], v[44:47]
	v_mfma_f32_16x16x32_bf16 v[28:31], v[152:155], v[184:187], v[28:31]
	v_mfma_f32_16x16x32_bf16 v[24:27], v[160:163], v[184:187], v[24:27]
	v_mfma_f32_16x16x32_bf16 v[8:11], v[160:163], v[192:195], v[8:11]
	v_mfma_f32_16x16x32_bf16 v[12:15], v[152:155], v[192:195], v[12:15]
	v_mfma_f32_16x16x32_bf16 v[60:63], v[156:159], v[172:175], v[60:63]
	v_mfma_f32_16x16x32_bf16 v[56:59], v[164:167], v[172:175], v[56:59]
	v_mfma_f32_16x16x32_bf16 v[40:43], v[164:167], v[180:183], v[40:43]
	v_mfma_f32_16x16x32_bf16 v[44:47], v[156:159], v[180:183], v[44:47]
	v_mfma_f32_16x16x32_bf16 v[28:31], v[156:159], v[188:191], v[28:31]
	v_mfma_f32_16x16x32_bf16 v[24:27], v[164:167], v[188:191], v[24:27]
	v_mfma_f32_16x16x32_bf16 v[8:11], v[164:167], v[196:199], v[8:11]
	v_mfma_f32_16x16x32_bf16 v[12:15], v[156:159], v[196:199], v[12:15]
	s_barrier
; #define PG8_STAGE(bufoff, gbase, voff) do { _Pragma("unroll") for (int _i = 0; _i < 2; ++_i) \
;         __builtin_amdgcn_global_load_lds((const unsigned*)((const char*)(gbase) + (voff)[_i]), (LAS unsigned*)(lds + (bufoff) + ldsw + _i * 8192), 16, 0, 0); } while (0)
; #define PG8_LDA(dst, b, h) do { _Pragma("unroll") for (int m = 0; m < 4; ++m) _Pragma("unroll") for (int k = 0; k < 2; ++k) dst[m][k] = *(const LAS bf16x8*)(lds + PG8_SA(b, h) + aoff + m * 2048 + k * 1024); } while (0)
; #define PG8_LDB(dst, b, h) do { _Pragma("unroll") for (int n = 0; n < 2; ++n) _Pragma("unroll") for (int k = 0; k < 2; ++k) dst[n][k] = *(const LAS bf16x8*)(lds + PG8_SB(b, h) + boff + n * 2048 + k * 1024); } while (0)
; #define PG8_WAIT_V(n) asm volatile("s_waitcnt vmcnt(" #n ")" ::: "memory")
; #define PG8_WAIT_L(n) asm volatile("s_waitcnt lgkmcnt(" #n ")" ::: "memory")
; #define PG8_BAR __builtin_amdgcn_s_barrier()
; #define PG8_SCHED __builtin_amdgcn_sched_barrier(0)
; template <class Epi, class Ptrs>
; __device__ __forceinline__ void gemm_phase(LAS unsigned char* lds, const int K, const StaticOrder& S, const Ptrs& P, const Epi& E) {
;     ...
;         for (int t = 0; t < nt; t += 2) {
;             const bool last = (t == nt - 2);
;             const char* a1 = cA + (size_t)(t + 1) * kstep;
;             const char* a2 = last ? nA : cA + (size_t)(t + 2) * kstep; const char* b2 = last ? nB : cB + (size_t)(t + 2) * kstep;
;             const char* a3 = a2 + kstep; const char* b3 = b2 + kstep;
;             PG8_LDB(B0, 0, 0); PG8_SCHED; PG8_LDA(At, 0, 0); PG8_STAGE(PG8_SA(1, 1), a1 + hstep, voffA);
;             PG8_WAIT_L(8); PG8_BAR; PG8_WAIT_L(0); PG8_MMA(0, 0, At, B0); PG8_BAR; PG8_SCHED;
;             PG8_LDB(B1, 0, 1); PG8_STAGE(PG8_SB(0, 0), b2, voffB);
;             PG8_BAR; PG8_WAIT_L(0); PG8_MMA(0, 1, At, B1); PG8_BAR;
;             PG8_LDA(At, 0, 1); PG8_STAGE(PG8_SA(0, 0), a2, voffA);
;             PG8_BAR; PG8_WAIT_L(0); PG8_MMA(1, 0, At, B0); PG8_BAR; PG8_SCHED;
;             PG8_STAGE(PG8_SB(0, 1), b2 + hstep, voffB);
;             PG8_WAIT_V(6); PG8_BAR; PG8_MMA(1, 1, At, B1); PG8_BAR;
;             PG8_LDB(B0, 1, 0); PG8_SCHED; PG8_LDA(At, 1, 0); PG8_STAGE(PG8_SA(0, 1), a2 + hstep, voffA);
;             PG8_WAIT_L(8); PG8_BAR; PG8_WAIT_L(0); PG8_MMA(0, 0, At, B0); PG8_BAR; PG8_SCHED;
	s_add_u32 s42, s42, 0x40080
	s_addc_u32 s43, s43, 0
	s_add_i32 s44, s44, s51
	s_mov_b32 m0, s44
	s_nop 0
	global_load_lds_dwordx4 v130, s[42:43]
	s_add_i32 m0, s44, 0x2000
	s_nop 0
	global_load_lds_dwordx4 v134, s[42:43]
	s_waitcnt vmcnt(6)
	s_barrier
	v_mfma_f32_16x16x32_bf16 v[52:55], v[200:203], v[168:171], v[52:55]
	v_mfma_f32_16x16x32_bf16 v[48:51], v[210:213], v[168:171], v[48:51]
	v_mfma_f32_16x16x32_bf16 v[32:35], v[210:213], v[176:179], v[32:35]
	v_mfma_f32_16x16x32_bf16 v[36:39], v[200:203], v[176:179], v[36:39]
	v_mfma_f32_16x16x32_bf16 v[20:23], v[200:203], v[184:187], v[20:23]
	v_mfma_f32_16x16x32_bf16 v[16:19], v[210:213], v[184:187], v[16:19]
	v_mfma_f32_16x16x32_bf16 v[0:3], v[210:213], v[192:195], v[0:3]
	v_mfma_f32_16x16x32_bf16 v[4:7], v[200:203], v[192:195], v[4:7]
	v_mfma_f32_16x16x32_bf16 v[52:55], v[204:207], v[172:175], v[52:55]
	v_mfma_f32_16x16x32_bf16 v[48:51], v[214:217], v[172:175], v[48:51]
	v_mfma_f32_16x16x32_bf16 v[32:35], v[214:217], v[180:183], v[32:35]
	v_mfma_f32_16x16x32_bf16 v[36:39], v[204:207], v[180:183], v[36:39]
	v_mfma_f32_16x16x32_bf16 v[20:23], v[204:207], v[188:191], v[20:23]
	v_mfma_f32_16x16x32_bf16 v[16:19], v[214:217], v[188:191], v[16:19]
	v_mfma_f32_16x16x32_bf16 v[0:3], v[214:217], v[196:199], v[0:3]
	v_mfma_f32_16x16x32_bf16 v[4:7], v[204:207], v[196:199], v[4:7]
	s_barrier
	s_add_i32 s70, s70, 2
	s_add_u32 s40, s40, 0x100
	s_addc_u32 s41, s41, 0
	s_add_u32 s23, s23, 0x100
	s_addc_u32 s25, s25, 0
	s_cmp_gt_u32 s70, 13
.LBB0_433:
	ds_read_b128 v[152:155], v149
	ds_read_b128 v[156:159], v149 offset:1024
	ds_read_b128 v[160:163], v149 offset:2048
	ds_read_b128 v[164:167], v149 offset:3072
	s_add_u32 s42, s40, 0xfffc0080
	s_addc_u32 s43, s41, -1
	s_cmp_eq_u32 s70, 12
	s_cselect_b32 s45, s1, s43
	s_cselect_b32 s44, s0, s42
	s_cselect_b32 s43, s37, s25
	s_cselect_b32 s42, s36, s23
	s_add_i32 m0, s39, 0xc000
	ds_read_b128 v[168:171], v150
	ds_read_b128 v[172:175], v150 offset:1024
	ds_read_b128 v[176:179], v150 offset:2048
	ds_read_b128 v[180:183], v150 offset:3072
	ds_read_b128 v[184:187], v150 offset:4096
	ds_read_b128 v[188:191], v150 offset:5120
	ds_read_b128 v[192:195], v150 offset:6144
	ds_read_b128 v[196:199], v150 offset:7168
	global_load_lds_dwordx4 v136, s[40:41]
	s_add_i32 m0, s39, 0xe000
	s_nop 0
	global_load_lds_dwordx4 v138, s[40:41]
	s_waitcnt lgkmcnt(8)
	s_barrier
	s_waitcnt lgkmcnt(0)
	v_mfma_f32_16x16x32_bf16 v[124:127], v[152:155], v[168:171], v[124:127]
	v_mfma_f32_16x16x32_bf16 v[120:123], v[160:163], v[168:171], v[120:123]
	v_mfma_f32_16x16x32_bf16 v[104:107], v[160:163], v[176:179], v[104:107]
	v_mfma_f32_16x16x32_bf16 v[108:111], v[152:155], v[176:179], v[108:111]
	v_mfma_f32_16x16x32_bf16 v[92:95], v[152:155], v[184:187], v[92:95]
	v_mfma_f32_16x16x32_bf16 v[88:91], v[160:163], v[184:187], v[88:91]
	v_mfma_f32_16x16x32_bf16 v[72:75], v[160:163], v[192:195], v[72:75]
	v_mfma_f32_16x16x32_bf16 v[76:79], v[152:155], v[192:195], v[76:79]
	v_mfma_f32_16x16x32_bf16 v[124:127], v[156:159], v[172:175], v[124:127]
	v_mfma_f32_16x16x32_bf16 v[120:123], v[164:167], v[172:175], v[120:123]
	v_mfma_f32_16x16x32_bf16 v[104:107], v[164:167], v[180:183], v[104:107]
	v_mfma_f32_16x16x32_bf16 v[108:111], v[156:159], v[180:183], v[108:111]
	v_mfma_f32_16x16x32_bf16 v[92:95], v[156:159], v[188:191], v[92:95]
	v_mfma_f32_16x16x32_bf16 v[88:91], v[164:167], v[188:191], v[88:91]
	v_mfma_f32_16x16x32_bf16 v[72:75], v[164:167], v[196:199], v[72:75]
	v_mfma_f32_16x16x32_bf16 v[76:79], v[156:159], v[196:199], v[76:79]
	s_barrier
	s_add_i32 s71, s63, s51
	s_add_u32 s76, s42, 0x80
	s_addc_u32 s77, s43, 0
	s_mov_b32 m0, s71
	ds_read_b128 v[200:203], v151
	ds_read_b128 v[204:207], v151 offset:1024
	ds_read_b128 v[210:213], v151 offset:2048
	ds_read_b128 v[214:217], v151 offset:3072
	global_load_lds_dwordx4 v130, s[42:43]
	s_add_i32 m0, s71, 0x2000
	s_nop 0
	global_load_lds_dwordx4 v134, s[42:43]
	s_barrier
	s_waitcnt lgkmcnt(0)
	v_mfma_f32_16x16x32_bf16 v[116:119], v[200:203], v[168:171], v[116:119]
	v_mfma_f32_16x16x32_bf16 v[112:115], v[210:213], v[168:171], v[112:115]
	v_mfma_f32_16x16x32_bf16 v[96:99], v[210:213], v[176:179], v[96:99]
	v_mfma_f32_16x16x32_bf16 v[100:103], v[200:203], v[176:179], v[100:103]
	v_mfma_f32_16x16x32_bf16 v[84:87], v[200:203], v[184:187], v[84:87]
	v_mfma_f32_16x16x32_bf16 v[80:83], v[210:213], v[184:187], v[80:83]
	v_mfma_f32_16x16x32_bf16 v[64:67], v[210:213], v[192:195], v[64:67]
	v_mfma_f32_16x16x32_bf16 v[68:71], v[200:203], v[192:195], v[68:71]
	v_mfma_f32_16x16x32_bf16 v[116:119], v[204:207], v[172:175], v[116:119]
	v_mfma_f32_16x16x32_bf16 v[112:115], v[214:217], v[172:175], v[112:115]
	v_mfma_f32_16x16x32_bf16 v[96:99], v[214:217], v[180:183], v[96:99]
	v_mfma_f32_16x16x32_bf16 v[100:103], v[204:207], v[180:183], v[100:103]
	v_mfma_f32_16x16x32_bf16 v[84:87], v[204:207], v[188:191], v[84:87]
	v_mfma_f32_16x16x32_bf16 v[80:83], v[214:217], v[188:191], v[80:83]
	v_mfma_f32_16x16x32_bf16 v[64:67], v[214:217], v[196:199], v[64:67]
	v_mfma_f32_16x16x32_bf16 v[68:71], v[204:207], v[196:199], v[68:71]
	s_barrier
	s_mov_b32 m0, s39
	s_add_u32 s78, s44, 0x80
	s_addc_u32 s79, s45, 0
	ds_read_b128 v[168:171], v150 offset:16384
	ds_read_b128 v[172:175], v150 offset:17408
	ds_read_b128 v[176:179], v150 offset:18432
	ds_read_b128 v[180:183], v150 offset:19456
	ds_read_b128 v[184:187], v150 offset:20480
	ds_read_b128 v[188:191], v150 offset:21504
	ds_read_b128 v[192:195], v150 offset:22528
	ds_read_b128 v[196:199], v150 offset:23552
	global_load_lds_dwordx4 v128, s[44:45]
	s_mov_b32 m0, s56
	s_nop 0
	global_load_lds_dwordx4 v132, s[44:45]
	s_barrier
; #define PG8_STAGE(bufoff, gbase, voff) do { _Pragma("unroll") for (int _i = 0; _i < 2; ++_i) \
;         __builtin_amdgcn_global_load_lds((const unsigned*)((const char*)(gbase) + (voff)[_i]), (LAS unsigned*)(lds + (bufoff) + ldsw + _i * 8192), 16, 0, 0); } while (0)
; #define PG8_LDA(dst, b, h) do { _Pragma("unroll") for (int m = 0; m < 4; ++m) _Pragma("unroll") for (int k = 0; k < 2; ++k) dst[m][k] = *(const LAS bf16x8*)(lds + PG8_SA(b, h) + aoff + m * 2048 + k * 1024); } while (0)
; #define PG8_LDB(dst, b, h) do { _Pragma("unroll") for (int n = 0; n < 2; ++n) _Pragma("unroll") for (int k = 0; k < 2; ++k) dst[n][k] = *(const LAS bf16x8*)(lds + PG8_SB(b, h) + boff + n * 2048 + k * 1024); } while (0)
; #define PG8_MMA(ai, bj, At, Bt) do { __builtin_amdgcn_s_setprio(1); _Pragma("unroll") for (int m = 0; m < 4; ++m) _Pragma("unroll") for (int n = 0; n < 2; ++n) _Pragma("unroll") for (int k = 0; k < 2; ++k) \
;         acc[ai][bj][m][n] = __builtin_amdgcn_mfma_f32_16x16x32_bf16(Bt[n][k], At[m][k], acc[ai][bj][m][n], 0, 0, 0); __builtin_amdgcn_s_setprio(0); } while (0)
; #define PG8_WAIT_V(n) asm volatile("s_waitcnt vmcnt(" #n ")" ::: "memory")
; #define PG8_WAIT_L(n) asm volatile("s_waitcnt lgkmcnt(" #n ")" ::: "memory")
; #define PG8_BAR __builtin_amdgcn_s_barrier()
; #define PG8_SCHED __builtin_amdgcn_sched_barrier(0)
; template <class Epi, class Ptrs>
; __device__ __forceinline__ void gemm_phase(LAS unsigned char* lds, const int K, const StaticOrder& S, const Ptrs& P, const Epi& E) {
;     ...
;             PG8_LDA(At, 0, 1); PG8_STAGE(PG8_SA(0, 0), a2, voffA);
;             PG8_BAR; PG8_WAIT_L(0); PG8_MMA(1, 0, At, B0); PG8_BAR; PG8_SCHED;
;             PG8_STAGE(PG8_SB(0, 1), b2 + hstep, voffB);
;             PG8_WAIT_V(6); PG8_BAR; PG8_MMA(1, 1, At, B1); PG8_BAR;
;             PG8_LDB(B0, 1, 0); PG8_SCHED; PG8_LDA(At, 1, 0); PG8_STAGE(PG8_SA(0, 1), a2 + hstep, voffA);
;             PG8_WAIT_L(8); PG8_BAR; PG8_WAIT_L(0); PG8_MMA(0, 0, At, B0); PG8_BAR; PG8_SCHED;
;             PG8_LDB(B1, 1, 1); PG8_STAGE(PG8_SB(1, 0), b3, voffB);
;             PG8_BAR; PG8_WAIT_L(0); PG8_MMA(0, 1, At, B1); PG8_BAR;
;             PG8_LDA(At, 1, 1); PG8_STAGE(PG8_SA(1, 0), a3, voffA);
;             PG8_BAR; PG8_WAIT_L(0); PG8_MMA(1, 0, At, B0); PG8_BAR; PG8_SCHED;
	s_waitcnt lgkmcnt(0)
	v_mfma_f32_16x16x32_bf16 v[60:63], v[152:155], v[168:171], v[60:63]
	v_mfma_f32_16x16x32_bf16 v[56:59], v[160:163], v[168:171], v[56:59]
	v_mfma_f32_16x16x32_bf16 v[40:43], v[160:163], v[176:179], v[40:43]
	v_mfma_f32_16x16x32_bf16 v[44:47], v[152:155], v[176:179], v[44:47]
	v_mfma_f32_16x16x32_bf16 v[28:31], v[152:155], v[184:187], v[28:31]
	v_mfma_f32_16x16x32_bf16 v[24:27], v[160:163], v[184:187], v[24:27]
	v_mfma_f32_16x16x32_bf16 v[8:11], v[160:163], v[192:195], v[8:11]
	v_mfma_f32_16x16x32_bf16 v[12:15], v[152:155], v[192:195], v[12:15]
	v_mfma_f32_16x16x32_bf16 v[60:63], v[156:159], v[172:175], v[60:63]
	v_mfma_f32_16x16x32_bf16 v[56:59], v[164:167], v[172:175], v[56:59]
	v_mfma_f32_16x16x32_bf16 v[40:43], v[164:167], v[180:183], v[40:43]
	v_mfma_f32_16x16x32_bf16 v[44:47], v[156:159], v[180:183], v[44:47]
	v_mfma_f32_16x16x32_bf16 v[28:31], v[156:159], v[188:191], v[28:31]
	v_mfma_f32_16x16x32_bf16 v[24:27], v[164:167], v[188:191], v[24:27]
	v_mfma_f32_16x16x32_bf16 v[8:11], v[164:167], v[196:199], v[8:11]
	v_mfma_f32_16x16x32_bf16 v[12:15], v[156:159], v[196:199], v[12:15]
	s_barrier
	s_add_u32 s72, s42, 0x40000
	s_addc_u32 s73, s43, 0
	s_add_i32 s71, s64, s51
	s_mov_b32 m0, s71
	s_nop 0
	global_load_lds_dwordx4 v130, s[72:73]
	s_add_i32 m0, s71, 0x2000
	s_nop 0
	global_load_lds_dwordx4 v134, s[72:73]
	s_waitcnt vmcnt(6)
	s_barrier
	v_mfma_f32_16x16x32_bf16 v[52:55], v[200:203], v[168:171], v[52:55]
	v_mfma_f32_16x16x32_bf16 v[48:51], v[210:213], v[168:171], v[48:51]
	v_mfma_f32_16x16x32_bf16 v[32:35], v[210:213], v[176:179], v[32:35]
	v_mfma_f32_16x16x32_bf16 v[36:39], v[200:203], v[176:179], v[36:39]
	v_mfma_f32_16x16x32_bf16 v[20:23], v[200:203], v[184:187], v[20:23]
	v_mfma_f32_16x16x32_bf16 v[16:19], v[210:213], v[184:187], v[16:19]
	v_mfma_f32_16x16x32_bf16 v[0:3], v[210:213], v[192:195], v[0:3]
	v_mfma_f32_16x16x32_bf16 v[4:7], v[200:203], v[192:195], v[4:7]
	v_mfma_f32_16x16x32_bf16 v[52:55], v[204:207], v[172:175], v[52:55]
	v_mfma_f32_16x16x32_bf16 v[48:51], v[214:217], v[172:175], v[48:51]
	v_mfma_f32_16x16x32_bf16 v[32:35], v[214:217], v[180:183], v[32:35]
	v_mfma_f32_16x16x32_bf16 v[36:39], v[204:207], v[180:183], v[36:39]
	v_mfma_f32_16x16x32_bf16 v[20:23], v[204:207], v[188:191], v[20:23]
	v_mfma_f32_16x16x32_bf16 v[16:19], v[214:217], v[188:191], v[16:19]
	v_mfma_f32_16x16x32_bf16 v[0:3], v[214:217], v[196:199], v[0:3]
	v_mfma_f32_16x16x32_bf16 v[4:7], v[204:207], v[196:199], v[4:7]
	s_barrier
	s_add_i32 s71, 0, 0x18000
	ds_read_b128 v[152:155], v252
	ds_read_b128 v[156:159], v252 offset:1024
	ds_read_b128 v[160:163], v252 offset:2048
	ds_read_b128 v[164:167], v252 offset:3072
	s_add_u32 s44, s44, 0x40000
	s_addc_u32 s45, s45, 0
	s_mov_b32 m0, s57
	ds_read_b128 v[168:171], v150 offset:32768
	ds_read_b128 v[172:175], v150 offset:33792
	ds_read_b128 v[176:179], v150 offset:34816
	ds_read_b128 v[180:183], v150 offset:35840
	ds_read_b128 v[184:187], v150 offset:36864
	ds_read_b128 v[188:191], v150 offset:37888
	ds_read_b128 v[192:195], v150 offset:38912
	ds_read_b128 v[196:199], v150 offset:39936
	global_load_lds_dwordx4 v128, s[44:45]
	s_mov_b32 m0, s58
	s_nop 0
	global_load_lds_dwordx4 v132, s[44:45]
	s_waitcnt lgkmcnt(8)
	s_barrier
	s_waitcnt lgkmcnt(0)
	v_mfma_f32_16x16x32_bf16 v[124:127], v[152:155], v[168:171], v[124:127]
	v_mfma_f32_16x16x32_bf16 v[120:123], v[160:163], v[168:171], v[120:123]
	v_mfma_f32_16x16x32_bf16 v[104:107], v[160:163], v[176:179], v[104:107]
	v_mfma_f32_16x16x32_bf16 v[108:111], v[152:155], v[176:179], v[108:111]
	v_mfma_f32_16x16x32_bf16 v[92:95], v[152:155], v[184:187], v[92:95]
	v_mfma_f32_16x16x32_bf16 v[88:91], v[160:163], v[184:187], v[88:91]
	v_mfma_f32_16x16x32_bf16 v[72:75], v[160:163], v[192:195], v[72:75]
	v_mfma_f32_16x16x32_bf16 v[76:79], v[152:155], v[192:195], v[76:79]
	v_mfma_f32_16x16x32_bf16 v[124:127], v[156:159], v[172:175], v[124:127]
	v_mfma_f32_16x16x32_bf16 v[120:123], v[164:167], v[172:175], v[120:123]
	v_mfma_f32_16x16x32_bf16 v[104:107], v[164:167], v[180:183], v[104:107]
	v_mfma_f32_16x16x32_bf16 v[108:111], v[156:159], v[180:183], v[108:111]
	v_mfma_f32_16x16x32_bf16 v[92:95], v[156:159], v[188:191], v[92:95]
	v_mfma_f32_16x16x32_bf16 v[88:91], v[164:167], v[188:191], v[88:91]
	v_mfma_f32_16x16x32_bf16 v[72:75], v[164:167], v[196:199], v[72:75]
	v_mfma_f32_16x16x32_bf16 v[76:79], v[156:159], v[196:199], v[76:79]
	s_barrier
	s_add_i32 s44, 0, 0x1c000
	s_add_i32 s45, s71, s51
	s_mov_b32 m0, s45
	ds_read_b128 v[200:203], v253
	ds_read_b128 v[204:207], v253 offset:1024
	ds_read_b128 v[210:213], v253 offset:2048
	ds_read_b128 v[214:217], v253 offset:3072
	global_load_lds_dwordx4 v130, s[76:77]
	s_add_i32 m0, s45, 0x2000
	s_nop 0
	global_load_lds_dwordx4 v134, s[76:77]
	s_barrier
	s_waitcnt lgkmcnt(0)
	v_mfma_f32_16x16x32_bf16 v[116:119], v[200:203], v[168:171], v[116:119]
	v_mfma_f32_16x16x32_bf16 v[112:115], v[210:213], v[168:171], v[112:115]
	v_mfma_f32_16x16x32_bf16 v[96:99], v[210:213], v[176:179], v[96:99]
	v_mfma_f32_16x16x32_bf16 v[100:103], v[200:203], v[176:179], v[100:103]
	v_mfma_f32_16x16x32_bf16 v[84:87], v[200:203], v[184:187], v[84:87]
	v_mfma_f32_16x16x32_bf16 v[80:83], v[210:213], v[184:187], v[80:83]
	v_mfma_f32_16x16x32_bf16 v[64:67], v[210:213], v[192:195], v[64:67]
	v_mfma_f32_16x16x32_bf16 v[68:71], v[200:203], v[192:195], v[68:71]
	v_mfma_f32_16x16x32_bf16 v[116:119], v[204:207], v[172:175], v[116:119]
	v_mfma_f32_16x16x32_bf16 v[112:115], v[214:217], v[172:175], v[112:115]
	v_mfma_f32_16x16x32_bf16 v[96:99], v[214:217], v[180:183], v[96:99]
	v_mfma_f32_16x16x32_bf16 v[100:103], v[204:207], v[180:183], v[100:103]
	v_mfma_f32_16x16x32_bf16 v[84:87], v[204:207], v[188:191], v[84:87]
	v_mfma_f32_16x16x32_bf16 v[80:83], v[214:217], v[188:191], v[80:83]
	v_mfma_f32_16x16x32_bf16 v[64:67], v[214:217], v[196:199], v[64:67]
	v_mfma_f32_16x16x32_bf16 v[68:71], v[204:207], v[196:199], v[68:71]
	s_barrier
; __device__ __forceinline__ unsigned cvt_pk_bf16(float lo, float hi) { unsigned r; asm volatile("v_cvt_pk_bf16_f32 %0, %1, %2" : "=v"(r) : "v"(lo), "v"(hi)); return r; }
; #define PG8_STAGE(bufoff, gbase, voff) do { _Pragma("unroll") for (int _i = 0; _i < 2; ++_i) \
;         __builtin_amdgcn_global_load_lds((const unsigned*)((const char*)(gbase) + (voff)[_i]), (LAS unsigned*)(lds + (bufoff) + ldsw + _i * 8192), 16, 0, 0); } while (0)
; #define PG8_LDA(dst, b, h) do { _Pragma("unroll") for (int m = 0; m < 4; ++m) _Pragma("unroll") for (int k = 0; k < 2; ++k) dst[m][k] = *(const LAS bf16x8*)(lds + PG8_SA(b, h) + aoff + m * 2048 + k * 1024); } while (0)
; #define PG8_WAIT_V(n) asm volatile("s_waitcnt vmcnt(" #n ")" ::: "memory")
; #define PG8_WAIT_L(n) asm volatile("s_waitcnt lgkmcnt(" #n ")" ::: "memory")
; #define PG8_BAR __builtin_amdgcn_s_barrier()
; #define PG8_SCHED __builtin_amdgcn_sched_barrier(0)
; template <class Epi, class Ptrs>
; __device__ __forceinline__ void gemm_phase(LAS unsigned char* lds, const int K, const StaticOrder& S, const Ptrs& P, const Epi& E) {
;     ...
;             PG8_LDA(At, 1, 1); PG8_STAGE(PG8_SA(1, 0), a3, voffA);
;             PG8_BAR; PG8_WAIT_L(0); PG8_MMA(1, 0, At, B0); PG8_BAR; PG8_SCHED;
;             PG8_STAGE(PG8_SB(1, 1), b3 + hstep, voffB);
;             PG8_WAIT_V(6); PG8_BAR; PG8_MMA(1, 1, At, B1); PG8_BAR;
;         }
;         E(acc, cur, ui, wr, wc, fr, fq);
;         if (!has_next) break;
;     __device__ __forceinline__ void operator()(const f32x4 (&acc)[2][2][4][2], const Unit& u, int ui, int wr, int wc, int fr, int fq) const {
;         const int row0 = u.pm * 256 + wr * 64 + fr, col0 = u.pn * 256 + wc * 32 + 8 * fq;
; #pragma unroll
;         for (int ai = 0; ai < 2; ++ai)
; #pragma unroll
;             for (int m = 0; m < 4; ++m) { bf16_t* rowp = hid + (size_t)(row0 + ai * 128 + m * 16) * DFF + col0;
; #pragma unroll
;                 for (int bj = 0; bj < 2; ++bj) { f32x4 v0 = acc[ai][bj][m][0], v1 = acc[ai][bj][m][1];
; #pragma unroll
;                     for (int j = 0; j < 4; ++j) { const float a = fmaxf(v0[j], 0.f), b = fmaxf(v1[j], 0.f); v0[j] = a * a; v1[j] = b * b; }
;                     u32x4 w; w.x = cvt_pk_bf16(v0[0], v0[1]); w.y = cvt_pk_bf16(v0[2], v0[3]); w.z = cvt_pk_bf16(v1[0], v1[1]); w.w = cvt_pk_bf16(v1[2], v1[3]);
;                     *(u32x4*)(rowp + bj * 128) = w; } }
	s_mov_b32 m0, s61
	ds_read_b128 v[168:171], v150 offset:49152
	ds_read_b128 v[172:175], v150 offset:50176
	ds_read_b128 v[176:179], v150 offset:51200
	ds_read_b128 v[180:183], v150 offset:52224
	ds_read_b128 v[184:187], v150 offset:53248
	ds_read_b128 v[188:191], v150 offset:54272
	ds_read_b128 v[192:195], v150 offset:55296
	ds_read_b128 v[196:199], v150 offset:56320
	global_load_lds_dwordx4 v128, s[78:79]
	s_mov_b32 m0, s62
	s_nop 0
	global_load_lds_dwordx4 v132, s[78:79]
	s_barrier
	s_waitcnt lgkmcnt(0)
	v_mfma_f32_16x16x32_bf16 v[60:63], v[152:155], v[168:171], v[60:63]
	v_mfma_f32_16x16x32_bf16 v[56:59], v[160:163], v[168:171], v[56:59]
	v_mfma_f32_16x16x32_bf16 v[40:43], v[160:163], v[176:179], v[40:43]
	v_mfma_f32_16x16x32_bf16 v[44:47], v[152:155], v[176:179], v[44:47]
	v_mfma_f32_16x16x32_bf16 v[28:31], v[152:155], v[184:187], v[28:31]
	v_mfma_f32_16x16x32_bf16 v[24:27], v[160:163], v[184:187], v[24:27]
	v_mfma_f32_16x16x32_bf16 v[8:11], v[160:163], v[192:195], v[8:11]
	v_mfma_f32_16x16x32_bf16 v[12:15], v[152:155], v[192:195], v[12:15]
	v_mfma_f32_16x16x32_bf16 v[60:63], v[156:159], v[172:175], v[60:63]
	v_mfma_f32_16x16x32_bf16 v[56:59], v[164:167], v[172:175], v[56:59]
	v_mfma_f32_16x16x32_bf16 v[40:43], v[164:167], v[180:183], v[40:43]
	v_mfma_f32_16x16x32_bf16 v[44:47], v[156:159], v[180:183], v[44:47]
	v_mfma_f32_16x16x32_bf16 v[28:31], v[156:159], v[188:191], v[28:31]
	v_mfma_f32_16x16x32_bf16 v[24:27], v[164:167], v[188:191], v[24:27]
	v_mfma_f32_16x16x32_bf16 v[8:11], v[164:167], v[196:199], v[8:11]
	v_mfma_f32_16x16x32_bf16 v[12:15], v[156:159], v[196:199], v[12:15]
	s_barrier
	s_add_u32 s42, s42, 0x40080
	s_addc_u32 s43, s43, 0
	s_add_i32 s44, s44, s51
	s_mov_b32 m0, s44
	s_nop 0
	global_load_lds_dwordx4 v130, s[42:43]
	s_add_i32 m0, s44, 0x2000
	s_nop 0
	global_load_lds_dwordx4 v134, s[42:43]
	s_waitcnt vmcnt(6)
	s_barrier
	v_mfma_f32_16x16x32_bf16 v[52:55], v[200:203], v[168:171], v[52:55]
	v_mfma_f32_16x16x32_bf16 v[48:51], v[210:213], v[168:171], v[48:51]
	v_mfma_f32_16x16x32_bf16 v[32:35], v[210:213], v[176:179], v[32:35]
	v_mfma_f32_16x16x32_bf16 v[36:39], v[200:203], v[176:179], v[36:39]
	v_mfma_f32_16x16x32_bf16 v[20:23], v[200:203], v[184:187], v[20:23]
	v_mfma_f32_16x16x32_bf16 v[16:19], v[210:213], v[184:187], v[16:19]
	v_mfma_f32_16x16x32_bf16 v[0:3], v[210:213], v[192:195], v[0:3]
	v_mfma_f32_16x16x32_bf16 v[4:7], v[200:203], v[192:195], v[4:7]
	v_mfma_f32_16x16x32_bf16 v[52:55], v[204:207], v[172:175], v[52:55]
	v_mfma_f32_16x16x32_bf16 v[48:51], v[214:217], v[172:175], v[48:51]
	v_mfma_f32_16x16x32_bf16 v[32:35], v[214:217], v[180:183], v[32:35]
	v_mfma_f32_16x16x32_bf16 v[36:39], v[204:207], v[180:183], v[36:39]
	v_mfma_f32_16x16x32_bf16 v[20:23], v[204:207], v[188:191], v[20:23]
	v_mfma_f32_16x16x32_bf16 v[16:19], v[214:217], v[188:191], v[16:19]
	v_mfma_f32_16x16x32_bf16 v[0:3], v[214:217], v[196:199], v[0:3]
	v_mfma_f32_16x16x32_bf16 v[4:7], v[204:207], v[196:199], v[4:7]
	s_barrier
	s_add_i32 s70, s70, 2
	s_add_u32 s40, s40, 0x100
	s_addc_u32 s41, s41, 0
	s_add_u32 s23, s23, 0x100
	s_addc_u32 s25, s25, 0
	s_cmp_gt_u32 s70, 13
	s_cbranch_scc0 .LBB0_433
	v_lshl_add_u32 v152, s38, 8, v146
	v_max_f32_e32 v120, 0, v120
	v_ashrrev_i32_e32 v153, 31, v152
	v_max_f32_e32 v121, 0, v121
	v_max_f32_e32 v122, 0, v122
	v_lshl_or_b32 v144, s69, 8, v148
	v_lshlrev_b64 v[154:155], 13, v[152:153]
	v_mul_f32_e32 v153, v120, v120
	v_max_f32_e32 v120, 0, v125
	v_ashrrev_i32_e32 v145, 31, v144
	v_max_f32_e32 v124, 0, v124
	v_mul_f32_e32 v125, v121, v121
	v_max_f32_e32 v121, 0, v126
	v_mul_f32_e32 v126, v122, v122
	v_max_f32_e32 v122, 0, v127
	v_max_f32_e32 v123, 0, v123
	v_lshl_add_u64 v[154:155], s[10:11], 0, v[154:155]
	v_lshlrev_b64 v[156:157], 1, v[144:145]
	v_mul_f32_e32 v120, v120, v120
	v_max_f32_e32 v112, 0, v112
	v_lshl_add_u64 v[144:145], v[154:155], 0, v[156:157]
	v_mul_f32_e32 v124, v124, v124
	v_mul_f32_e32 v121, v121, v121
	v_mul_f32_e32 v122, v122, v122
	v_mul_f32_e32 v123, v123, v123
	v_cvt_pk_bf16_f32 v120, v124, v120
	v_max_f32_e32 v113, 0, v113
	v_max_f32_e32 v114, 0, v114
	v_cvt_pk_bf16_f32 v121, v121, v122
	v_cvt_pk_bf16_f32 v122, v153, v125
	v_cvt_pk_bf16_f32 v123, v126, v123
	global_store_dwordx4 v[144:145], v[120:123], off
	s_nop 1
	v_mul_f32_e32 v120, v112, v112
	v_max_f32_e32 v112, 0, v117
	v_max_f32_e32 v116, 0, v116
	v_mul_f32_e32 v117, v113, v113
	v_max_f32_e32 v113, 0, v118
	v_mul_f32_e32 v118, v114, v114
	v_max_f32_e32 v114, 0, v119
	v_max_f32_e32 v115, 0, v115
	v_mul_f32_e32 v112, v112, v112
	v_mul_f32_e32 v116, v116, v116
	v_mul_f32_e32 v113, v113, v113
	v_mul_f32_e32 v114, v114, v114
	v_mul_f32_e32 v115, v115, v115
	v_cvt_pk_bf16_f32 v112, v116, v112
	v_max_f32_e32 v104, 0, v104
	v_cvt_pk_bf16_f32 v113, v113, v114
	v_cvt_pk_bf16_f32 v114, v120, v117
	v_cvt_pk_bf16_f32 v115, v118, v115
	global_store_dwordx4 v[144:145], v[112:115], off offset:256
	s_nop 0
	v_max_f32_e32 v105, 0, v105
	v_or_b32_e32 v112, 16, v152
	v_max_f32_e32 v106, 0, v106
	v_ashrrev_i32_e32 v113, 31, v112
	v_mul_f32_e32 v114, v104, v104
	v_max_f32_e32 v104, 0, v109
	v_lshlrev_b64 v[112:113], 13, v[112:113]
	v_max_f32_e32 v108, 0, v108
	v_mul_f32_e32 v109, v105, v105
	v_max_f32_e32 v105, 0, v110
	v_mul_f32_e32 v110, v106, v106
	v_max_f32_e32 v106, 0, v111
	v_max_f32_e32 v107, 0, v107
	v_lshl_add_u64 v[112:113], s[10:11], 0, v[112:113]
	v_mul_f32_e32 v104, v104, v104
	v_max_f32_e32 v96, 0, v96
	v_lshl_add_u64 v[112:113], v[112:113], 0, v[156:157]
	v_mul_f32_e32 v108, v108, v108
	v_mul_f32_e32 v105, v105, v105
	v_mul_f32_e32 v106, v106, v106
	v_mul_f32_e32 v107, v107, v107
	v_cvt_pk_bf16_f32 v104, v108, v104
; __device__ __forceinline__ unsigned cvt_pk_bf16(float lo, float hi) { unsigned r; asm volatile("v_cvt_pk_bf16_f32 %0, %1, %2" : "=v"(r) : "v"(lo), "v"(hi)); return r; }
;     __device__ __forceinline__ void operator()(const f32x4 (&acc)[2][2][4][2], const Unit& u, int ui, int wr, int wc, int fr, int fq) const {
;     ...
;         for (int ai = 0; ai < 2; ++ai)
; #pragma unroll
;             for (int m = 0; m < 4; ++m) { bf16_t* rowp = hid + (size_t)(row0 + ai * 128 + m * 16) * DFF + col0;
; #pragma unroll
;                 for (int bj = 0; bj < 2; ++bj) { f32x4 v0 = acc[ai][bj][m][0], v1 = acc[ai][bj][m][1];
; #pragma unroll
;                     for (int j = 0; j < 4; ++j) { const float a = fmaxf(v0[j], 0.f), b = fmaxf(v1[j], 0.f); v0[j] = a * a; v1[j] = b * b; }
;                     u32x4 w; w.x = cvt_pk_bf16(v0[0], v0[1]); w.y = cvt_pk_bf16(v0[2], v0[3]); w.z = cvt_pk_bf16(v1[0], v1[1]); w.w = cvt_pk_bf16(v1[2], v1[3]);
;                     *(u32x4*)(rowp + bj * 128) = w; } }
	v_max_f32_e32 v97, 0, v97
	v_max_f32_e32 v98, 0, v98
	v_cvt_pk_bf16_f32 v105, v105, v106
	v_cvt_pk_bf16_f32 v106, v114, v109
	v_cvt_pk_bf16_f32 v107, v110, v107
	global_store_dwordx4 v[112:113], v[104:107], off
	s_nop 1
	v_mul_f32_e32 v104, v96, v96
	v_max_f32_e32 v96, 0, v101
	v_max_f32_e32 v100, 0, v100
	v_mul_f32_e32 v101, v97, v97
	v_max_f32_e32 v97, 0, v102
	v_mul_f32_e32 v102, v98, v98
	v_max_f32_e32 v98, 0, v103
	v_max_f32_e32 v99, 0, v99
	v_mul_f32_e32 v96, v96, v96
	v_mul_f32_e32 v100, v100, v100
	v_mul_f32_e32 v97, v97, v97
	v_mul_f32_e32 v98, v98, v98
	v_mul_f32_e32 v99, v99, v99
	v_cvt_pk_bf16_f32 v96, v100, v96
	v_max_f32_e32 v88, 0, v88
	v_cvt_pk_bf16_f32 v97, v97, v98
	v_cvt_pk_bf16_f32 v98, v104, v101
	v_cvt_pk_bf16_f32 v99, v102, v99
	global_store_dwordx4 v[112:113], v[96:99], off offset:256
	s_nop 0
	v_max_f32_e32 v89, 0, v89
	v_or_b32_e32 v96, 32, v152
	v_max_f32_e32 v90, 0, v90
	v_ashrrev_i32_e32 v97, 31, v96
	v_mul_f32_e32 v98, v88, v88
	v_max_f32_e32 v88, 0, v93
	v_lshlrev_b64 v[96:97], 13, v[96:97]
	v_max_f32_e32 v92, 0, v92
	v_mul_f32_e32 v93, v89, v89
	v_max_f32_e32 v89, 0, v94
	v_mul_f32_e32 v94, v90, v90
	v_max_f32_e32 v90, 0, v95
	v_max_f32_e32 v91, 0, v91
	v_lshl_add_u64 v[96:97], s[10:11], 0, v[96:97]
	v_mul_f32_e32 v88, v88, v88
	v_max_f32_e32 v80, 0, v80
	v_lshl_add_u64 v[96:97], v[96:97], 0, v[156:157]
	v_mul_f32_e32 v92, v92, v92
	v_mul_f32_e32 v89, v89, v89
	v_mul_f32_e32 v90, v90, v90
	v_mul_f32_e32 v91, v91, v91
	v_cvt_pk_bf16_f32 v88, v92, v88
	v_max_f32_e32 v81, 0, v81
	v_max_f32_e32 v82, 0, v82
	v_cvt_pk_bf16_f32 v89, v89, v90
	v_cvt_pk_bf16_f32 v90, v98, v93
	v_cvt_pk_bf16_f32 v91, v94, v91
	global_store_dwordx4 v[96:97], v[88:91], off
	s_nop 1
	v_mul_f32_e32 v88, v80, v80
	v_max_f32_e32 v80, 0, v85
	v_max_f32_e32 v84, 0, v84
	v_mul_f32_e32 v85, v81, v81
	v_max_f32_e32 v81, 0, v86
	v_mul_f32_e32 v86, v82, v82
	v_max_f32_e32 v82, 0, v87
	v_max_f32_e32 v83, 0, v83
	v_mul_f32_e32 v80, v80, v80
	v_mul_f32_e32 v84, v84, v84
	v_mul_f32_e32 v81, v81, v81
	v_mul_f32_e32 v82, v82, v82
	v_mul_f32_e32 v83, v83, v83
	v_cvt_pk_bf16_f32 v80, v84, v80
	v_max_f32_e32 v72, 0, v72
	v_cvt_pk_bf16_f32 v81, v81, v82
	v_cvt_pk_bf16_f32 v82, v88, v85
	v_cvt_pk_bf16_f32 v83, v86, v83
	global_store_dwordx4 v[96:97], v[80:83], off offset:256
	s_nop 0
	v_max_f32_e32 v73, 0, v73
	v_or_b32_e32 v80, 48, v152
	v_max_f32_e32 v74, 0, v74
	v_ashrrev_i32_e32 v81, 31, v80
	v_mul_f32_e32 v82, v72, v72
	v_max_f32_e32 v72, 0, v77
	v_lshlrev_b64 v[80:81], 13, v[80:81]
	v_max_f32_e32 v76, 0, v76
	v_mul_f32_e32 v77, v73, v73
	v_max_f32_e32 v73, 0, v78
	v_mul_f32_e32 v78, v74, v74
	v_max_f32_e32 v74, 0, v79
	v_max_f32_e32 v75, 0, v75
	v_lshl_add_u64 v[80:81], s[10:11], 0, v[80:81]
	v_mul_f32_e32 v72, v72, v72
	v_max_f32_e32 v64, 0, v64
	v_max_f32_e32 v65, 0, v65
	v_max_f32_e32 v66, 0, v66
	v_lshl_add_u64 v[80:81], v[80:81], 0, v[156:157]
	v_mul_f32_e32 v76, v76, v76
	v_mul_f32_e32 v73, v73, v73
	v_mul_f32_e32 v74, v74, v74
	v_mul_f32_e32 v75, v75, v75
	v_cvt_pk_bf16_f32 v72, v76, v72
	v_cvt_pk_bf16_f32 v73, v73, v74
	v_cvt_pk_bf16_f32 v74, v82, v77
	v_cvt_pk_bf16_f32 v75, v78, v75
	global_store_dwordx4 v[80:81], v[72:75], off
	v_max_f32_e32 v68, 0, v68
	v_max_f32_e32 v67, 0, v67
	v_mul_f32_e32 v72, v64, v64
	v_max_f32_e32 v64, 0, v69
	v_mul_f32_e32 v69, v65, v65
	v_max_f32_e32 v65, 0, v70
	v_mul_f32_e32 v70, v66, v66
	v_max_f32_e32 v66, 0, v71
	v_mul_f32_e32 v64, v64, v64
	v_mul_f32_e32 v65, v65, v65
	v_mul_f32_e32 v66, v66, v66
	v_max_f32_e32 v56, 0, v56
	v_mul_f32_e32 v68, v68, v68
	v_mul_f32_e32 v67, v67, v67
	v_cvt_pk_bf16_f32 v64, v68, v64
	v_cvt_pk_bf16_f32 v65, v65, v66
	v_cvt_pk_bf16_f32 v66, v72, v69
	v_max_f32_e32 v57, 0, v57
	v_max_f32_e32 v58, 0, v58
	v_cvt_pk_bf16_f32 v67, v70, v67
	global_store_dwordx4 v[80:81], v[64:67], off offset:256
	s_nop 0
	v_max_f32_e32 v60, 0, v60
	v_mul_f32_e32 v66, v56, v56
	v_max_f32_e32 v56, 0, v61
	v_mul_f32_e32 v61, v57, v57
	v_max_f32_e32 v57, 0, v62
	v_mul_f32_e32 v62, v58, v58
	v_max_f32_e32 v58, 0, v63
	v_mul_f32_e32 v60, v60, v60
	v_mul_f32_e32 v56, v56, v56
	v_max_f32_e32 v59, 0, v59
	v_mul_f32_e32 v57, v57, v57
	v_mul_f32_e32 v58, v58, v58
	v_cvt_pk_bf16_f32 v56, v60, v56
	v_add_co_u32_e32 v60, vcc, s65, v144
	v_max_f32_e32 v48, 0, v48
	v_max_f32_e32 v49, 0, v49
	v_max_f32_e32 v50, 0, v50
	v_mul_f32_e32 v59, v59, v59
	v_cvt_pk_bf16_f32 v57, v57, v58
	v_cvt_pk_bf16_f32 v58, v66, v61
	v_addc_co_u32_e32 v61, vcc, 0, v145, vcc
	v_cvt_pk_bf16_f32 v59, v62, v59
	global_store_dwordx4 v[60:61], v[56:59], off
	v_max_f32_e32 v52, 0, v52
	v_max_f32_e32 v51, 0, v51
	v_mul_f32_e32 v56, v48, v48
	v_max_f32_e32 v48, 0, v53
	v_mul_f32_e32 v53, v49, v49
	v_max_f32_e32 v49, 0, v54
	v_mul_f32_e32 v54, v50, v50
	v_max_f32_e32 v50, 0, v55
; __device__ __forceinline__ unsigned cvt_pk_bf16(float lo, float hi) { unsigned r; asm volatile("v_cvt_pk_bf16_f32 %0, %1, %2" : "=v"(r) : "v"(lo), "v"(hi)); return r; }
; #define PG8_WAIT_V(n) asm volatile("s_waitcnt vmcnt(" #n ")" ::: "memory")
; #define PG8_BAR __builtin_amdgcn_s_barrier()
; template <class Epi, class Ptrs>
; __device__ __forceinline__ void gemm_phase(LAS unsigned char* lds, const int K, const StaticOrder& S, const Ptrs& P, const Epi& E) {
;     ...
;         if (!has_next) break;
; #pragma unroll
;         for (int a = 0; a < 2; ++a)
; #pragma unroll
;             for (int b = 0; b < 2; ++b)
; #pragma unroll
;                 for (int m = 0; m < 4; ++m)
; #pragma unroll
;                     for (int n = 0; n < 2; ++n) acc[a][b][m][n] = (f32x4){0.f, 0.f, 0.f, 0.f};
;         cur = nxt; cA = nA; cB = nB; ++ui;
;     }
;     PG8_WAIT_V(0);
;     if (wr == 0) PG8_BAR;
;     PG8_BAR;
;     __device__ __forceinline__ void operator()(const f32x4 (&acc)[2][2][4][2], const Unit& u, int ui, int wr, int wc, int fr, int fq) const {
;     ...
;         for (int ai = 0; ai < 2; ++ai)
; #pragma unroll
;             for (int m = 0; m < 4; ++m) { bf16_t* rowp = hid + (size_t)(row0 + ai * 128 + m * 16) * DFF + col0;
; #pragma unroll
;                 for (int bj = 0; bj < 2; ++bj) { f32x4 v0 = acc[ai][bj][m][0], v1 = acc[ai][bj][m][1];
; #pragma unroll
;                     for (int j = 0; j < 4; ++j) { const float a = fmaxf(v0[j], 0.f), b = fmaxf(v1[j], 0.f); v0[j] = a * a; v1[j] = b * b; }
;                     u32x4 w; w.x = cvt_pk_bf16(v0[0], v0[1]); w.y = cvt_pk_bf16(v0[2], v0[3]); w.z = cvt_pk_bf16(v1[0], v1[1]); w.w = cvt_pk_bf16(v1[2], v1[3]);
;                     *(u32x4*)(rowp + bj * 128) = w; } }
	v_mul_f32_e32 v48, v48, v48
	v_mul_f32_e32 v49, v49, v49
	v_mul_f32_e32 v50, v50, v50
	v_max_f32_e32 v40, 0, v40
	v_lshl_add_u64 v[64:65], v[144:145], 0, s[14:15]
	v_mul_f32_e32 v52, v52, v52
	v_mul_f32_e32 v51, v51, v51
	v_cvt_pk_bf16_f32 v48, v52, v48
	v_cvt_pk_bf16_f32 v49, v49, v50
	v_cvt_pk_bf16_f32 v50, v56, v53
	v_max_f32_e32 v41, 0, v41
	v_max_f32_e32 v42, 0, v42
	v_cvt_pk_bf16_f32 v51, v54, v51
	global_store_dwordx4 v[64:65], v[48:51], off offset:256
	s_nop 0
	v_max_f32_e32 v44, 0, v44
	v_mul_f32_e32 v50, v40, v40
	v_max_f32_e32 v40, 0, v45
	v_mul_f32_e32 v45, v41, v41
	v_max_f32_e32 v41, 0, v46
	v_mul_f32_e32 v46, v42, v42
	v_max_f32_e32 v42, 0, v47
	v_mul_f32_e32 v44, v44, v44
	v_mul_f32_e32 v40, v40, v40
	v_max_f32_e32 v43, 0, v43
	v_mul_f32_e32 v41, v41, v41
	v_mul_f32_e32 v42, v42, v42
	v_cvt_pk_bf16_f32 v40, v44, v40
	v_add_co_u32_e32 v44, vcc, s66, v144
	v_max_f32_e32 v32, 0, v32
	v_max_f32_e32 v33, 0, v33
	v_max_f32_e32 v34, 0, v34
	v_mul_f32_e32 v43, v43, v43
	v_cvt_pk_bf16_f32 v41, v41, v42
	v_cvt_pk_bf16_f32 v42, v50, v45
	v_addc_co_u32_e32 v45, vcc, 0, v145, vcc
	v_cvt_pk_bf16_f32 v43, v46, v43
	global_store_dwordx4 v[44:45], v[40:43], off
	v_max_f32_e32 v36, 0, v36
	v_max_f32_e32 v35, 0, v35
	v_mul_f32_e32 v40, v32, v32
	v_max_f32_e32 v32, 0, v37
	v_mul_f32_e32 v37, v33, v33
	v_max_f32_e32 v33, 0, v38
	v_mul_f32_e32 v38, v34, v34
	v_max_f32_e32 v34, 0, v39
	v_mul_f32_e32 v32, v32, v32
	v_mul_f32_e32 v33, v33, v33
	v_mul_f32_e32 v34, v34, v34
	v_max_f32_e32 v24, 0, v24
	v_lshl_add_u64 v[48:49], v[144:145], 0, s[16:17]
	v_mul_f32_e32 v36, v36, v36
	v_mul_f32_e32 v35, v35, v35
	v_cvt_pk_bf16_f32 v32, v36, v32
	v_cvt_pk_bf16_f32 v33, v33, v34
	v_cvt_pk_bf16_f32 v34, v40, v37
	v_max_f32_e32 v25, 0, v25
	v_max_f32_e32 v26, 0, v26
	v_cvt_pk_bf16_f32 v35, v38, v35
	global_store_dwordx4 v[48:49], v[32:35], off offset:256
	s_nop 0
	v_max_f32_e32 v28, 0, v28
	v_mul_f32_e32 v34, v24, v24
	v_max_f32_e32 v24, 0, v29
	v_mul_f32_e32 v29, v25, v25
	v_max_f32_e32 v25, 0, v30
	v_mul_f32_e32 v30, v26, v26
	v_max_f32_e32 v26, 0, v31
	v_mul_f32_e32 v28, v28, v28
	v_mul_f32_e32 v24, v24, v24
	v_max_f32_e32 v27, 0, v27
	v_mul_f32_e32 v25, v25, v25
	v_mul_f32_e32 v26, v26, v26
	v_cvt_pk_bf16_f32 v24, v28, v24
	v_add_co_u32_e32 v28, vcc, s67, v144
	v_max_f32_e32 v16, 0, v16
	v_max_f32_e32 v17, 0, v17
	v_max_f32_e32 v18, 0, v18
	v_mul_f32_e32 v27, v27, v27
	v_cvt_pk_bf16_f32 v25, v25, v26
	v_cvt_pk_bf16_f32 v26, v34, v29
	v_addc_co_u32_e32 v29, vcc, 0, v145, vcc
	v_cvt_pk_bf16_f32 v27, v30, v27
	global_store_dwordx4 v[28:29], v[24:27], off
	v_max_f32_e32 v20, 0, v20
	v_max_f32_e32 v19, 0, v19
	v_mul_f32_e32 v24, v16, v16
	v_max_f32_e32 v16, 0, v21
	v_mul_f32_e32 v21, v17, v17
	v_max_f32_e32 v17, 0, v22
	v_mul_f32_e32 v22, v18, v18
	v_max_f32_e32 v18, 0, v23
	v_mul_f32_e32 v16, v16, v16
	v_mul_f32_e32 v17, v17, v17
	v_mul_f32_e32 v18, v18, v18
	v_max_f32_e32 v8, 0, v8
	v_lshl_add_u64 v[32:33], v[144:145], 0, s[18:19]
	v_mul_f32_e32 v20, v20, v20
	v_mul_f32_e32 v19, v19, v19
	v_cvt_pk_bf16_f32 v16, v20, v16
	v_cvt_pk_bf16_f32 v17, v17, v18
	v_cvt_pk_bf16_f32 v18, v24, v21
	v_max_f32_e32 v9, 0, v9
	v_max_f32_e32 v10, 0, v10
	v_cvt_pk_bf16_f32 v19, v22, v19
	global_store_dwordx4 v[32:33], v[16:19], off offset:256
	s_nop 0
	v_max_f32_e32 v12, 0, v12
	v_mul_f32_e32 v18, v8, v8
	v_max_f32_e32 v8, 0, v13
	v_mul_f32_e32 v13, v9, v9
	v_max_f32_e32 v9, 0, v14
	v_mul_f32_e32 v14, v10, v10
	v_max_f32_e32 v10, 0, v15
	v_mul_f32_e32 v12, v12, v12
	v_mul_f32_e32 v8, v8, v8
	v_max_f32_e32 v11, 0, v11
	v_mul_f32_e32 v9, v9, v9
	v_mul_f32_e32 v10, v10, v10
	v_cvt_pk_bf16_f32 v8, v12, v8
	v_add_co_u32_e32 v12, vcc, s68, v144
	v_max_f32_e32 v0, 0, v0
	v_max_f32_e32 v1, 0, v1
	v_max_f32_e32 v2, 0, v2
	v_mul_f32_e32 v11, v11, v11
	v_cvt_pk_bf16_f32 v9, v9, v10
	v_cvt_pk_bf16_f32 v10, v18, v13
	v_addc_co_u32_e32 v13, vcc, 0, v145, vcc
	v_cvt_pk_bf16_f32 v11, v14, v11
	global_store_dwordx4 v[12:13], v[8:11], off
	v_max_f32_e32 v3, 0, v3
	v_max_f32_e32 v4, 0, v4
	v_mul_f32_e32 v8, v0, v0
	v_max_f32_e32 v0, 0, v5
	v_mul_f32_e32 v5, v1, v1
	v_max_f32_e32 v1, 0, v6
	v_mul_f32_e32 v6, v2, v2
	v_max_f32_e32 v2, 0, v7
	v_lshl_add_u64 v[16:17], v[144:145], 0, s[20:21]
	v_mul_f32_e32 v0, v0, v0
	v_mul_f32_e32 v1, v1, v1
	v_mul_f32_e32 v2, v2, v2
	v_mul_f32_e32 v3, v3, v3
	s_and_b64 vcc, exec, s[4:5]
	s_mov_b32 s69, s22
	s_mov_b32 s38, s24
	s_mov_b64 s[40:41], s[0:1]
	s_mov_b64 s[42:43], s[36:37]
	v_mul_f32_e32 v4, v4, v4
	v_cvt_pk_bf16_f32 v0, v4, v0
	v_cvt_pk_bf16_f32 v1, v1, v2
	v_cvt_pk_bf16_f32 v2, v8, v5
	v_cvt_pk_bf16_f32 v3, v6, v3
	global_store_dwordx4 v[16:17], v[0:3], off offset:256
	s_cbranch_vccz .LBB0_428
	s_waitcnt vmcnt(0)
	s_setprio 0
	s_cmpk_gt_u32 s46, 0xff
	s_cbranch_scc1 .LBB0_437
	s_barrier

; #define PG8_STAGE(bufoff, gbase, voff) do { _Pragma("unroll") for (int _i = 0; _i < 2; ++_i) \
;         __builtin_amdgcn_global_load_lds((const unsigned*)((const char*)(gbase) + (voff)[_i]), (LAS unsigned*)(lds + (bufoff) + ldsw + _i * 8192), 16, 0, 0); } while (0)
; #define PG8_LDA(dst, b, h) do { _Pragma("unroll") for (int m = 0; m < 4; ++m) _Pragma("unroll") for (int k = 0; k < 2; ++k) dst[m][k] = *(const LAS bf16x8*)(lds + PG8_SA(b, h) + aoff + m * 2048 + k * 1024); } while (0)
; #define PG8_LDB(dst, b, h) do { _Pragma("unroll") for (int n = 0; n < 2; ++n) _Pragma("unroll") for (int k = 0; k < 2; ++k) dst[n][k] = *(const LAS bf16x8*)(lds + PG8_SB(b, h) + boff + n * 2048 + k * 1024); } while (0)
; #define PG8_WAIT_V(n) asm volatile("s_waitcnt vmcnt(" #n ")" ::: "memory")
; #define PG8_WAIT_L(n) asm volatile("s_waitcnt lgkmcnt(" #n ")" ::: "memory")
; #define PG8_BAR __builtin_amdgcn_s_barrier()
; template <class Epi, class Ptrs>
; __device__ __forceinline__ void gemm_phase(LAS unsigned char* lds, const int K, const StaticOrder& S, const Ptrs& P, const Epi& E) {
;     ...
;         const char* nA = cA; const char* nB = cB; if (has_next) P.get(nxt, nA, nB);
;         for (int t = 0; t < nt; t += 2) {
;             const bool last = (t == nt - 2);
;             const char* a1 = cA + (size_t)(t + 1) * kstep;
;             const char* a2 = last ? nA : cA + (size_t)(t + 2) * kstep; const char* b2 = last ? nB : cB + (size_t)(t + 2) * kstep;
;             const char* a3 = a2 + kstep; const char* b3 = b2 + kstep;
;             PG8_LDB(B0, 0, 0); PG8_SCHED; PG8_LDA(At, 0, 0); PG8_STAGE(PG8_SA(1, 1), a1 + hstep, voffA);
;             PG8_WAIT_L(8); PG8_BAR; PG8_WAIT_L(0); PG8_MMA(0, 0, At, B0); PG8_BAR; PG8_SCHED;
;             PG8_LDB(B1, 0, 1); PG8_STAGE(PG8_SB(0, 0), b2, voffB);
;             PG8_BAR; PG8_WAIT_L(0); PG8_MMA(0, 1, At, B1); PG8_BAR;
;             PG8_LDA(At, 0, 1); PG8_STAGE(PG8_SA(0, 0), a2, voffA);
;             PG8_BAR; PG8_WAIT_L(0); PG8_MMA(1, 0, At, B0); PG8_BAR; PG8_SCHED;
;             PG8_STAGE(PG8_SB(0, 1), b2 + hstep, voffB);
;             PG8_WAIT_V(6); PG8_BAR; PG8_MMA(1, 1, At, B1); PG8_BAR;
;             PG8_LDB(B0, 1, 0); PG8_SCHED; PG8_LDA(At, 1, 0); PG8_STAGE(PG8_SA(0, 1), a2 + hstep, voffA);
;             PG8_WAIT_L(8); PG8_BAR; PG8_WAIT_L(0); PG8_MMA(0, 0, At, B0); PG8_BAR; PG8_SCHED;
.LBB0_521:
	s_add_u32 s20, s20, 0x100080
	s_addc_u32 s21, s21, 0
	s_add_u32 s11, s22, 0x100
	s_addc_u32 s13, s23, 0
	s_mov_b32 s46, -2
	v_add_u32_e32 v252, 0x18000, v187
	v_add_u32_e32 v253, 0x1c000, v187
	ds_read_b128 v[128:131], v193
	ds_read_b128 v[132:135], v193 offset:1024
	ds_read_b128 v[136:139], v193 offset:2048
	ds_read_b128 v[140:143], v193 offset:3072
	s_add_u32 s22, s20, 0xfff00080
	s_addc_u32 s23, s21, -1
	s_cmp_eq_u32 s46, 60
	s_cselect_b32 s25, s5, s23
	s_cselect_b32 s24, s4, s22
	s_cselect_b32 s23, s15, s13
	s_cselect_b32 s22, s14, s11
	s_add_i32 m0, s17, 0xc000
	ds_read_b128 v[144:147], v194
	ds_read_b128 v[148:151], v194 offset:1024
	ds_read_b128 v[152:155], v194 offset:2048
	ds_read_b128 v[156:159], v194 offset:3072
	ds_read_b128 v[176:179], v194 offset:4096
	ds_read_b128 v[180:183], v194 offset:5120
	ds_read_b128 v[196:199], v194 offset:6144
	ds_read_b128 v[200:203], v194 offset:7168
	global_load_lds_dwordx4 v168, s[20:21]
	s_add_i32 m0, s17, 0xe000
	s_nop 0
	global_load_lds_dwordx4 v170, s[20:21]
	s_waitcnt lgkmcnt(8)
	s_barrier
	s_waitcnt lgkmcnt(0)
	v_mfma_f32_16x16x32_bf16 v[124:127], v[128:131], v[144:147], 0
	v_mfma_f32_16x16x32_bf16 v[120:123], v[136:139], v[144:147], 0
	v_mfma_f32_16x16x32_bf16 v[104:107], v[136:139], v[152:155], 0
	v_mfma_f32_16x16x32_bf16 v[112:115], v[128:131], v[152:155], 0
	v_mfma_f32_16x16x32_bf16 v[92:95], v[128:131], v[176:179], 0
	v_mfma_f32_16x16x32_bf16 v[88:91], v[136:139], v[176:179], 0
	v_mfma_f32_16x16x32_bf16 v[72:75], v[136:139], v[196:199], 0
	v_mfma_f32_16x16x32_bf16 v[76:79], v[128:131], v[196:199], 0
	v_mfma_f32_16x16x32_bf16 v[124:127], v[132:135], v[148:151], v[124:127]
	v_mfma_f32_16x16x32_bf16 v[120:123], v[140:143], v[148:151], v[120:123]
	v_mfma_f32_16x16x32_bf16 v[104:107], v[140:143], v[156:159], v[104:107]
	v_mfma_f32_16x16x32_bf16 v[112:115], v[132:135], v[156:159], v[112:115]
	v_mfma_f32_16x16x32_bf16 v[92:95], v[132:135], v[180:183], v[92:95]
	v_mfma_f32_16x16x32_bf16 v[88:91], v[140:143], v[180:183], v[88:91]
	v_mfma_f32_16x16x32_bf16 v[72:75], v[140:143], v[200:203], v[72:75]
	v_mfma_f32_16x16x32_bf16 v[76:79], v[132:135], v[200:203], v[76:79]
	s_barrier
	s_add_i32 s47, s42, s34
	s_add_u32 s90, s22, 0x80
	s_addc_u32 s91, s23, 0
	s_mov_b32 m0, s47
	ds_read_b128 v[204:207], v195
	ds_read_b128 v[208:211], v195 offset:1024
	ds_read_b128 v[212:215], v195 offset:2048
	ds_read_b128 v[216:219], v195 offset:3072
	global_load_lds_dwordx4 v162, s[22:23]
	s_add_i32 m0, s47, 0x2000
	s_nop 0
	global_load_lds_dwordx4 v166, s[22:23]
	s_barrier
	s_waitcnt lgkmcnt(0)
	v_mfma_f32_16x16x32_bf16 v[116:119], v[204:207], v[144:147], 0
	v_mfma_f32_16x16x32_bf16 v[108:111], v[212:215], v[144:147], 0
	v_mfma_f32_16x16x32_bf16 v[96:99], v[212:215], v[152:155], 0
	v_mfma_f32_16x16x32_bf16 v[100:103], v[204:207], v[152:155], 0
	v_mfma_f32_16x16x32_bf16 v[84:87], v[204:207], v[176:179], 0
	v_mfma_f32_16x16x32_bf16 v[80:83], v[212:215], v[176:179], 0
	v_mfma_f32_16x16x32_bf16 v[64:67], v[212:215], v[196:199], 0
	v_mfma_f32_16x16x32_bf16 v[68:71], v[204:207], v[196:199], 0
	v_mfma_f32_16x16x32_bf16 v[116:119], v[208:211], v[148:151], v[116:119]
	v_mfma_f32_16x16x32_bf16 v[108:111], v[216:219], v[148:151], v[108:111]
	v_mfma_f32_16x16x32_bf16 v[96:99], v[216:219], v[156:159], v[96:99]
	v_mfma_f32_16x16x32_bf16 v[100:103], v[208:211], v[156:159], v[100:103]
	v_mfma_f32_16x16x32_bf16 v[84:87], v[208:211], v[180:183], v[84:87]
	v_mfma_f32_16x16x32_bf16 v[80:83], v[216:219], v[180:183], v[80:83]
	v_mfma_f32_16x16x32_bf16 v[64:67], v[216:219], v[200:203], v[64:67]
	v_mfma_f32_16x16x32_bf16 v[68:71], v[208:211], v[200:203], v[68:71]
	s_barrier
	s_mov_b32 m0, s17
	s_add_u32 s92, s24, 0x80
	s_addc_u32 s93, s25, 0
	ds_read_b128 v[144:147], v194 offset:16384
	ds_read_b128 v[148:151], v194 offset:17408
	ds_read_b128 v[152:155], v194 offset:18432
	ds_read_b128 v[156:159], v194 offset:19456
	ds_read_b128 v[176:179], v194 offset:20480
	ds_read_b128 v[180:183], v194 offset:21504
	ds_read_b128 v[196:199], v194 offset:22528
	ds_read_b128 v[200:203], v194 offset:23552
	global_load_lds_dwordx4 v160, s[24:25]
	s_mov_b32 m0, s19
	s_nop 0
	global_load_lds_dwordx4 v164, s[24:25]
	s_barrier
	s_waitcnt lgkmcnt(0)
	v_mfma_f32_16x16x32_bf16 v[60:63], v[128:131], v[144:147], 0
	v_mfma_f32_16x16x32_bf16 v[56:59], v[136:139], v[144:147], 0
	v_mfma_f32_16x16x32_bf16 v[40:43], v[136:139], v[152:155], 0
	v_mfma_f32_16x16x32_bf16 v[48:51], v[128:131], v[152:155], 0
	v_mfma_f32_16x16x32_bf16 v[32:35], v[128:131], v[176:179], 0
	v_mfma_f32_16x16x32_bf16 v[24:27], v[136:139], v[176:179], 0
	v_mfma_f32_16x16x32_bf16 v[8:11], v[136:139], v[196:199], 0
	v_mfma_f32_16x16x32_bf16 v[16:19], v[128:131], v[196:199], 0
	v_mfma_f32_16x16x32_bf16 v[60:63], v[132:135], v[148:151], v[60:63]
	v_mfma_f32_16x16x32_bf16 v[56:59], v[140:143], v[148:151], v[56:59]
	v_mfma_f32_16x16x32_bf16 v[40:43], v[140:143], v[156:159], v[40:43]
	v_mfma_f32_16x16x32_bf16 v[48:51], v[132:135], v[156:159], v[48:51]
	v_mfma_f32_16x16x32_bf16 v[32:35], v[132:135], v[180:183], v[32:35]
	v_mfma_f32_16x16x32_bf16 v[24:27], v[140:143], v[180:183], v[24:27]
	v_mfma_f32_16x16x32_bf16 v[8:11], v[140:143], v[200:203], v[8:11]
	v_mfma_f32_16x16x32_bf16 v[16:19], v[132:135], v[200:203], v[16:19]
	s_barrier
	s_add_u32 s48, s22, 0x100000
	s_addc_u32 s49, s23, 0
	s_add_i32 s47, s43, s34
	s_mov_b32 m0, s47
	s_nop 0
	global_load_lds_dwordx4 v162, s[48:49]
	s_add_i32 m0, s47, 0x2000
	s_nop 0
	global_load_lds_dwordx4 v166, s[48:49]
	s_waitcnt vmcnt(6)
	s_barrier
; #define PG8_STAGE(bufoff, gbase, voff) do { _Pragma("unroll") for (int _i = 0; _i < 2; ++_i) \
;         __builtin_amdgcn_global_load_lds((const unsigned*)((const char*)(gbase) + (voff)[_i]), (LAS unsigned*)(lds + (bufoff) + ldsw + _i * 8192), 16, 0, 0); } while (0)
; #define PG8_LDA(dst, b, h) do { _Pragma("unroll") for (int m = 0; m < 4; ++m) _Pragma("unroll") for (int k = 0; k < 2; ++k) dst[m][k] = *(const LAS bf16x8*)(lds + PG8_SA(b, h) + aoff + m * 2048 + k * 1024); } while (0)
; #define PG8_LDB(dst, b, h) do { _Pragma("unroll") for (int n = 0; n < 2; ++n) _Pragma("unroll") for (int k = 0; k < 2; ++k) dst[n][k] = *(const LAS bf16x8*)(lds + PG8_SB(b, h) + boff + n * 2048 + k * 1024); } while (0)
; #define PG8_MMA(ai, bj, At, Bt) do { __builtin_amdgcn_s_setprio(1); _Pragma("unroll") for (int m = 0; m < 4; ++m) _Pragma("unroll") for (int n = 0; n < 2; ++n) _Pragma("unroll") for (int k = 0; k < 2; ++k) \
;         acc[ai][bj][m][n] = __builtin_amdgcn_mfma_f32_16x16x32_bf16(Bt[n][k], At[m][k], acc[ai][bj][m][n], 0, 0, 0); __builtin_amdgcn_s_setprio(0); } while (0)
; #define PG8_WAIT_V(n) asm volatile("s_waitcnt vmcnt(" #n ")" ::: "memory")
; #define PG8_WAIT_L(n) asm volatile("s_waitcnt lgkmcnt(" #n ")" ::: "memory")
; #define PG8_BAR __builtin_amdgcn_s_barrier()
; #define PG8_SCHED __builtin_amdgcn_sched_barrier(0)
; template <class Epi, class Ptrs>
; __device__ __forceinline__ void gemm_phase(LAS unsigned char* lds, const int K, const StaticOrder& S, const Ptrs& P, const Epi& E) {
;     ...
;             PG8_WAIT_V(6); PG8_BAR; PG8_MMA(1, 1, At, B1); PG8_BAR;
;             PG8_LDB(B0, 1, 0); PG8_SCHED; PG8_LDA(At, 1, 0); PG8_STAGE(PG8_SA(0, 1), a2 + hstep, voffA);
;             PG8_WAIT_L(8); PG8_BAR; PG8_WAIT_L(0); PG8_MMA(0, 0, At, B0); PG8_BAR; PG8_SCHED;
;             PG8_LDB(B1, 1, 1); PG8_STAGE(PG8_SB(1, 0), b3, voffB);
;             PG8_BAR; PG8_WAIT_L(0); PG8_MMA(0, 1, At, B1); PG8_BAR;
;             PG8_LDA(At, 1, 1); PG8_STAGE(PG8_SA(1, 0), a3, voffA);
;             PG8_BAR; PG8_WAIT_L(0); PG8_MMA(1, 0, At, B0); PG8_BAR; PG8_SCHED;
	v_mfma_f32_16x16x32_bf16 v[52:55], v[204:207], v[144:147], 0
	v_mfma_f32_16x16x32_bf16 v[44:47], v[212:215], v[144:147], 0
	v_mfma_f32_16x16x32_bf16 v[28:31], v[212:215], v[152:155], 0
	v_mfma_f32_16x16x32_bf16 v[36:39], v[204:207], v[152:155], 0
	v_mfma_f32_16x16x32_bf16 v[20:23], v[204:207], v[176:179], 0
	v_mfma_f32_16x16x32_bf16 v[12:15], v[212:215], v[176:179], 0
	v_mfma_f32_16x16x32_bf16 v[0:3], v[212:215], v[196:199], 0
	v_mfma_f32_16x16x32_bf16 v[4:7], v[204:207], v[196:199], 0
	v_mfma_f32_16x16x32_bf16 v[52:55], v[208:211], v[148:151], v[52:55]
	v_mfma_f32_16x16x32_bf16 v[44:47], v[216:219], v[148:151], v[44:47]
	v_mfma_f32_16x16x32_bf16 v[28:31], v[216:219], v[156:159], v[28:31]
	v_mfma_f32_16x16x32_bf16 v[36:39], v[208:211], v[156:159], v[36:39]
	v_mfma_f32_16x16x32_bf16 v[20:23], v[208:211], v[180:183], v[20:23]
	v_mfma_f32_16x16x32_bf16 v[12:15], v[216:219], v[180:183], v[12:15]
	v_mfma_f32_16x16x32_bf16 v[0:3], v[216:219], v[200:203], v[0:3]
	v_mfma_f32_16x16x32_bf16 v[4:7], v[208:211], v[200:203], v[4:7]
	s_barrier
	s_add_i32 s47, 0, 0x18000
	ds_read_b128 v[128:131], v252
	ds_read_b128 v[132:135], v252 offset:1024
	ds_read_b128 v[136:139], v252 offset:2048
	ds_read_b128 v[140:143], v252 offset:3072
	s_add_u32 s24, s24, 0x100000
	s_addc_u32 s25, s25, 0
	s_mov_b32 m0, s40
	ds_read_b128 v[144:147], v194 offset:32768
	ds_read_b128 v[148:151], v194 offset:33792
	ds_read_b128 v[152:155], v194 offset:34816
	ds_read_b128 v[156:159], v194 offset:35840
	ds_read_b128 v[176:179], v194 offset:36864
	ds_read_b128 v[180:183], v194 offset:37888
	ds_read_b128 v[196:199], v194 offset:38912
	ds_read_b128 v[200:203], v194 offset:39936
	global_load_lds_dwordx4 v160, s[24:25]
	s_mov_b32 m0, s41
	s_nop 0
	global_load_lds_dwordx4 v164, s[24:25]
	s_waitcnt lgkmcnt(8)
	s_barrier
	s_waitcnt lgkmcnt(0)
	v_mfma_f32_16x16x32_bf16 v[124:127], v[128:131], v[144:147], v[124:127]
	v_mfma_f32_16x16x32_bf16 v[120:123], v[136:139], v[144:147], v[120:123]
	v_mfma_f32_16x16x32_bf16 v[104:107], v[136:139], v[152:155], v[104:107]
	v_mfma_f32_16x16x32_bf16 v[112:115], v[128:131], v[152:155], v[112:115]
	v_mfma_f32_16x16x32_bf16 v[92:95], v[128:131], v[176:179], v[92:95]
	v_mfma_f32_16x16x32_bf16 v[88:91], v[136:139], v[176:179], v[88:91]
	v_mfma_f32_16x16x32_bf16 v[72:75], v[136:139], v[196:199], v[72:75]
	v_mfma_f32_16x16x32_bf16 v[76:79], v[128:131], v[196:199], v[76:79]
	v_mfma_f32_16x16x32_bf16 v[124:127], v[132:135], v[148:151], v[124:127]
	v_mfma_f32_16x16x32_bf16 v[120:123], v[140:143], v[148:151], v[120:123]
	v_mfma_f32_16x16x32_bf16 v[104:107], v[140:143], v[156:159], v[104:107]
	v_mfma_f32_16x16x32_bf16 v[112:115], v[132:135], v[156:159], v[112:115]
	v_mfma_f32_16x16x32_bf16 v[92:95], v[132:135], v[180:183], v[92:95]
	v_mfma_f32_16x16x32_bf16 v[88:91], v[140:143], v[180:183], v[88:91]
	v_mfma_f32_16x16x32_bf16 v[72:75], v[140:143], v[200:203], v[72:75]
	v_mfma_f32_16x16x32_bf16 v[76:79], v[132:135], v[200:203], v[76:79]
	s_barrier
	s_add_i32 s24, 0, 0x1c000
	s_add_i32 s25, s47, s34
	s_mov_b32 m0, s25
	ds_read_b128 v[204:207], v253
	ds_read_b128 v[208:211], v253 offset:1024
	ds_read_b128 v[212:215], v253 offset:2048
	ds_read_b128 v[216:219], v253 offset:3072
	global_load_lds_dwordx4 v162, s[90:91]
	s_add_i32 m0, s25, 0x2000
	s_nop 0
	global_load_lds_dwordx4 v166, s[90:91]
	s_barrier
	s_waitcnt lgkmcnt(0)
	v_mfma_f32_16x16x32_bf16 v[116:119], v[204:207], v[144:147], v[116:119]
	v_mfma_f32_16x16x32_bf16 v[108:111], v[212:215], v[144:147], v[108:111]
	v_mfma_f32_16x16x32_bf16 v[96:99], v[212:215], v[152:155], v[96:99]
	v_mfma_f32_16x16x32_bf16 v[100:103], v[204:207], v[152:155], v[100:103]
	v_mfma_f32_16x16x32_bf16 v[84:87], v[204:207], v[176:179], v[84:87]
	v_mfma_f32_16x16x32_bf16 v[80:83], v[212:215], v[176:179], v[80:83]
	v_mfma_f32_16x16x32_bf16 v[64:67], v[212:215], v[196:199], v[64:67]
	v_mfma_f32_16x16x32_bf16 v[68:71], v[204:207], v[196:199], v[68:71]
	v_mfma_f32_16x16x32_bf16 v[116:119], v[208:211], v[148:151], v[116:119]
	v_mfma_f32_16x16x32_bf16 v[108:111], v[216:219], v[148:151], v[108:111]
	v_mfma_f32_16x16x32_bf16 v[96:99], v[216:219], v[156:159], v[96:99]
	v_mfma_f32_16x16x32_bf16 v[100:103], v[208:211], v[156:159], v[100:103]
	v_mfma_f32_16x16x32_bf16 v[84:87], v[208:211], v[180:183], v[84:87]
	v_mfma_f32_16x16x32_bf16 v[80:83], v[216:219], v[180:183], v[80:83]
	v_mfma_f32_16x16x32_bf16 v[64:67], v[216:219], v[200:203], v[64:67]
	v_mfma_f32_16x16x32_bf16 v[68:71], v[208:211], v[200:203], v[68:71]
	s_barrier
	s_mov_b32 m0, s28
	ds_read_b128 v[144:147], v194 offset:49152
	ds_read_b128 v[148:151], v194 offset:50176
	ds_read_b128 v[152:155], v194 offset:51200
	ds_read_b128 v[156:159], v194 offset:52224
	ds_read_b128 v[176:179], v194 offset:53248
	ds_read_b128 v[180:183], v194 offset:54272
	ds_read_b128 v[196:199], v194 offset:55296
	ds_read_b128 v[200:203], v194 offset:56320
	global_load_lds_dwordx4 v160, s[92:93]
	s_mov_b32 m0, s29
	s_nop 0
	global_load_lds_dwordx4 v164, s[92:93]
	s_barrier
	s_waitcnt lgkmcnt(0)
	v_mfma_f32_16x16x32_bf16 v[60:63], v[128:131], v[144:147], v[60:63]
	v_mfma_f32_16x16x32_bf16 v[56:59], v[136:139], v[144:147], v[56:59]
	v_mfma_f32_16x16x32_bf16 v[40:43], v[136:139], v[152:155], v[40:43]
	v_mfma_f32_16x16x32_bf16 v[48:51], v[128:131], v[152:155], v[48:51]
	v_mfma_f32_16x16x32_bf16 v[32:35], v[128:131], v[176:179], v[32:35]
	v_mfma_f32_16x16x32_bf16 v[24:27], v[136:139], v[176:179], v[24:27]
	v_mfma_f32_16x16x32_bf16 v[8:11], v[136:139], v[196:199], v[8:11]
	v_mfma_f32_16x16x32_bf16 v[16:19], v[128:131], v[196:199], v[16:19]
	v_mfma_f32_16x16x32_bf16 v[60:63], v[132:135], v[148:151], v[60:63]
	v_mfma_f32_16x16x32_bf16 v[56:59], v[140:143], v[148:151], v[56:59]
	v_mfma_f32_16x16x32_bf16 v[40:43], v[140:143], v[156:159], v[40:43]
	v_mfma_f32_16x16x32_bf16 v[48:51], v[132:135], v[156:159], v[48:51]
	v_mfma_f32_16x16x32_bf16 v[32:35], v[132:135], v[180:183], v[32:35]
	v_mfma_f32_16x16x32_bf16 v[24:27], v[140:143], v[180:183], v[24:27]
	v_mfma_f32_16x16x32_bf16 v[8:11], v[140:143], v[200:203], v[8:11]
	v_mfma_f32_16x16x32_bf16 v[16:19], v[132:135], v[200:203], v[16:19]
	s_barrier
; #define PG8_STAGE(bufoff, gbase, voff) do { _Pragma("unroll") for (int _i = 0; _i < 2; ++_i) \
;         __builtin_amdgcn_global_load_lds((const unsigned*)((const char*)(gbase) + (voff)[_i]), (LAS unsigned*)(lds + (bufoff) + ldsw + _i * 8192), 16, 0, 0); } while (0)
; #define PG8_LDA(dst, b, h) do { _Pragma("unroll") for (int m = 0; m < 4; ++m) _Pragma("unroll") for (int k = 0; k < 2; ++k) dst[m][k] = *(const LAS bf16x8*)(lds + PG8_SA(b, h) + aoff + m * 2048 + k * 1024); } while (0)
; #define PG8_LDB(dst, b, h) do { _Pragma("unroll") for (int n = 0; n < 2; ++n) _Pragma("unroll") for (int k = 0; k < 2; ++k) dst[n][k] = *(const LAS bf16x8*)(lds + PG8_SB(b, h) + boff + n * 2048 + k * 1024); } while (0)
; #define PG8_WAIT_V(n) asm volatile("s_waitcnt vmcnt(" #n ")" ::: "memory")
; #define PG8_WAIT_L(n) asm volatile("s_waitcnt lgkmcnt(" #n ")" ::: "memory")
; #define PG8_BAR __builtin_amdgcn_s_barrier()
; #define PG8_SCHED __builtin_amdgcn_sched_barrier(0)
; template <class Epi, class Ptrs>
; __device__ __forceinline__ void gemm_phase(LAS unsigned char* lds, const int K, const StaticOrder& S, const Ptrs& P, const Epi& E) {
;     ...
;             PG8_LDB(B0, 0, 0); PG8_SCHED; PG8_LDA(At, 0, 0); PG8_STAGE(PG8_SA(1, 1), a1 + hstep, voffA);
;             PG8_WAIT_L(8); PG8_BAR; PG8_WAIT_L(0); PG8_MMA(0, 0, At, B0); PG8_BAR; PG8_SCHED;
;             PG8_LDB(B1, 0, 1); PG8_STAGE(PG8_SB(0, 0), b2, voffB);
;             PG8_BAR; PG8_WAIT_L(0); PG8_MMA(0, 1, At, B1); PG8_BAR;
;             PG8_LDA(At, 0, 1); PG8_STAGE(PG8_SA(0, 0), a2, voffA);
;             PG8_BAR; PG8_WAIT_L(0); PG8_MMA(1, 0, At, B0); PG8_BAR; PG8_SCHED;
;             PG8_STAGE(PG8_SB(0, 1), b2 + hstep, voffB);
;             PG8_WAIT_V(6); PG8_BAR; PG8_MMA(1, 1, At, B1); PG8_BAR;
;             PG8_LDB(B0, 1, 0); PG8_SCHED; PG8_LDA(At, 1, 0); PG8_STAGE(PG8_SA(0, 1), a2 + hstep, voffA);
;             PG8_WAIT_L(8); PG8_BAR; PG8_WAIT_L(0); PG8_MMA(0, 0, At, B0); PG8_BAR; PG8_SCHED;
;             PG8_LDB(B1, 1, 1); PG8_STAGE(PG8_SB(1, 0), b3, voffB);
;             PG8_BAR; PG8_WAIT_L(0); PG8_MMA(0, 1, At, B1); PG8_BAR;
;             PG8_LDA(At, 1, 1); PG8_STAGE(PG8_SA(1, 0), a3, voffA);
;             PG8_BAR; PG8_WAIT_L(0); PG8_MMA(1, 0, At, B0); PG8_BAR; PG8_SCHED;
;             PG8_STAGE(PG8_SB(1, 1), b3 + hstep, voffB);
;             PG8_WAIT_V(6); PG8_BAR; PG8_MMA(1, 1, At, B1); PG8_BAR;
	s_add_u32 s22, s22, 0x100080
	s_addc_u32 s23, s23, 0
	s_add_i32 s24, s24, s34
	s_mov_b32 m0, s24
	s_nop 0
	global_load_lds_dwordx4 v162, s[22:23]
	s_add_i32 m0, s24, 0x2000
	s_nop 0
	global_load_lds_dwordx4 v166, s[22:23]
	s_waitcnt vmcnt(6)
	s_barrier
	v_mfma_f32_16x16x32_bf16 v[52:55], v[204:207], v[144:147], v[52:55]
	v_mfma_f32_16x16x32_bf16 v[44:47], v[212:215], v[144:147], v[44:47]
	v_mfma_f32_16x16x32_bf16 v[28:31], v[212:215], v[152:155], v[28:31]
	v_mfma_f32_16x16x32_bf16 v[36:39], v[204:207], v[152:155], v[36:39]
	v_mfma_f32_16x16x32_bf16 v[20:23], v[204:207], v[176:179], v[20:23]
	v_mfma_f32_16x16x32_bf16 v[12:15], v[212:215], v[176:179], v[12:15]
	v_mfma_f32_16x16x32_bf16 v[0:3], v[212:215], v[196:199], v[0:3]
	v_mfma_f32_16x16x32_bf16 v[4:7], v[204:207], v[196:199], v[4:7]
	v_mfma_f32_16x16x32_bf16 v[52:55], v[208:211], v[148:151], v[52:55]
	v_mfma_f32_16x16x32_bf16 v[44:47], v[216:219], v[148:151], v[44:47]
	v_mfma_f32_16x16x32_bf16 v[28:31], v[216:219], v[156:159], v[28:31]
	v_mfma_f32_16x16x32_bf16 v[36:39], v[208:211], v[156:159], v[36:39]
	v_mfma_f32_16x16x32_bf16 v[20:23], v[208:211], v[180:183], v[20:23]
	v_mfma_f32_16x16x32_bf16 v[12:15], v[216:219], v[180:183], v[12:15]
	v_mfma_f32_16x16x32_bf16 v[0:3], v[216:219], v[200:203], v[0:3]
	v_mfma_f32_16x16x32_bf16 v[4:7], v[208:211], v[200:203], v[4:7]
	s_barrier
	s_add_i32 s46, s46, 2
	s_add_u32 s20, s20, 0x100
	s_addc_u32 s21, s21, 0
	s_add_u32 s11, s11, 0x100
	s_addc_u32 s13, s13, 0
	s_cmp_gt_u32 s46, 61
.LBB0_522:
	ds_read_b128 v[128:131], v193
	ds_read_b128 v[132:135], v193 offset:1024
	ds_read_b128 v[136:139], v193 offset:2048
	ds_read_b128 v[140:143], v193 offset:3072
	s_add_u32 s22, s20, 0xfff00080
	s_addc_u32 s23, s21, -1
	s_cmp_eq_u32 s46, 60
	s_cselect_b32 s25, s5, s23
	s_cselect_b32 s24, s4, s22
	s_cselect_b32 s23, s15, s13
	s_cselect_b32 s22, s14, s11
	s_add_i32 m0, s17, 0xc000
	ds_read_b128 v[144:147], v194
	ds_read_b128 v[148:151], v194 offset:1024
	ds_read_b128 v[152:155], v194 offset:2048
	ds_read_b128 v[156:159], v194 offset:3072
	ds_read_b128 v[176:179], v194 offset:4096
	ds_read_b128 v[180:183], v194 offset:5120
	ds_read_b128 v[196:199], v194 offset:6144
	ds_read_b128 v[200:203], v194 offset:7168
	global_load_lds_dwordx4 v168, s[20:21]
	s_add_i32 m0, s17, 0xe000
	s_nop 0
	global_load_lds_dwordx4 v170, s[20:21]
	s_waitcnt lgkmcnt(8)
	s_barrier
	s_waitcnt lgkmcnt(0)
	v_mfma_f32_16x16x32_bf16 v[124:127], v[128:131], v[144:147], v[124:127]
	v_mfma_f32_16x16x32_bf16 v[120:123], v[136:139], v[144:147], v[120:123]
	v_mfma_f32_16x16x32_bf16 v[104:107], v[136:139], v[152:155], v[104:107]
	v_mfma_f32_16x16x32_bf16 v[112:115], v[128:131], v[152:155], v[112:115]
	v_mfma_f32_16x16x32_bf16 v[92:95], v[128:131], v[176:179], v[92:95]
	v_mfma_f32_16x16x32_bf16 v[88:91], v[136:139], v[176:179], v[88:91]
	v_mfma_f32_16x16x32_bf16 v[72:75], v[136:139], v[196:199], v[72:75]
	v_mfma_f32_16x16x32_bf16 v[76:79], v[128:131], v[196:199], v[76:79]
	v_mfma_f32_16x16x32_bf16 v[124:127], v[132:135], v[148:151], v[124:127]
	v_mfma_f32_16x16x32_bf16 v[120:123], v[140:143], v[148:151], v[120:123]
	v_mfma_f32_16x16x32_bf16 v[104:107], v[140:143], v[156:159], v[104:107]
	v_mfma_f32_16x16x32_bf16 v[112:115], v[132:135], v[156:159], v[112:115]
	v_mfma_f32_16x16x32_bf16 v[92:95], v[132:135], v[180:183], v[92:95]
	v_mfma_f32_16x16x32_bf16 v[88:91], v[140:143], v[180:183], v[88:91]
	v_mfma_f32_16x16x32_bf16 v[72:75], v[140:143], v[200:203], v[72:75]
	v_mfma_f32_16x16x32_bf16 v[76:79], v[132:135], v[200:203], v[76:79]
	s_barrier
	s_add_i32 s47, s42, s34
	s_add_u32 s90, s22, 0x80
	s_addc_u32 s91, s23, 0
	s_mov_b32 m0, s47
	ds_read_b128 v[204:207], v195
	ds_read_b128 v[208:211], v195 offset:1024
	ds_read_b128 v[212:215], v195 offset:2048
	ds_read_b128 v[216:219], v195 offset:3072
	global_load_lds_dwordx4 v162, s[22:23]
	s_add_i32 m0, s47, 0x2000
	s_nop 0
	global_load_lds_dwordx4 v166, s[22:23]
	s_barrier
	s_waitcnt lgkmcnt(0)
	v_mfma_f32_16x16x32_bf16 v[116:119], v[204:207], v[144:147], v[116:119]
	v_mfma_f32_16x16x32_bf16 v[108:111], v[212:215], v[144:147], v[108:111]
	v_mfma_f32_16x16x32_bf16 v[96:99], v[212:215], v[152:155], v[96:99]
	v_mfma_f32_16x16x32_bf16 v[100:103], v[204:207], v[152:155], v[100:103]
	v_mfma_f32_16x16x32_bf16 v[84:87], v[204:207], v[176:179], v[84:87]
	v_mfma_f32_16x16x32_bf16 v[80:83], v[212:215], v[176:179], v[80:83]
	v_mfma_f32_16x16x32_bf16 v[64:67], v[212:215], v[196:199], v[64:67]
	v_mfma_f32_16x16x32_bf16 v[68:71], v[204:207], v[196:199], v[68:71]
	v_mfma_f32_16x16x32_bf16 v[116:119], v[208:211], v[148:151], v[116:119]
	v_mfma_f32_16x16x32_bf16 v[108:111], v[216:219], v[148:151], v[108:111]
	v_mfma_f32_16x16x32_bf16 v[96:99], v[216:219], v[156:159], v[96:99]
	v_mfma_f32_16x16x32_bf16 v[100:103], v[208:211], v[156:159], v[100:103]
	v_mfma_f32_16x16x32_bf16 v[84:87], v[208:211], v[180:183], v[84:87]
	v_mfma_f32_16x16x32_bf16 v[80:83], v[216:219], v[180:183], v[80:83]
	v_mfma_f32_16x16x32_bf16 v[64:67], v[216:219], v[200:203], v[64:67]
	v_mfma_f32_16x16x32_bf16 v[68:71], v[208:211], v[200:203], v[68:71]
	s_barrier
	s_mov_b32 m0, s17
	s_add_u32 s92, s24, 0x80
	s_addc_u32 s93, s25, 0
	ds_read_b128 v[144:147], v194 offset:16384
	ds_read_b128 v[148:151], v194 offset:17408
	ds_read_b128 v[152:155], v194 offset:18432
	ds_read_b128 v[156:159], v194 offset:19456
	ds_read_b128 v[176:179], v194 offset:20480
	ds_read_b128 v[180:183], v194 offset:21504
	ds_read_b128 v[196:199], v194 offset:22528
	ds_read_b128 v[200:203], v194 offset:23552
	global_load_lds_dwordx4 v160, s[24:25]
	s_mov_b32 m0, s19
	s_nop 0
	global_load_lds_dwordx4 v164, s[24:25]
	s_barrier
; #define PG8_STAGE(bufoff, gbase, voff) do { _Pragma("unroll") for (int _i = 0; _i < 2; ++_i) \
;         __builtin_amdgcn_global_load_lds((const unsigned*)((const char*)(gbase) + (voff)[_i]), (LAS unsigned*)(lds + (bufoff) + ldsw + _i * 8192), 16, 0, 0); } while (0)
; #define PG8_LDA(dst, b, h) do { _Pragma("unroll") for (int m = 0; m < 4; ++m) _Pragma("unroll") for (int k = 0; k < 2; ++k) dst[m][k] = *(const LAS bf16x8*)(lds + PG8_SA(b, h) + aoff + m * 2048 + k * 1024); } while (0)
; #define PG8_LDB(dst, b, h) do { _Pragma("unroll") for (int n = 0; n < 2; ++n) _Pragma("unroll") for (int k = 0; k < 2; ++k) dst[n][k] = *(const LAS bf16x8*)(lds + PG8_SB(b, h) + boff + n * 2048 + k * 1024); } while (0)
; #define PG8_MMA(ai, bj, At, Bt) do { __builtin_amdgcn_s_setprio(1); _Pragma("unroll") for (int m = 0; m < 4; ++m) _Pragma("unroll") for (int n = 0; n < 2; ++n) _Pragma("unroll") for (int k = 0; k < 2; ++k) \
;         acc[ai][bj][m][n] = __builtin_amdgcn_mfma_f32_16x16x32_bf16(Bt[n][k], At[m][k], acc[ai][bj][m][n], 0, 0, 0); __builtin_amdgcn_s_setprio(0); } while (0)
; #define PG8_WAIT_V(n) asm volatile("s_waitcnt vmcnt(" #n ")" ::: "memory")
; #define PG8_WAIT_L(n) asm volatile("s_waitcnt lgkmcnt(" #n ")" ::: "memory")
; #define PG8_BAR __builtin_amdgcn_s_barrier()
; #define PG8_SCHED __builtin_amdgcn_sched_barrier(0)
; template <class Epi, class Ptrs>
; __device__ __forceinline__ void gemm_phase(LAS unsigned char* lds, const int K, const StaticOrder& S, const Ptrs& P, const Epi& E) {
;     ...
;             PG8_BAR; PG8_WAIT_L(0); PG8_MMA(1, 0, At, B0); PG8_BAR; PG8_SCHED;
;             PG8_STAGE(PG8_SB(0, 1), b2 + hstep, voffB);
;             PG8_WAIT_V(6); PG8_BAR; PG8_MMA(1, 1, At, B1); PG8_BAR;
;             PG8_LDB(B0, 1, 0); PG8_SCHED; PG8_LDA(At, 1, 0); PG8_STAGE(PG8_SA(0, 1), a2 + hstep, voffA);
;             PG8_WAIT_L(8); PG8_BAR; PG8_WAIT_L(0); PG8_MMA(0, 0, At, B0); PG8_BAR; PG8_SCHED;
;             PG8_LDB(B1, 1, 1); PG8_STAGE(PG8_SB(1, 0), b3, voffB);
;             PG8_BAR; PG8_WAIT_L(0); PG8_MMA(0, 1, At, B1); PG8_BAR;
	s_waitcnt lgkmcnt(0)
	v_mfma_f32_16x16x32_bf16 v[60:63], v[128:131], v[144:147], v[60:63]
	v_mfma_f32_16x16x32_bf16 v[56:59], v[136:139], v[144:147], v[56:59]
	v_mfma_f32_16x16x32_bf16 v[40:43], v[136:139], v[152:155], v[40:43]
	v_mfma_f32_16x16x32_bf16 v[48:51], v[128:131], v[152:155], v[48:51]
	v_mfma_f32_16x16x32_bf16 v[32:35], v[128:131], v[176:179], v[32:35]
	v_mfma_f32_16x16x32_bf16 v[24:27], v[136:139], v[176:179], v[24:27]
	v_mfma_f32_16x16x32_bf16 v[8:11], v[136:139], v[196:199], v[8:11]
	v_mfma_f32_16x16x32_bf16 v[16:19], v[128:131], v[196:199], v[16:19]
	v_mfma_f32_16x16x32_bf16 v[60:63], v[132:135], v[148:151], v[60:63]
	v_mfma_f32_16x16x32_bf16 v[56:59], v[140:143], v[148:151], v[56:59]
	v_mfma_f32_16x16x32_bf16 v[40:43], v[140:143], v[156:159], v[40:43]
	v_mfma_f32_16x16x32_bf16 v[48:51], v[132:135], v[156:159], v[48:51]
	v_mfma_f32_16x16x32_bf16 v[32:35], v[132:135], v[180:183], v[32:35]
	v_mfma_f32_16x16x32_bf16 v[24:27], v[140:143], v[180:183], v[24:27]
	v_mfma_f32_16x16x32_bf16 v[8:11], v[140:143], v[200:203], v[8:11]
	v_mfma_f32_16x16x32_bf16 v[16:19], v[132:135], v[200:203], v[16:19]
	s_barrier
	s_add_u32 s48, s22, 0x100000
	s_addc_u32 s49, s23, 0
	s_add_i32 s47, s43, s34
	s_mov_b32 m0, s47
	s_nop 0
	global_load_lds_dwordx4 v162, s[48:49]
	s_add_i32 m0, s47, 0x2000
	s_nop 0
	global_load_lds_dwordx4 v166, s[48:49]
	s_waitcnt vmcnt(6)
	s_barrier
	v_mfma_f32_16x16x32_bf16 v[52:55], v[204:207], v[144:147], v[52:55]
	v_mfma_f32_16x16x32_bf16 v[44:47], v[212:215], v[144:147], v[44:47]
	v_mfma_f32_16x16x32_bf16 v[28:31], v[212:215], v[152:155], v[28:31]
	v_mfma_f32_16x16x32_bf16 v[36:39], v[204:207], v[152:155], v[36:39]
	v_mfma_f32_16x16x32_bf16 v[20:23], v[204:207], v[176:179], v[20:23]
	v_mfma_f32_16x16x32_bf16 v[12:15], v[212:215], v[176:179], v[12:15]
	v_mfma_f32_16x16x32_bf16 v[0:3], v[212:215], v[196:199], v[0:3]
	v_mfma_f32_16x16x32_bf16 v[4:7], v[204:207], v[196:199], v[4:7]
	v_mfma_f32_16x16x32_bf16 v[52:55], v[208:211], v[148:151], v[52:55]
	v_mfma_f32_16x16x32_bf16 v[44:47], v[216:219], v[148:151], v[44:47]
	v_mfma_f32_16x16x32_bf16 v[28:31], v[216:219], v[156:159], v[28:31]
	v_mfma_f32_16x16x32_bf16 v[36:39], v[208:211], v[156:159], v[36:39]
	v_mfma_f32_16x16x32_bf16 v[20:23], v[208:211], v[180:183], v[20:23]
	v_mfma_f32_16x16x32_bf16 v[12:15], v[216:219], v[180:183], v[12:15]
	v_mfma_f32_16x16x32_bf16 v[0:3], v[216:219], v[200:203], v[0:3]
	v_mfma_f32_16x16x32_bf16 v[4:7], v[208:211], v[200:203], v[4:7]
	s_barrier
	s_add_i32 s47, 0, 0x18000
	ds_read_b128 v[128:131], v252
	ds_read_b128 v[132:135], v252 offset:1024
	ds_read_b128 v[136:139], v252 offset:2048
	ds_read_b128 v[140:143], v252 offset:3072
	s_add_u32 s24, s24, 0x100000
	s_addc_u32 s25, s25, 0
	s_mov_b32 m0, s40
	ds_read_b128 v[144:147], v194 offset:32768
	ds_read_b128 v[148:151], v194 offset:33792
	ds_read_b128 v[152:155], v194 offset:34816
	ds_read_b128 v[156:159], v194 offset:35840
	ds_read_b128 v[176:179], v194 offset:36864
	ds_read_b128 v[180:183], v194 offset:37888
	ds_read_b128 v[196:199], v194 offset:38912
	ds_read_b128 v[200:203], v194 offset:39936
	global_load_lds_dwordx4 v160, s[24:25]
	s_mov_b32 m0, s41
	s_nop 0
	global_load_lds_dwordx4 v164, s[24:25]
	s_waitcnt lgkmcnt(8)
	s_barrier
	s_waitcnt lgkmcnt(0)
	v_mfma_f32_16x16x32_bf16 v[124:127], v[128:131], v[144:147], v[124:127]
	v_mfma_f32_16x16x32_bf16 v[120:123], v[136:139], v[144:147], v[120:123]
	v_mfma_f32_16x16x32_bf16 v[104:107], v[136:139], v[152:155], v[104:107]
	v_mfma_f32_16x16x32_bf16 v[112:115], v[128:131], v[152:155], v[112:115]
	v_mfma_f32_16x16x32_bf16 v[92:95], v[128:131], v[176:179], v[92:95]
	v_mfma_f32_16x16x32_bf16 v[88:91], v[136:139], v[176:179], v[88:91]
	v_mfma_f32_16x16x32_bf16 v[72:75], v[136:139], v[196:199], v[72:75]
	v_mfma_f32_16x16x32_bf16 v[76:79], v[128:131], v[196:199], v[76:79]
	v_mfma_f32_16x16x32_bf16 v[124:127], v[132:135], v[148:151], v[124:127]
	v_mfma_f32_16x16x32_bf16 v[120:123], v[140:143], v[148:151], v[120:123]
	v_mfma_f32_16x16x32_bf16 v[104:107], v[140:143], v[156:159], v[104:107]
	v_mfma_f32_16x16x32_bf16 v[112:115], v[132:135], v[156:159], v[112:115]
	v_mfma_f32_16x16x32_bf16 v[92:95], v[132:135], v[180:183], v[92:95]
	v_mfma_f32_16x16x32_bf16 v[88:91], v[140:143], v[180:183], v[88:91]
	v_mfma_f32_16x16x32_bf16 v[72:75], v[140:143], v[200:203], v[72:75]
	v_mfma_f32_16x16x32_bf16 v[76:79], v[132:135], v[200:203], v[76:79]
	s_barrier
	s_add_i32 s24, 0, 0x1c000
	s_add_i32 s25, s47, s34
	s_mov_b32 m0, s25
	ds_read_b128 v[204:207], v253
	ds_read_b128 v[208:211], v253 offset:1024
	ds_read_b128 v[212:215], v253 offset:2048
	ds_read_b128 v[216:219], v253 offset:3072
	global_load_lds_dwordx4 v162, s[90:91]
	s_add_i32 m0, s25, 0x2000
	s_nop 0
	global_load_lds_dwordx4 v166, s[90:91]
	s_barrier
	s_waitcnt lgkmcnt(0)
	v_mfma_f32_16x16x32_bf16 v[116:119], v[204:207], v[144:147], v[116:119]
	v_mfma_f32_16x16x32_bf16 v[108:111], v[212:215], v[144:147], v[108:111]
	v_mfma_f32_16x16x32_bf16 v[96:99], v[212:215], v[152:155], v[96:99]
	v_mfma_f32_16x16x32_bf16 v[100:103], v[204:207], v[152:155], v[100:103]
	v_mfma_f32_16x16x32_bf16 v[84:87], v[204:207], v[176:179], v[84:87]
	v_mfma_f32_16x16x32_bf16 v[80:83], v[212:215], v[176:179], v[80:83]
	v_mfma_f32_16x16x32_bf16 v[64:67], v[212:215], v[196:199], v[64:67]
	v_mfma_f32_16x16x32_bf16 v[68:71], v[204:207], v[196:199], v[68:71]
	v_mfma_f32_16x16x32_bf16 v[116:119], v[208:211], v[148:151], v[116:119]
	v_mfma_f32_16x16x32_bf16 v[108:111], v[216:219], v[148:151], v[108:111]
	v_mfma_f32_16x16x32_bf16 v[96:99], v[216:219], v[156:159], v[96:99]
	v_mfma_f32_16x16x32_bf16 v[100:103], v[208:211], v[156:159], v[100:103]
	v_mfma_f32_16x16x32_bf16 v[84:87], v[208:211], v[180:183], v[84:87]
	v_mfma_f32_16x16x32_bf16 v[80:83], v[216:219], v[180:183], v[80:83]
	v_mfma_f32_16x16x32_bf16 v[64:67], v[216:219], v[200:203], v[64:67]
	v_mfma_f32_16x16x32_bf16 v[68:71], v[208:211], v[200:203], v[68:71]
	s_barrier
; #define PG8_STAGE(bufoff, gbase, voff) do { _Pragma("unroll") for (int _i = 0; _i < 2; ++_i) \
;         __builtin_amdgcn_global_load_lds((const unsigned*)((const char*)(gbase) + (voff)[_i]), (LAS unsigned*)(lds + (bufoff) + ldsw + _i * 8192), 16, 0, 0); } while (0)
; #define PG8_LDA(dst, b, h) do { _Pragma("unroll") for (int m = 0; m < 4; ++m) _Pragma("unroll") for (int k = 0; k < 2; ++k) dst[m][k] = *(const LAS bf16x8*)(lds + PG8_SA(b, h) + aoff + m * 2048 + k * 1024); } while (0)
; #define PG8_MMA(ai, bj, At, Bt) do { __builtin_amdgcn_s_setprio(1); _Pragma("unroll") for (int m = 0; m < 4; ++m) _Pragma("unroll") for (int n = 0; n < 2; ++n) _Pragma("unroll") for (int k = 0; k < 2; ++k) \
;         acc[ai][bj][m][n] = __builtin_amdgcn_mfma_f32_16x16x32_bf16(Bt[n][k], At[m][k], acc[ai][bj][m][n], 0, 0, 0); __builtin_amdgcn_s_setprio(0); } while (0)
; #define PG8_WAIT_V(n) asm volatile("s_waitcnt vmcnt(" #n ")" ::: "memory")
; #define PG8_WAIT_L(n) asm volatile("s_waitcnt lgkmcnt(" #n ")" ::: "memory")
; #define PG8_BAR __builtin_amdgcn_s_barrier()
; #define PG8_SCHED __builtin_amdgcn_sched_barrier(0)
; template <class Epi, class Ptrs>
; __device__ __forceinline__ void gemm_phase(LAS unsigned char* lds, const int K, const StaticOrder& S, const Ptrs& P, const Epi& E) {
;     ...
;             PG8_LDA(At, 1, 1); PG8_STAGE(PG8_SA(1, 0), a3, voffA);
;             PG8_BAR; PG8_WAIT_L(0); PG8_MMA(1, 0, At, B0); PG8_BAR; PG8_SCHED;
;             PG8_STAGE(PG8_SB(1, 1), b3 + hstep, voffB);
;             PG8_WAIT_V(6); PG8_BAR; PG8_MMA(1, 1, At, B1); PG8_BAR;
;     __device__ __forceinline__ void operator()(const f32x4 (&acc)[2][2][4][2], const Unit& u, int ui, int wr, int wc, int fr, int fq) const {
;         const int rl0 = wr * 64 + fr, col0 = u.pn * 256 + wc * 32 + 8 * fq;
;         u32x4 xv[2][4][2];
; #pragma unroll
;         for (int ai = 0; ai < 2; ++ai)
; #pragma unroll
;             for (int m = 0; m < 4; ++m)
; #pragma unroll
;                 for (int bj = 0; bj < 2; ++bj) xv[ai][m][bj] = *(const u32x4*)(xb + (size_t)(u.pm * 256 + rl0 + ai * 128 + m * 16) * DM + col0 + bj * 128);
; #pragma unroll
;         for (int ai = 0; ai < 2; ++ai)
; #pragma unroll
;             for (int m = 0; m < 4; ++m) { const int rl = rl0 + ai * 128 + m * 16; float* rowp = out + (size_t)(u.pm * 256 + rl) * DM + col0;
;                 const float r2 = tab[ui * 256 + rl];
	s_mov_b32 m0, s28
	ds_read_b128 v[144:147], v194 offset:49152
	ds_read_b128 v[148:151], v194 offset:50176
	ds_read_b128 v[152:155], v194 offset:51200
	ds_read_b128 v[156:159], v194 offset:52224
	ds_read_b128 v[176:179], v194 offset:53248
	ds_read_b128 v[180:183], v194 offset:54272
	ds_read_b128 v[196:199], v194 offset:55296
	ds_read_b128 v[200:203], v194 offset:56320
	global_load_lds_dwordx4 v160, s[92:93]
	s_mov_b32 m0, s29
	s_nop 0
	global_load_lds_dwordx4 v164, s[92:93]
	s_barrier
	s_waitcnt lgkmcnt(0)
	v_mfma_f32_16x16x32_bf16 v[60:63], v[128:131], v[144:147], v[60:63]
	v_mfma_f32_16x16x32_bf16 v[56:59], v[136:139], v[144:147], v[56:59]
	v_mfma_f32_16x16x32_bf16 v[40:43], v[136:139], v[152:155], v[40:43]
	v_mfma_f32_16x16x32_bf16 v[48:51], v[128:131], v[152:155], v[48:51]
	v_mfma_f32_16x16x32_bf16 v[32:35], v[128:131], v[176:179], v[32:35]
	v_mfma_f32_16x16x32_bf16 v[24:27], v[136:139], v[176:179], v[24:27]
	v_mfma_f32_16x16x32_bf16 v[8:11], v[136:139], v[196:199], v[8:11]
	v_mfma_f32_16x16x32_bf16 v[16:19], v[128:131], v[196:199], v[16:19]
	v_mfma_f32_16x16x32_bf16 v[60:63], v[132:135], v[148:151], v[60:63]
	v_mfma_f32_16x16x32_bf16 v[56:59], v[140:143], v[148:151], v[56:59]
	v_mfma_f32_16x16x32_bf16 v[40:43], v[140:143], v[156:159], v[40:43]
	v_mfma_f32_16x16x32_bf16 v[48:51], v[132:135], v[156:159], v[48:51]
	v_mfma_f32_16x16x32_bf16 v[32:35], v[132:135], v[180:183], v[32:35]
	v_mfma_f32_16x16x32_bf16 v[24:27], v[140:143], v[180:183], v[24:27]
	v_mfma_f32_16x16x32_bf16 v[8:11], v[140:143], v[200:203], v[8:11]
	v_mfma_f32_16x16x32_bf16 v[16:19], v[132:135], v[200:203], v[16:19]
	s_barrier
	s_add_u32 s22, s22, 0x100080
	s_addc_u32 s23, s23, 0
	s_add_i32 s24, s24, s34
	s_mov_b32 m0, s24
	s_nop 0
	global_load_lds_dwordx4 v162, s[22:23]
	s_add_i32 m0, s24, 0x2000
	s_nop 0
	global_load_lds_dwordx4 v166, s[22:23]
	s_waitcnt vmcnt(6)
	s_barrier
	v_mfma_f32_16x16x32_bf16 v[52:55], v[204:207], v[144:147], v[52:55]
	v_mfma_f32_16x16x32_bf16 v[44:47], v[212:215], v[144:147], v[44:47]
	v_mfma_f32_16x16x32_bf16 v[28:31], v[212:215], v[152:155], v[28:31]
	v_mfma_f32_16x16x32_bf16 v[36:39], v[204:207], v[152:155], v[36:39]
	v_mfma_f32_16x16x32_bf16 v[20:23], v[204:207], v[176:179], v[20:23]
	v_mfma_f32_16x16x32_bf16 v[12:15], v[212:215], v[176:179], v[12:15]
	v_mfma_f32_16x16x32_bf16 v[0:3], v[212:215], v[196:199], v[0:3]
	v_mfma_f32_16x16x32_bf16 v[4:7], v[204:207], v[196:199], v[4:7]
	v_mfma_f32_16x16x32_bf16 v[52:55], v[208:211], v[148:151], v[52:55]
	v_mfma_f32_16x16x32_bf16 v[44:47], v[216:219], v[148:151], v[44:47]
	v_mfma_f32_16x16x32_bf16 v[28:31], v[216:219], v[156:159], v[28:31]
	v_mfma_f32_16x16x32_bf16 v[36:39], v[208:211], v[156:159], v[36:39]
	v_mfma_f32_16x16x32_bf16 v[20:23], v[208:211], v[180:183], v[20:23]
	v_mfma_f32_16x16x32_bf16 v[12:15], v[216:219], v[180:183], v[12:15]
	v_mfma_f32_16x16x32_bf16 v[0:3], v[216:219], v[200:203], v[0:3]
	v_mfma_f32_16x16x32_bf16 v[4:7], v[208:211], v[200:203], v[4:7]
	s_barrier
	s_add_i32 s46, s46, 2
	s_add_u32 s20, s20, 0x100
	s_addc_u32 s21, s21, 0
	s_add_u32 s11, s11, 0x100
	s_addc_u32 s13, s13, 0
	s_cmp_gt_u32 s46, 61
	s_cbranch_scc0 .LBB0_522
	s_lshl_b32 s11, s18, 8
	v_lshl_or_b32 v128, s16, 8, v191
	v_add_u32_e32 v130, s11, v186
	v_ashrrev_i32_e32 v129, 31, v128
	v_ashrrev_i32_e32 v131, 31, v130
	v_lshl_add_u64 v[132:133], v[128:129], 1, s[6:7]
	v_lshlrev_b64 v[134:135], 11, v[130:131]
	v_lshl_add_u64 v[134:135], v[132:133], 0, v[134:135]
	global_load_dwordx4 v[198:201], v[134:135], off
	global_load_dwordx4 v[202:205], v[134:135], off offset:256
	v_or_b32_e32 v134, 16, v130
	v_ashrrev_i32_e32 v135, 31, v134
	v_lshlrev_b64 v[134:135], 11, v[134:135]
	v_lshl_add_u64 v[134:135], v[132:133], 0, v[134:135]
	global_load_dwordx4 v[206:209], v[134:135], off
	global_load_dwordx4 v[210:213], v[134:135], off offset:256
	v_or_b32_e32 v136, 32, v130
	v_ashrrev_i32_e32 v137, 31, v136
	v_or_b32_e32 v138, 48, v130
	v_add_u32_e32 v184, 0x80, v130
	v_add_u32_e32 v182, 0x90, v130
	v_add_u32_e32 v180, 0xa0, v130
	v_add_u32_e32 v178, 0xb0, v130
	v_lshlrev_b64 v[176:177], 2, v[128:129]
	v_lshlrev_b64 v[128:129], 12, v[130:131]
	v_lshlrev_b64 v[130:131], 11, v[136:137]
	v_lshl_add_u64 v[130:131], v[132:133], 0, v[130:131]
	global_load_dwordx4 v[214:217], v[130:131], off
	v_ashrrev_i32_e32 v139, 31, v138
	v_ashrrev_i32_e32 v185, 31, v184
	v_ashrrev_i32_e32 v183, 31, v182
	v_ashrrev_i32_e32 v181, 31, v180
	v_ashrrev_i32_e32 v179, 31, v178
	v_lshlrev_b64 v[134:135], 11, v[138:139]
	v_lshlrev_b64 v[136:137], 11, v[184:185]
	v_lshlrev_b64 v[138:139], 11, v[182:183]
	v_lshl_add_u32 v196, s45, 10, v192
	v_lshlrev_b64 v[140:141], 11, v[180:181]
	v_lshlrev_b64 v[142:143], 11, v[178:179]
	v_lshl_add_u64 v[128:129], s[26:27], 0, v[128:129]
	v_lshl_add_u64 v[134:135], v[132:133], 0, v[134:135]
	v_lshl_add_u64 v[136:137], v[132:133], 0, v[136:137]
	v_lshl_add_u64 v[138:139], v[132:133], 0, v[138:139]
	ds_read2_b32 v[230:231], v196 offset1:16
	v_lshl_add_u64 v[234:235], v[132:133], 0, v[140:141]
	v_lshl_add_u64 v[236:237], v[132:133], 0, v[142:143]
	v_lshl_add_u64 v[238:239], v[128:129], 0, v[176:177]
	global_load_dwordx4 v[218:221], v[130:131], off offset:256
	global_load_dwordx4 v[222:225], v[134:135], off
	global_load_dwordx4 v[226:229], v[134:135], off offset:256
	global_load_dwordx4 v[156:159], v[136:137], off
	global_load_dwordx4 v[152:155], v[136:137], off offset:256
	global_load_dwordx4 v[148:151], v[138:139], off
	global_load_dwordx4 v[144:147], v[138:139], off offset:256
	global_load_dwordx4 v[140:143], v[234:235], off
	s_nop 0
	global_load_dwordx4 v[136:139], v[234:235], off offset:256
	global_load_dwordx4 v[132:135], v[236:237], off
	global_load_dwordx4 v[128:131], v[236:237], off offset:256
	v_add_u32_e32 v232, s11, v188
	v_ashrrev_i32_e32 v233, 31, v232
	s_and_b64 vcc, exec, s[0:1]
	s_mov_b32 s16, s10
	s_mov_b32 s18, s12
	s_mov_b64 s[20:21], s[4:5]
	s_mov_b64 s[22:23], s[14:15]
	s_mov_b32 s45, s44
	s_waitcnt vmcnt(0)
; __device__ __forceinline__ float bf_lo(unsigned w) { return __uint_as_float(w << 16); }
; __device__ __forceinline__ float bf_hi(unsigned w) { return __uint_as_float(w & 0xffff0000u); }
;     __device__ __forceinline__ void operator()(const f32x4 (&acc)[2][2][4][2], const Unit& u, int ui, int wr, int wc, int fr, int fq) const {
;     ...
; #pragma unroll
;         for (int ai = 0; ai < 2; ++ai)
; #pragma unroll
;             for (int m = 0; m < 4; ++m) { const int rl = rl0 + ai * 128 + m * 16; float* rowp = out + (size_t)(u.pm * 256 + rl) * DM + col0;
;                 const float r2 = tab[ui * 256 + rl];
; #pragma unroll
;                 for (int bj = 0; bj < 2; ++bj) { const u32x4 x = xv[ai][m][bj];
;                     const f32x4 x0 = {bf_lo(x.x), bf_hi(x.x), bf_lo(x.y), bf_hi(x.y)}, x1 = {bf_lo(x.z), bf_hi(x.z), bf_lo(x.w), bf_hi(x.w)};
;                     *(f32x4*)(rowp + bj * 128) = acc[ai][bj][m][0] * r2 + x0; *(f32x4*)(rowp + bj * 128 + 4) = acc[ai][bj][m][1] * r2 + x1; } }
	v_lshlrev_b32_e32 v234, 16, v198
	v_and_b32_e32 v235, 0xffff0000, v198
	v_lshlrev_b32_e32 v198, 16, v199
	v_and_b32_e32 v199, 0xffff0000, v199
	v_lshlrev_b32_e32 v242, 16, v204
	v_and_b32_e32 v243, 0xffff0000, v204
	v_lshlrev_b32_e32 v236, 16, v200
	v_and_b32_e32 v237, 0xffff0000, v200
	v_lshlrev_b32_e32 v200, 16, v201
	v_and_b32_e32 v201, 0xffff0000, v201
	v_lshlrev_b32_e32 v240, 16, v202
	v_and_b32_e32 v241, 0xffff0000, v202
	v_lshlrev_b32_e32 v202, 16, v203
	v_and_b32_e32 v203, 0xffff0000, v203
	v_lshlrev_b32_e32 v204, 16, v205
	v_and_b32_e32 v205, 0xffff0000, v205
	s_waitcnt lgkmcnt(0)
	v_pk_fma_f32 v[126:127], v[126:127], v[230:231], v[198:199] op_sel_hi:[1,0,1]
	v_pk_fma_f32 v[124:125], v[124:125], v[230:231], v[234:235] op_sel_hi:[1,0,1]
	v_pk_fma_f32 v[108:109], v[108:109], v[230:231], v[242:243] op_sel_hi:[1,0,1]
	v_pk_fma_f32 v[122:123], v[122:123], v[230:231], v[200:201] op_sel_hi:[1,0,1]
	v_pk_fma_f32 v[120:121], v[120:121], v[230:231], v[236:237] op_sel_hi:[1,0,1]
	v_pk_fma_f32 v[118:119], v[118:119], v[230:231], v[202:203] op_sel_hi:[1,0,1]
	v_pk_fma_f32 v[116:117], v[116:117], v[230:231], v[240:241] op_sel_hi:[1,0,1]
	v_pk_fma_f32 v[110:111], v[110:111], v[230:231], v[204:205] op_sel_hi:[1,0,1]
	global_store_dwordx4 v[238:239], v[124:127], off
	global_store_dwordx4 v[238:239], v[120:123], off offset:16
	global_store_dwordx4 v[238:239], v[116:119], off offset:512
	global_store_dwordx4 v[238:239], v[108:111], off offset:528
	v_mov_b32_e32 v122, v231
	v_lshlrev_b32_e32 v118, 16, v208
	v_lshlrev_b64 v[108:109], 12, v[232:233]
	v_lshl_add_u64 v[108:109], s[26:27], 0, v[108:109]
	v_lshl_add_u64 v[116:117], v[108:109], 0, v[176:177]
	v_lshlrev_b32_e32 v108, 16, v206
	v_and_b32_e32 v109, 0xffff0000, v206
	v_lshlrev_b32_e32 v110, 16, v207
	v_and_b32_e32 v111, 0xffff0000, v207
	v_pk_fma_f32 v[110:111], v[114:115], v[122:123], v[110:111] op_sel_hi:[1,0,1]
	v_pk_fma_f32 v[108:109], v[112:113], v[122:123], v[108:109] op_sel_hi:[1,0,1]
	global_store_dwordx4 v[116:117], v[108:111], off
	v_and_b32_e32 v119, 0xffff0000, v208
	v_lshlrev_b32_e32 v120, 16, v209
	v_lshlrev_b32_e32 v108, 16, v212
	v_and_b32_e32 v109, 0xffff0000, v212
	v_lshlrev_b32_e32 v110, 16, v213
	v_and_b32_e32 v111, 0xffff0000, v213
	v_pk_fma_f32 v[98:99], v[98:99], v[122:123], v[110:111] op_sel_hi:[1,0,1]
	v_pk_fma_f32 v[96:97], v[96:97], v[122:123], v[108:109] op_sel_hi:[1,0,1]
	v_and_b32_e32 v121, 0xffff0000, v209
	global_store_dwordx4 v[116:117], v[96:99], off offset:528
	ds_read2_b32 v[98:99], v196 offset0:32 offset1:48
	v_pk_fma_f32 v[106:107], v[106:107], v[122:123], v[120:121] op_sel_hi:[1,0,1]
	v_pk_fma_f32 v[104:105], v[104:105], v[122:123], v[118:119] op_sel_hi:[1,0,1]
	v_add_u32_e32 v96, s11, v189
	global_store_dwordx4 v[116:117], v[104:107], off offset:16
	v_ashrrev_i32_e32 v97, 31, v96
	v_lshlrev_b64 v[96:97], 12, v[96:97]
	v_lshlrev_b32_e32 v104, 16, v210
	v_and_b32_e32 v105, 0xffff0000, v210
	v_lshlrev_b32_e32 v106, 16, v211
	v_and_b32_e32 v107, 0xffff0000, v211
	v_pk_fma_f32 v[102:103], v[102:103], v[122:123], v[106:107] op_sel_hi:[1,0,1]
	v_pk_fma_f32 v[100:101], v[100:101], v[122:123], v[104:105] op_sel_hi:[1,0,1]
	global_store_dwordx4 v[116:117], v[100:103], off offset:512
	v_lshl_add_u64 v[96:97], s[26:27], 0, v[96:97]
	v_lshl_add_u64 v[96:97], v[96:97], 0, v[176:177]
	v_lshlrev_b32_e32 v100, 16, v214
	v_and_b32_e32 v101, 0xffff0000, v214
	v_lshlrev_b32_e32 v102, 16, v215
	v_and_b32_e32 v103, 0xffff0000, v215
	s_waitcnt lgkmcnt(0)
	v_pk_fma_f32 v[94:95], v[94:95], v[98:99], v[102:103] op_sel_hi:[1,0,1]
	v_pk_fma_f32 v[92:93], v[92:93], v[98:99], v[100:101] op_sel_hi:[1,0,1]
	global_store_dwordx4 v[96:97], v[92:95], off
	v_lshlrev_b32_e32 v104, 16, v216
	v_and_b32_e32 v105, 0xffff0000, v216
	v_lshlrev_b32_e32 v92, 16, v220
	v_and_b32_e32 v93, 0xffff0000, v220
	v_lshlrev_b32_e32 v94, 16, v221
	v_and_b32_e32 v95, 0xffff0000, v221
	v_lshlrev_b32_e32 v106, 16, v217
	v_and_b32_e32 v107, 0xffff0000, v217
	v_pk_fma_f32 v[82:83], v[82:83], v[98:99], v[94:95] op_sel_hi:[1,0,1]
	v_pk_fma_f32 v[80:81], v[80:81], v[98:99], v[92:93] op_sel_hi:[1,0,1]
	v_pk_fma_f32 v[90:91], v[90:91], v[98:99], v[106:107] op_sel_hi:[1,0,1]
	v_pk_fma_f32 v[88:89], v[88:89], v[98:99], v[104:105] op_sel_hi:[1,0,1]
	global_store_dwordx4 v[96:97], v[80:83], off offset:528
	global_store_dwordx4 v[96:97], v[88:91], off offset:16
	s_nop 0
	v_add_u32_e32 v80, s11, v190
	v_lshlrev_b32_e32 v88, 16, v218
	v_and_b32_e32 v89, 0xffff0000, v218
	v_lshlrev_b32_e32 v90, 16, v219
	v_and_b32_e32 v91, 0xffff0000, v219
	v_ashrrev_i32_e32 v81, 31, v80
	v_pk_fma_f32 v[86:87], v[86:87], v[98:99], v[90:91] op_sel_hi:[1,0,1]
	v_pk_fma_f32 v[84:85], v[84:85], v[98:99], v[88:89] op_sel_hi:[1,0,1]
	v_lshlrev_b64 v[80:81], 12, v[80:81]
	global_store_dwordx4 v[96:97], v[84:87], off offset:512
	v_lshl_add_u64 v[80:81], s[26:27], 0, v[80:81]
	v_lshlrev_b32_e32 v82, 16, v222
	v_and_b32_e32 v83, 0xffff0000, v222
	v_lshlrev_b32_e32 v84, 16, v223
	v_and_b32_e32 v85, 0xffff0000, v223
	v_mov_b32_e32 v90, v99
	v_lshl_add_u64 v[80:81], v[80:81], 0, v[176:177]
	v_pk_fma_f32 v[78:79], v[78:79], v[90:91], v[84:85] op_sel_hi:[1,0,1]
	v_pk_fma_f32 v[76:77], v[76:77], v[90:91], v[82:83] op_sel_hi:[1,0,1]
	global_store_dwordx4 v[80:81], v[76:79], off
	v_lshlrev_b32_e32 v86, 16, v224
	v_and_b32_e32 v87, 0xffff0000, v224
	v_lshlrev_b32_e32 v76, 16, v228
	v_and_b32_e32 v77, 0xffff0000, v228
	v_lshlrev_b32_e32 v78, 16, v229
	v_and_b32_e32 v79, 0xffff0000, v229
	v_pk_fma_f32 v[66:67], v[66:67], v[90:91], v[78:79] op_sel_hi:[1,0,1]
	v_pk_fma_f32 v[64:65], v[64:65], v[90:91], v[76:77] op_sel_hi:[1,0,1]
	v_lshlrev_b32_e32 v88, 16, v225
	v_and_b32_e32 v89, 0xffff0000, v225
	global_store_dwordx4 v[80:81], v[64:67], off offset:528
	ds_read2_b32 v[66:67], v196 offset0:128 offset1:144
	v_pk_fma_f32 v[74:75], v[74:75], v[90:91], v[88:89] op_sel_hi:[1,0,1]
	v_pk_fma_f32 v[72:73], v[72:73], v[90:91], v[86:87] op_sel_hi:[1,0,1]
	global_store_dwordx4 v[80:81], v[72:75], off offset:16
	v_lshlrev_b64 v[64:65], 12, v[184:185]
	v_lshl_add_u64 v[64:65], s[26:27], 0, v[64:65]
	v_lshlrev_b32_e32 v72, 16, v226
	v_and_b32_e32 v73, 0xffff0000, v226
	v_lshlrev_b32_e32 v74, 16, v227
	v_and_b32_e32 v75, 0xffff0000, v227
	v_pk_fma_f32 v[70:71], v[70:71], v[90:91], v[74:75] op_sel_hi:[1,0,1]
	v_pk_fma_f32 v[68:69], v[68:69], v[90:91], v[72:73] op_sel_hi:[1,0,1]
	global_store_dwordx4 v[80:81], v[68:71], off offset:512
	v_lshl_add_u64 v[64:65], v[64:65], 0, v[176:177]
	v_lshlrev_b32_e32 v72, 16, v158
	v_lshlrev_b32_e32 v68, 16, v156
	v_and_b32_e32 v69, 0xffff0000, v156
	v_lshlrev_b32_e32 v70, 16, v157
	v_and_b32_e32 v71, 0xffff0000, v157
	v_and_b32_e32 v73, 0xffff0000, v158
	v_lshlrev_b32_e32 v74, 16, v159
	v_and_b32_e32 v75, 0xffff0000, v159
	s_waitcnt lgkmcnt(0)
; __device__ __forceinline__ float bf_lo(unsigned w) { return __uint_as_float(w << 16); }
; __device__ __forceinline__ float bf_hi(unsigned w) { return __uint_as_float(w & 0xffff0000u); }
; #define PG8_WAIT_V(n) asm volatile("s_waitcnt vmcnt(" #n ")" ::: "memory")
; #define PG8_BAR __builtin_amdgcn_s_barrier()
; template <class Epi, class Ptrs>
; __device__ __forceinline__ void gemm_phase(LAS unsigned char* lds, const int K, const StaticOrder& S, const Ptrs& P, const Epi& E) {
;     ...
;         if (!has_next) break;
; #pragma unroll
;         for (int a = 0; a < 2; ++a)
; #pragma unroll
;             for (int b = 0; b < 2; ++b)
; #pragma unroll
;                 for (int m = 0; m < 4; ++m)
; #pragma unroll
;                     for (int n = 0; n < 2; ++n) acc[a][b][m][n] = (f32x4){0.f, 0.f, 0.f, 0.f};
;         cur = nxt; cA = nA; cB = nB; ++ui;
;     }
;     PG8_WAIT_V(0);
;     if (wr == 0) PG8_BAR;
;     PG8_BAR;
;     __device__ __forceinline__ void operator()(const f32x4 (&acc)[2][2][4][2], const Unit& u, int ui, int wr, int wc, int fr, int fq) const {
;     ...
;             for (int m = 0; m < 4; ++m) { const int rl = rl0 + ai * 128 + m * 16; float* rowp = out + (size_t)(u.pm * 256 + rl) * DM + col0;
;                 const float r2 = tab[ui * 256 + rl];
; #pragma unroll
;                 for (int bj = 0; bj < 2; ++bj) { const u32x4 x = xv[ai][m][bj];
;                     const f32x4 x0 = {bf_lo(x.x), bf_hi(x.x), bf_lo(x.y), bf_hi(x.y)}, x1 = {bf_lo(x.z), bf_hi(x.z), bf_lo(x.w), bf_hi(x.w)};
;                     *(f32x4*)(rowp + bj * 128) = acc[ai][bj][m][0] * r2 + x0; *(f32x4*)(rowp + bj * 128 + 4) = acc[ai][bj][m][1] * r2 + x1; } }
	v_pk_fma_f32 v[62:63], v[62:63], v[66:67], v[70:71] op_sel_hi:[1,0,1]
	v_pk_fma_f32 v[60:61], v[60:61], v[66:67], v[68:69] op_sel_hi:[1,0,1]
	global_store_dwordx4 v[64:65], v[60:63], off
	v_pk_fma_f32 v[58:59], v[58:59], v[66:67], v[74:75] op_sel_hi:[1,0,1]
	v_pk_fma_f32 v[56:57], v[56:57], v[66:67], v[72:73] op_sel_hi:[1,0,1]
	v_lshlrev_b32_e32 v60, 16, v154
	v_and_b32_e32 v61, 0xffff0000, v154
	v_lshlrev_b32_e32 v62, 16, v155
	v_and_b32_e32 v63, 0xffff0000, v155
	global_store_dwordx4 v[64:65], v[56:59], off offset:16
	v_pk_fma_f32 v[46:47], v[46:47], v[66:67], v[62:63] op_sel_hi:[1,0,1]
	v_pk_fma_f32 v[44:45], v[44:45], v[66:67], v[60:61] op_sel_hi:[1,0,1]
	v_lshlrev_b32_e32 v56, 16, v152
	v_and_b32_e32 v57, 0xffff0000, v152
	v_lshlrev_b32_e32 v58, 16, v153
	v_and_b32_e32 v59, 0xffff0000, v153
	v_pk_fma_f32 v[54:55], v[54:55], v[66:67], v[58:59] op_sel_hi:[1,0,1]
	v_pk_fma_f32 v[52:53], v[52:53], v[66:67], v[56:57] op_sel_hi:[1,0,1]
	global_store_dwordx4 v[64:65], v[44:47], off offset:528
	global_store_dwordx4 v[64:65], v[52:55], off offset:512
	v_lshlrev_b32_e32 v56, 16, v151
	v_lshlrev_b64 v[44:45], 12, v[182:183]
	v_lshl_add_u64 v[44:45], s[26:27], 0, v[44:45]
	v_lshlrev_b32_e32 v54, 16, v150
	v_and_b32_e32 v55, 0xffff0000, v150
	v_and_b32_e32 v57, 0xffff0000, v151
	v_mov_b32_e32 v58, v67
	v_lshl_add_u64 v[52:53], v[44:45], 0, v[176:177]
	v_pk_fma_f32 v[42:43], v[42:43], v[58:59], v[56:57] op_sel_hi:[1,0,1]
	v_pk_fma_f32 v[40:41], v[40:41], v[58:59], v[54:55] op_sel_hi:[1,0,1]
	v_lshlrev_b32_e32 v44, 16, v148
	v_and_b32_e32 v45, 0xffff0000, v148
	v_lshlrev_b32_e32 v46, 16, v149
	v_and_b32_e32 v47, 0xffff0000, v149
	global_store_dwordx4 v[52:53], v[40:43], off offset:16
	v_pk_fma_f32 v[46:47], v[50:51], v[58:59], v[46:47] op_sel_hi:[1,0,1]
	v_pk_fma_f32 v[44:45], v[48:49], v[58:59], v[44:45] op_sel_hi:[1,0,1]
	v_lshlrev_b32_e32 v40, 16, v144
	v_and_b32_e32 v41, 0xffff0000, v144
	v_lshlrev_b32_e32 v42, 16, v145
	v_and_b32_e32 v43, 0xffff0000, v145
	v_pk_fma_f32 v[38:39], v[38:39], v[58:59], v[42:43] op_sel_hi:[1,0,1]
	v_pk_fma_f32 v[36:37], v[36:37], v[58:59], v[40:41] op_sel_hi:[1,0,1]
	global_store_dwordx4 v[52:53], v[44:47], off
	global_store_dwordx4 v[52:53], v[36:39], off offset:512
	ds_read2_b32 v[38:39], v196 offset0:160 offset1:176
	v_lshlrev_b32_e32 v44, 16, v146
	v_and_b32_e32 v45, 0xffff0000, v146
	v_lshlrev_b32_e32 v46, 16, v147
	v_and_b32_e32 v47, 0xffff0000, v147
	v_pk_fma_f32 v[30:31], v[30:31], v[58:59], v[46:47] op_sel_hi:[1,0,1]
	v_pk_fma_f32 v[28:29], v[28:29], v[58:59], v[44:45] op_sel_hi:[1,0,1]
	global_store_dwordx4 v[52:53], v[28:31], off offset:528
	v_lshlrev_b32_e32 v40, 16, v142
	v_and_b32_e32 v41, 0xffff0000, v142
	v_lshlrev_b64 v[28:29], 12, v[180:181]
	v_lshl_add_u64 v[28:29], s[26:27], 0, v[28:29]
	v_lshl_add_u64 v[36:37], v[28:29], 0, v[176:177]
	v_lshlrev_b32_e32 v28, 16, v140
	v_and_b32_e32 v29, 0xffff0000, v140
	v_lshlrev_b32_e32 v30, 16, v141
	v_and_b32_e32 v31, 0xffff0000, v141
	s_waitcnt lgkmcnt(0)
	v_pk_fma_f32 v[30:31], v[34:35], v[38:39], v[30:31] op_sel_hi:[1,0,1]
	v_pk_fma_f32 v[28:29], v[32:33], v[38:39], v[28:29] op_sel_hi:[1,0,1]
	v_lshlrev_b32_e32 v42, 16, v143
	v_and_b32_e32 v43, 0xffff0000, v143
	global_store_dwordx4 v[36:37], v[28:31], off
	v_pk_fma_f32 v[26:27], v[26:27], v[38:39], v[42:43] op_sel_hi:[1,0,1]
	v_pk_fma_f32 v[24:25], v[24:25], v[38:39], v[40:41] op_sel_hi:[1,0,1]
	v_lshlrev_b32_e32 v28, 16, v138
	v_and_b32_e32 v29, 0xffff0000, v138
	v_lshlrev_b32_e32 v30, 16, v139
	v_and_b32_e32 v31, 0xffff0000, v139
	v_pk_fma_f32 v[14:15], v[14:15], v[38:39], v[30:31] op_sel_hi:[1,0,1]
	v_pk_fma_f32 v[12:13], v[12:13], v[38:39], v[28:29] op_sel_hi:[1,0,1]
	global_store_dwordx4 v[36:37], v[24:27], off offset:16
	global_store_dwordx4 v[36:37], v[12:15], off offset:528
	s_nop 0
	v_lshlrev_b32_e32 v24, 16, v136
	v_and_b32_e32 v25, 0xffff0000, v136
	v_lshlrev_b32_e32 v26, 16, v137
	v_and_b32_e32 v27, 0xffff0000, v137
	v_lshlrev_b64 v[12:13], 12, v[178:179]
	v_pk_fma_f32 v[22:23], v[22:23], v[38:39], v[26:27] op_sel_hi:[1,0,1]
	v_pk_fma_f32 v[20:21], v[20:21], v[38:39], v[24:25] op_sel_hi:[1,0,1]
	v_lshl_add_u64 v[12:13], s[26:27], 0, v[12:13]
	global_store_dwordx4 v[36:37], v[20:23], off offset:512
	v_lshlrev_b32_e32 v14, 16, v133
	v_and_b32_e32 v15, 0xffff0000, v133
	v_lshl_add_u64 v[20:21], v[12:13], 0, v[176:177]
	v_lshlrev_b32_e32 v12, 16, v132
	v_and_b32_e32 v13, 0xffff0000, v132
	v_lshlrev_b32_e32 v22, 16, v134
	v_and_b32_e32 v23, 0xffff0000, v134
	v_lshlrev_b32_e32 v24, 16, v135
	v_and_b32_e32 v25, 0xffff0000, v135
	v_mov_b32_e32 v26, v39
	v_pk_fma_f32 v[14:15], v[18:19], v[26:27], v[14:15] op_sel_hi:[1,0,1]
	v_pk_fma_f32 v[12:13], v[16:17], v[26:27], v[12:13] op_sel_hi:[1,0,1]
	v_pk_fma_f32 v[10:11], v[10:11], v[26:27], v[24:25] op_sel_hi:[1,0,1]
	v_pk_fma_f32 v[8:9], v[8:9], v[26:27], v[22:23] op_sel_hi:[1,0,1]
	global_store_dwordx4 v[20:21], v[12:15], off
	global_store_dwordx4 v[20:21], v[8:11], off offset:16
	s_nop 0
	v_lshlrev_b32_e32 v12, 16, v130
	v_lshlrev_b32_e32 v8, 16, v128
	v_and_b32_e32 v9, 0xffff0000, v128
	v_lshlrev_b32_e32 v10, 16, v129
	v_and_b32_e32 v11, 0xffff0000, v129
	v_and_b32_e32 v13, 0xffff0000, v130
	v_lshlrev_b32_e32 v14, 16, v131
	v_and_b32_e32 v15, 0xffff0000, v131
	v_pk_fma_f32 v[6:7], v[6:7], v[26:27], v[10:11] op_sel_hi:[1,0,1]
	v_pk_fma_f32 v[4:5], v[4:5], v[26:27], v[8:9] op_sel_hi:[1,0,1]
	v_pk_fma_f32 v[2:3], v[2:3], v[26:27], v[14:15] op_sel_hi:[1,0,1]
	v_pk_fma_f32 v[0:1], v[0:1], v[26:27], v[12:13] op_sel_hi:[1,0,1]
	global_store_dwordx4 v[20:21], v[4:7], off offset:512
	global_store_dwordx4 v[20:21], v[0:3], off offset:528
	s_cbranch_vccz .LBB0_517
	s_waitcnt vmcnt(0)
	s_setprio 0
	s_cmpk_gt_u32 s33, 0xff
	s_cbranch_scc1 .LBB0_526
	s_barrier
